# static s_setprio 1 for waves 4-7 set once at kernel entry; the per-MFMA-cluster priority flips of the GEMM loops removed
# speedup vs baseline: 1.0071x; 1.0071x over previous
; #define LAS __attribute__((address_space(3)))
; __device__ __forceinline__ unsigned xb_add(unsigned* p, unsigned v) { return __hip_atomic_fetch_add(p, v, __ATOMIC_RELAXED, __HIP_MEMORY_SCOPE_AGENT); }
; __device__ __forceinline__ unsigned xb_xcc_id() { return (unsigned)__builtin_amdgcn_s_getreg((3 << 11) | 20) & 0xFu; }
; __device__ __forceinline__ XcdBarrier xcd_barrier_post(unsigned* bar, volatile LAS unsigned* st) {
;     XcdBarrier b; b.bar = bar; b.x = xb_xcc_id(); b.st = st;
;     if (threadIdx.x == 0) (void)xb_add(&bar[XB_XCNT(b.x)], 1u);
;     return b;
; __global__ void __launch_bounds__(NTHREADS, 2) fwd_kernel(Params P) {
;     extern __shared__ __attribute__((aligned(16))) unsigned char lds_raw[];
;     LAS unsigned char* lds = (LAS unsigned char*)lds_raw;
;     cg::grid_group grid = cg::this_grid();
;     int tid = threadIdx.x, lane = tid & 63, wave = __builtin_amdgcn_readfirstlane(tid >> 6);
;     const int G = gridDim.x, NGW = G * 8; int gw = blockIdx.x * 8 + wave;
;     ...
;     ((LAS int*)(lds + 145408))[tid] = tid; if (tid < 2) ((LAS unsigned*)(lds + 131072))[tid] = 0u; __syncthreads();
;     const XcdBarrier xbar = xcd_barrier_post((unsigned*)(P.ws + WS_BAR), (volatile LAS unsigned*)(lds + 131072));
_Z10fwd_kernel6Params:
	v_readfirstlane_b32 s3, v0
	s_cmpk_lt_u32 s3, 0x100
	s_cbranch_scc1 .Lprio_keep0
	s_setprio 1
.Lprio_keep0:
	s_load_dword s3, s[0:1], 0x118
	s_add_u32 s4, s0, 0x110
	s_load_dwordx4 s[28:31], s[0:1], 0x100
	s_load_dwordx2 s[84:85], s[0:1], 0x110
	s_addc_u32 s5, s1, 0
	v_and_b32_e32 v180, 0x3ff, v0
	v_writelane_b32 v254, s4, 0
	v_lshl_add_u32 v1, v180, 2, 0
	v_add_u32_e32 v181, 0x23800, v1
	v_writelane_b32 v254, s5, 1
	s_waitcnt lgkmcnt(0)
	v_writelane_b32 v254, s3, 2
	v_readfirstlane_b32 s3, v180
	v_cmp_gt_u32_e32 vcc, 2, v180
	ds_write_b32 v181, v180
	s_and_saveexec_b64 s[4:5], vcc
	v_add_u32_e32 v1, 0x20000, v1
	v_mov_b32_e32 v2, 0
	ds_write_b32 v1, v2
	s_or_b64 exec, exec, s[4:5]
	s_waitcnt lgkmcnt(0)
	s_barrier
	s_add_u32 s10, s30, 0x38998800
	s_getreg_b32 s4, hwreg(HW_REG_XCC_ID, 0, 4)
	s_addc_u32 s11, s31, 0
	s_and_b32 s12, s4, 15
	v_cmp_eq_u32_e64 s[6:7], 0, v180
	s_mov_b64 s[4:5], exec
	s_nop 0
	v_writelane_b32 v254, s6, 3
	s_nop 1
	v_writelane_b32 v254, s7, 4
	s_and_b64 s[6:7], s[4:5], s[6:7]
	s_mov_b64 exec, s[6:7]
	s_cbranch_execz .LBB0_5
	s_mov_b64 s[6:7], exec
	v_mbcnt_lo_u32_b32 v1, s6, 0
	v_mbcnt_hi_u32_b32 v1, s7, v1
	v_cmp_eq_u32_e32 vcc, 0, v1
	s_and_b64 s[8:9], exec, vcc
	s_mov_b64 exec, s[8:9]
	s_cbranch_execz .LBB0_5
	s_lshl_b32 s8, s12, 8
	s_bcnt1_i32_b64 s6, s[6:7]
	v_mov_b32_e32 v1, s8
	v_mov_b32_e32 v2, s6
	global_atomic_add v1, v2, s[10:11] offset:1024

; #define PG8_STAGE(bufoff, gbase, voff) do { _Pragma("unroll") for (int _i = 0; _i < 2; ++_i) \
;         __builtin_amdgcn_global_load_lds((const unsigned*)((const char*)(gbase) + (voff)[_i]), (LAS unsigned*)(lds + (bufoff) + ldsw + _i * 8192), 16, 0, 0); } while (0)
; #define PG8_LDA(dst, b, h) do { _Pragma("unroll") for (int m = 0; m < 4; ++m) _Pragma("unroll") for (int k = 0; k < 2; ++k) dst[m][k] = *(const LAS bf16x8*)(lds + PG8_SA(b, h) + aoff + m * 2048 + k * 1024); } while (0)
; #define PG8_LDB(dst, b, h) do { _Pragma("unroll") for (int n = 0; n < 2; ++n) _Pragma("unroll") for (int k = 0; k < 2; ++k) dst[n][k] = *(const LAS bf16x8*)(lds + PG8_SB(b, h) + boff + n * 2048 + k * 1024); } while (0)
; #define PG8_WAIT_V(n) asm volatile("s_waitcnt vmcnt(" #n ")" ::: "memory")
; #define PG8_BAR __builtin_amdgcn_s_barrier()
; template <bool LT, class Epi>
; __device__ __forceinline__ void gemm_phase(LAS unsigned char* lds, const Gemm g, const StaticOrder& S, const Epi& E) {
;     ...
;         for (int t = 0; t < nt; t += 2) {
;             const bool last = (t == nt - 2);
;             const char* a1 = cA + (size_t)(t + 1) * kstep;
;             const char* a2 = last ? nA : cA + (size_t)(t + 2) * kstep; const char* b2 = last ? nB : cB + (size_t)(t + 2) * kstep;
;             const char* a3 = a2 + kstep; const char* b3 = b2 + kstep;
;             PG8_LDB(B0, 0, 0); PG8_LDB(B1, 0, 1); PG8_SCHED; PG8_LDA(At, 0, 0); PG8_STAGE(PG8_SA(1, 1), a1 + hstepA, voffA);
;             PG8_WAIT_V(8); PG8_WAIT_L(0); PG8_BAR; PG8_MMA(0, 0, At, B0); PG8_MMA(0, 1, At, B1); PG8_BAR; PG8_SCHED;
;             PG8_LDA(At, 0, 1); PG8_STAGE(PG8_SB(0, 0), b2, voffB); PG8_STAGE(PG8_SB(0, 1), b2 + hstepB, voffB); PG8_STAGE(PG8_SA(0, 0), a2, voffA);
;             PG8_WAIT_V(8); PG8_WAIT_L(0); PG8_BAR; PG8_MMA(1, 0, At, B0); PG8_MMA(1, 1, At, B1); PG8_BAR; PG8_SCHED;
;             PG8_LDB(B0, 1, 0); PG8_LDB(B1, 1, 1); PG8_SCHED; PG8_LDA(At, 1, 0); PG8_STAGE(PG8_SA(0, 1), a2 + hstepA, voffA);
;             PG8_WAIT_V(8); PG8_WAIT_L(0); PG8_BAR; PG8_MMA(0, 0, At, B0); PG8_MMA(0, 1, At, B1); PG8_BAR; PG8_SCHED;
;             PG8_LDA(At, 1, 1); PG8_STAGE(PG8_SB(1, 0), b3, voffB); PG8_STAGE(PG8_SB(1, 1), b3 + hstepB, voffB); PG8_STAGE(PG8_SA(1, 0), a3, voffA);
;             PG8_WAIT_V(8); PG8_WAIT_L(0); PG8_BAR; PG8_MMA(1, 0, At, B0); PG8_MMA(1, 1, At, B1); PG8_BAR; PG8_SCHED;
;         }
.LBB0_157:
	ds_read_b128 v[152:155], v149
	ds_read_b128 v[156:159], v149 offset:1024
	ds_read_b128 v[160:163], v149 offset:2048
	ds_read_b128 v[164:167], v149 offset:3072
	ds_read_b128 v[168:171], v150
	ds_read_b128 v[172:175], v150 offset:1024
	ds_read_b128 v[176:179], v150 offset:2048
	ds_read_b128 v[184:187], v150 offset:3072
	s_add_u32 s62, s58, 0xfff80080
	s_addc_u32 s63, s59, -1
	s_cmp_eq_u32 s90, 28
	s_cselect_b32 s67, s42, s63
	s_cselect_b32 s66, s43, s62
	s_cselect_b32 s63, s37, s89
	s_cselect_b32 s62, s45, s88
	v_lshl_add_u64 v[144:145], s[58:59], 0, v[136:137]
	s_add_i32 m0, s27, 0xc000
	ds_read_b128 v[188:191], v151
	ds_read_b128 v[192:195], v151 offset:1024
	ds_read_b128 v[196:199], v151 offset:2048
	ds_read_b128 v[200:203], v151 offset:3072
	ds_read_b128 v[204:207], v151 offset:4096
	ds_read_b128 v[208:211], v151 offset:5120
	ds_read_b128 v[212:215], v151 offset:6144
	ds_read_b128 v[216:219], v151 offset:7168
	global_load_lds_dwordx4 v[144:145], off
	v_lshl_add_u64 v[144:145], s[58:59], 0, v[138:139]
	s_add_i32 m0, s27, 0xe000
	s_nop 0
	global_load_lds_dwordx4 v[144:145], off
	s_waitcnt vmcnt(8)
	s_waitcnt lgkmcnt(0)
	s_barrier
	s_waitcnt lgkmcnt(0)
	v_mfma_f32_16x16x32_bf16 v[124:127], v[152:155], v[188:191], v[124:127]
	v_mfma_f32_16x16x32_bf16 v[120:123], v[160:163], v[188:191], v[120:123]
	v_mfma_f32_16x16x32_bf16 v[108:111], v[152:155], v[196:199], v[108:111]
	v_mfma_f32_16x16x32_bf16 v[104:107], v[160:163], v[196:199], v[104:107]
	v_mfma_f32_16x16x32_bf16 v[92:95], v[152:155], v[204:207], v[92:95]
	v_mfma_f32_16x16x32_bf16 v[88:91], v[160:163], v[204:207], v[88:91]
	v_mfma_f32_16x16x32_bf16 v[76:79], v[152:155], v[212:215], v[76:79]
	v_mfma_f32_16x16x32_bf16 v[72:75], v[160:163], v[212:215], v[72:75]
	v_mfma_f32_16x16x32_bf16 v[124:127], v[156:159], v[192:195], v[124:127]
	v_mfma_f32_16x16x32_bf16 v[120:123], v[164:167], v[192:195], v[120:123]
	v_mfma_f32_16x16x32_bf16 v[108:111], v[156:159], v[200:203], v[108:111]
	v_mfma_f32_16x16x32_bf16 v[104:107], v[164:167], v[200:203], v[104:107]
	v_mfma_f32_16x16x32_bf16 v[92:95], v[156:159], v[208:211], v[92:95]
	v_mfma_f32_16x16x32_bf16 v[88:91], v[164:167], v[208:211], v[88:91]
	v_mfma_f32_16x16x32_bf16 v[76:79], v[156:159], v[216:219], v[76:79]
	v_mfma_f32_16x16x32_bf16 v[72:75], v[164:167], v[216:219], v[72:75]
	v_mfma_f32_16x16x32_bf16 v[116:119], v[168:171], v[188:191], v[116:119]
	v_mfma_f32_16x16x32_bf16 v[112:115], v[176:179], v[188:191], v[112:115]
	v_mfma_f32_16x16x32_bf16 v[100:103], v[168:171], v[196:199], v[100:103]
	v_mfma_f32_16x16x32_bf16 v[96:99], v[176:179], v[196:199], v[96:99]
	v_mfma_f32_16x16x32_bf16 v[84:87], v[168:171], v[204:207], v[84:87]
	v_mfma_f32_16x16x32_bf16 v[80:83], v[176:179], v[204:207], v[80:83]
	v_mfma_f32_16x16x32_bf16 v[68:71], v[168:171], v[212:215], v[68:71]
	v_mfma_f32_16x16x32_bf16 v[64:67], v[176:179], v[212:215], v[64:67]
	v_mfma_f32_16x16x32_bf16 v[116:119], v[172:175], v[192:195], v[116:119]
	v_mfma_f32_16x16x32_bf16 v[112:115], v[184:187], v[192:195], v[112:115]
	v_mfma_f32_16x16x32_bf16 v[100:103], v[172:175], v[200:203], v[100:103]
	v_mfma_f32_16x16x32_bf16 v[96:99], v[184:187], v[200:203], v[96:99]
	v_mfma_f32_16x16x32_bf16 v[84:87], v[172:175], v[208:211], v[84:87]
	v_mfma_f32_16x16x32_bf16 v[80:83], v[184:187], v[208:211], v[80:83]
	v_mfma_f32_16x16x32_bf16 v[68:71], v[172:175], v[216:219], v[68:71]
	v_mfma_f32_16x16x32_bf16 v[64:67], v[184:187], v[216:219], v[64:67]
	s_barrier
	s_add_i32 s91, s74, s3
	v_lshl_add_u64 v[144:145], s[62:63], 0, v[132:133]
	s_mov_b32 m0, s91
	ds_read_b128 v[188:191], v151 offset:16384
	ds_read_b128 v[192:195], v151 offset:17408
	ds_read_b128 v[196:199], v151 offset:18432
	ds_read_b128 v[200:203], v151 offset:19456
	ds_read_b128 v[204:207], v151 offset:20480
	ds_read_b128 v[208:211], v151 offset:21504
	ds_read_b128 v[212:215], v151 offset:22528
	ds_read_b128 v[216:219], v151 offset:23552
	global_load_lds_dwordx4 v[144:145], off
	s_add_i32 m0, s91, 0x2000
	s_add_u32 s92, s62, 0x80000
	v_lshl_add_u64 v[220:221], s[62:63], 0, v[128:129]
	s_addc_u32 s93, s63, 0
	s_add_i32 s91, s75, s3
	global_load_lds_dwordx4 v[220:221], off
	v_lshl_add_u64 v[222:223], s[92:93], 0, v[132:133]
	s_mov_b32 m0, s91
	v_lshl_add_u64 v[224:225], s[66:67], 0, v[130:131]
	global_load_lds_dwordx4 v[222:223], off
	v_lshl_add_u64 v[222:223], s[92:93], 0, v[128:129]
	s_add_i32 m0, s91, 0x2000
	s_nop 0
	global_load_lds_dwordx4 v[222:223], off
	v_lshl_add_u64 v[222:223], s[66:67], 0, v[134:135]
	s_mov_b32 m0, s27
	s_nop 0
	global_load_lds_dwordx4 v[222:223], off
	s_mov_b32 m0, s33
	s_nop 0
	global_load_lds_dwordx4 v[224:225], off
	s_waitcnt vmcnt(8)
	s_waitcnt lgkmcnt(0)
	s_barrier
; #define PG8_STAGE(bufoff, gbase, voff) do { _Pragma("unroll") for (int _i = 0; _i < 2; ++_i) \
;         __builtin_amdgcn_global_load_lds((const unsigned*)((const char*)(gbase) + (voff)[_i]), (LAS unsigned*)(lds + (bufoff) + ldsw + _i * 8192), 16, 0, 0); } while (0)
; #define PG8_LDA(dst, b, h) do { _Pragma("unroll") for (int m = 0; m < 4; ++m) _Pragma("unroll") for (int k = 0; k < 2; ++k) dst[m][k] = *(const LAS bf16x8*)(lds + PG8_SA(b, h) + aoff + m * 2048 + k * 1024); } while (0)
; #define PG8_LDB(dst, b, h) do { _Pragma("unroll") for (int n = 0; n < 2; ++n) _Pragma("unroll") for (int k = 0; k < 2; ++k) dst[n][k] = *(const LAS bf16x8*)(lds + PG8_SB(b, h) + boff + n * 2048 + k * 1024); } while (0)
; #define PG8_WAIT_V(n) asm volatile("s_waitcnt vmcnt(" #n ")" ::: "memory")
; #define PG8_BAR __builtin_amdgcn_s_barrier()
; template <bool LT, class Epi>
; __device__ __forceinline__ void gemm_phase(LAS unsigned char* lds, const Gemm g, const StaticOrder& S, const Epi& E) {
;     ...
;         for (int t = 0; t < nt; t += 2) {
;             const bool last = (t == nt - 2);
;             const char* a1 = cA + (size_t)(t + 1) * kstep;
;             const char* a2 = last ? nA : cA + (size_t)(t + 2) * kstep; const char* b2 = last ? nB : cB + (size_t)(t + 2) * kstep;
;             const char* a3 = a2 + kstep; const char* b3 = b2 + kstep;
;             PG8_LDB(B0, 0, 0); PG8_LDB(B1, 0, 1); PG8_SCHED; PG8_LDA(At, 0, 0); PG8_STAGE(PG8_SA(1, 1), a1 + hstepA, voffA);
;             PG8_WAIT_V(8); PG8_WAIT_L(0); PG8_BAR; PG8_MMA(0, 0, At, B0); PG8_MMA(0, 1, At, B1); PG8_BAR; PG8_SCHED;
;             PG8_LDA(At, 0, 1); PG8_STAGE(PG8_SB(0, 0), b2, voffB); PG8_STAGE(PG8_SB(0, 1), b2 + hstepB, voffB); PG8_STAGE(PG8_SA(0, 0), a2, voffA);
;             PG8_WAIT_V(8); PG8_WAIT_L(0); PG8_BAR; PG8_MMA(1, 0, At, B0); PG8_MMA(1, 1, At, B1); PG8_BAR; PG8_SCHED;
;             PG8_LDB(B0, 1, 0); PG8_LDB(B1, 1, 1); PG8_SCHED; PG8_LDA(At, 1, 0); PG8_STAGE(PG8_SA(0, 1), a2 + hstepA, voffA);
;             PG8_WAIT_V(8); PG8_WAIT_L(0); PG8_BAR; PG8_MMA(0, 0, At, B0); PG8_MMA(0, 1, At, B1); PG8_BAR; PG8_SCHED;
;             PG8_LDA(At, 1, 1); PG8_STAGE(PG8_SB(1, 0), b3, voffB); PG8_STAGE(PG8_SB(1, 1), b3 + hstepB, voffB); PG8_STAGE(PG8_SA(1, 0), a3, voffA);
;             PG8_WAIT_V(8); PG8_WAIT_L(0); PG8_BAR; PG8_MMA(1, 0, At, B0); PG8_MMA(1, 1, At, B1); PG8_BAR; PG8_SCHED;
;         }
	s_waitcnt lgkmcnt(0)
	v_mfma_f32_16x16x32_bf16 v[60:63], v[152:155], v[188:191], v[60:63]
	v_mfma_f32_16x16x32_bf16 v[56:59], v[160:163], v[188:191], v[56:59]
	v_mfma_f32_16x16x32_bf16 v[44:47], v[152:155], v[196:199], v[44:47]
	v_mfma_f32_16x16x32_bf16 v[40:43], v[160:163], v[196:199], v[40:43]
	v_mfma_f32_16x16x32_bf16 v[28:31], v[152:155], v[204:207], v[28:31]
	v_mfma_f32_16x16x32_bf16 v[24:27], v[160:163], v[204:207], v[24:27]
	v_mfma_f32_16x16x32_bf16 v[12:15], v[152:155], v[212:215], v[12:15]
	v_mfma_f32_16x16x32_bf16 v[8:11], v[160:163], v[212:215], v[8:11]
	v_mfma_f32_16x16x32_bf16 v[60:63], v[156:159], v[192:195], v[60:63]
	v_mfma_f32_16x16x32_bf16 v[56:59], v[164:167], v[192:195], v[56:59]
	v_mfma_f32_16x16x32_bf16 v[44:47], v[156:159], v[200:203], v[44:47]
	v_mfma_f32_16x16x32_bf16 v[40:43], v[164:167], v[200:203], v[40:43]
	v_mfma_f32_16x16x32_bf16 v[28:31], v[156:159], v[208:211], v[28:31]
	v_mfma_f32_16x16x32_bf16 v[24:27], v[164:167], v[208:211], v[24:27]
	v_mfma_f32_16x16x32_bf16 v[12:15], v[156:159], v[216:219], v[12:15]
	v_mfma_f32_16x16x32_bf16 v[8:11], v[164:167], v[216:219], v[8:11]
	v_mfma_f32_16x16x32_bf16 v[52:55], v[168:171], v[188:191], v[52:55]
	v_mfma_f32_16x16x32_bf16 v[48:51], v[176:179], v[188:191], v[48:51]
	v_mfma_f32_16x16x32_bf16 v[36:39], v[168:171], v[196:199], v[36:39]
	v_mfma_f32_16x16x32_bf16 v[32:35], v[176:179], v[196:199], v[32:35]
	v_mfma_f32_16x16x32_bf16 v[20:23], v[168:171], v[204:207], v[20:23]
	v_mfma_f32_16x16x32_bf16 v[16:19], v[176:179], v[204:207], v[16:19]
	v_mfma_f32_16x16x32_bf16 v[4:7], v[168:171], v[212:215], v[4:7]
	v_mfma_f32_16x16x32_bf16 v[0:3], v[176:179], v[212:215], v[0:3]
	v_mfma_f32_16x16x32_bf16 v[52:55], v[172:175], v[192:195], v[52:55]
	v_mfma_f32_16x16x32_bf16 v[48:51], v[184:187], v[192:195], v[48:51]
	v_mfma_f32_16x16x32_bf16 v[36:39], v[172:175], v[200:203], v[36:39]
	v_mfma_f32_16x16x32_bf16 v[32:35], v[184:187], v[200:203], v[32:35]
	v_mfma_f32_16x16x32_bf16 v[20:23], v[172:175], v[208:211], v[20:23]
	v_mfma_f32_16x16x32_bf16 v[16:19], v[184:187], v[208:211], v[16:19]
	v_mfma_f32_16x16x32_bf16 v[4:7], v[172:175], v[216:219], v[4:7]
	v_mfma_f32_16x16x32_bf16 v[0:3], v[184:187], v[216:219], v[0:3]
	s_barrier
	s_add_i32 s91, 0, 0x18000
	s_add_i32 s92, 0, 0x1c000
	v_add_u32_e32 v164, s91, v147
	v_add_u32_e32 v183, s92, v147
	ds_read_b128 v[152:155], v164
	ds_read_b128 v[156:159], v164 offset:1024
	ds_read_b128 v[160:163], v164 offset:2048
	ds_read_b128 v[164:167], v164 offset:3072
	ds_read_b128 v[168:171], v183
	ds_read_b128 v[172:175], v183 offset:1024
	ds_read_b128 v[176:179], v183 offset:2048
	ds_read_b128 v[184:187], v183 offset:3072
	s_add_u32 s66, s66, 0x80000
	s_addc_u32 s67, s67, 0
	s_mov_b32 m0, s55
	v_lshl_add_u64 v[226:227], s[66:67], 0, v[134:135]
	ds_read_b128 v[188:191], v151 offset:32768
	ds_read_b128 v[192:195], v151 offset:33792
	ds_read_b128 v[196:199], v151 offset:34816
	ds_read_b128 v[200:203], v151 offset:35840
	ds_read_b128 v[204:207], v151 offset:36864
	ds_read_b128 v[208:211], v151 offset:37888
	ds_read_b128 v[212:215], v151 offset:38912
	ds_read_b128 v[216:219], v151 offset:39936
	global_load_lds_dwordx4 v[226:227], off
	v_lshl_add_u64 v[226:227], s[66:67], 0, v[130:131]
	s_mov_b32 m0, s68
	s_nop 0
	global_load_lds_dwordx4 v[226:227], off
	s_waitcnt vmcnt(8)
	s_waitcnt lgkmcnt(0)
	s_barrier
	s_waitcnt lgkmcnt(0)
	v_mfma_f32_16x16x32_bf16 v[124:127], v[152:155], v[188:191], v[124:127]
	v_mfma_f32_16x16x32_bf16 v[120:123], v[160:163], v[188:191], v[120:123]
	v_mfma_f32_16x16x32_bf16 v[108:111], v[152:155], v[196:199], v[108:111]
	v_mfma_f32_16x16x32_bf16 v[104:107], v[160:163], v[196:199], v[104:107]
	v_mfma_f32_16x16x32_bf16 v[92:95], v[152:155], v[204:207], v[92:95]
	v_mfma_f32_16x16x32_bf16 v[88:91], v[160:163], v[204:207], v[88:91]
	v_mfma_f32_16x16x32_bf16 v[76:79], v[152:155], v[212:215], v[76:79]
	v_mfma_f32_16x16x32_bf16 v[72:75], v[160:163], v[212:215], v[72:75]
	v_mfma_f32_16x16x32_bf16 v[124:127], v[156:159], v[192:195], v[124:127]
	v_mfma_f32_16x16x32_bf16 v[120:123], v[164:167], v[192:195], v[120:123]
	v_mfma_f32_16x16x32_bf16 v[108:111], v[156:159], v[200:203], v[108:111]
	v_mfma_f32_16x16x32_bf16 v[104:107], v[164:167], v[200:203], v[104:107]
	v_mfma_f32_16x16x32_bf16 v[92:95], v[156:159], v[208:211], v[92:95]
	v_mfma_f32_16x16x32_bf16 v[88:91], v[164:167], v[208:211], v[88:91]
	v_mfma_f32_16x16x32_bf16 v[76:79], v[156:159], v[216:219], v[76:79]
	v_mfma_f32_16x16x32_bf16 v[72:75], v[164:167], v[216:219], v[72:75]
	v_mfma_f32_16x16x32_bf16 v[116:119], v[168:171], v[188:191], v[116:119]
	v_mfma_f32_16x16x32_bf16 v[112:115], v[176:179], v[188:191], v[112:115]
	v_mfma_f32_16x16x32_bf16 v[100:103], v[168:171], v[196:199], v[100:103]
	v_mfma_f32_16x16x32_bf16 v[96:99], v[176:179], v[196:199], v[96:99]
	v_mfma_f32_16x16x32_bf16 v[84:87], v[168:171], v[204:207], v[84:87]
	v_mfma_f32_16x16x32_bf16 v[80:83], v[176:179], v[204:207], v[80:83]
	v_mfma_f32_16x16x32_bf16 v[68:71], v[168:171], v[212:215], v[68:71]
	v_mfma_f32_16x16x32_bf16 v[64:67], v[176:179], v[212:215], v[64:67]
	v_mfma_f32_16x16x32_bf16 v[116:119], v[172:175], v[192:195], v[116:119]
	v_mfma_f32_16x16x32_bf16 v[112:115], v[184:187], v[192:195], v[112:115]
	v_mfma_f32_16x16x32_bf16 v[100:103], v[172:175], v[200:203], v[100:103]
	v_mfma_f32_16x16x32_bf16 v[96:99], v[184:187], v[200:203], v[96:99]
	v_mfma_f32_16x16x32_bf16 v[84:87], v[172:175], v[208:211], v[84:87]
	v_mfma_f32_16x16x32_bf16 v[80:83], v[184:187], v[208:211], v[80:83]
	v_mfma_f32_16x16x32_bf16 v[68:71], v[172:175], v[216:219], v[68:71]
	v_mfma_f32_16x16x32_bf16 v[64:67], v[184:187], v[216:219], v[64:67]
	s_barrier
; #define PG8_STAGE(bufoff, gbase, voff) do { _Pragma("unroll") for (int _i = 0; _i < 2; ++_i) \
;         __builtin_amdgcn_global_load_lds((const unsigned*)((const char*)(gbase) + (voff)[_i]), (LAS unsigned*)(lds + (bufoff) + ldsw + _i * 8192), 16, 0, 0); } while (0)
; #define PG8_LDA(dst, b, h) do { _Pragma("unroll") for (int m = 0; m < 4; ++m) _Pragma("unroll") for (int k = 0; k < 2; ++k) dst[m][k] = *(const LAS bf16x8*)(lds + PG8_SA(b, h) + aoff + m * 2048 + k * 1024); } while (0)
; #define PG8_LDB(dst, b, h) do { _Pragma("unroll") for (int n = 0; n < 2; ++n) _Pragma("unroll") for (int k = 0; k < 2; ++k) dst[n][k] = *(const LAS bf16x8*)(lds + PG8_SB(b, h) + boff + n * 2048 + k * 1024); } while (0)
; #define PG8_WAIT_V(n) asm volatile("s_waitcnt vmcnt(" #n ")" ::: "memory")
; #define PG8_BAR __builtin_amdgcn_s_barrier()
; template <bool LT, class Epi>
; __device__ __forceinline__ void gemm_phase(LAS unsigned char* lds, const Gemm g, const StaticOrder& S, const Epi& E) {
;     ...
;         for (int t = 0; t < nt; t += 2) {
;             const bool last = (t == nt - 2);
;             const char* a1 = cA + (size_t)(t + 1) * kstep;
;             const char* a2 = last ? nA : cA + (size_t)(t + 2) * kstep; const char* b2 = last ? nB : cB + (size_t)(t + 2) * kstep;
;             const char* a3 = a2 + kstep; const char* b3 = b2 + kstep;
;             PG8_LDB(B0, 0, 0); PG8_LDB(B1, 0, 1); PG8_SCHED; PG8_LDA(At, 0, 0); PG8_STAGE(PG8_SA(1, 1), a1 + hstepA, voffA);
;             PG8_WAIT_V(8); PG8_WAIT_L(0); PG8_BAR; PG8_MMA(0, 0, At, B0); PG8_MMA(0, 1, At, B1); PG8_BAR; PG8_SCHED;
;             PG8_LDA(At, 0, 1); PG8_STAGE(PG8_SB(0, 0), b2, voffB); PG8_STAGE(PG8_SB(0, 1), b2 + hstepB, voffB); PG8_STAGE(PG8_SA(0, 0), a2, voffA);
;             PG8_WAIT_V(8); PG8_WAIT_L(0); PG8_BAR; PG8_MMA(1, 0, At, B0); PG8_MMA(1, 1, At, B1); PG8_BAR; PG8_SCHED;
;             PG8_LDB(B0, 1, 0); PG8_LDB(B1, 1, 1); PG8_SCHED; PG8_LDA(At, 1, 0); PG8_STAGE(PG8_SA(0, 1), a2 + hstepA, voffA);
;             PG8_WAIT_V(8); PG8_WAIT_L(0); PG8_BAR; PG8_MMA(0, 0, At, B0); PG8_MMA(0, 1, At, B1); PG8_BAR; PG8_SCHED;
;             PG8_LDA(At, 1, 1); PG8_STAGE(PG8_SB(1, 0), b3, voffB); PG8_STAGE(PG8_SB(1, 1), b3 + hstepB, voffB); PG8_STAGE(PG8_SA(1, 0), a3, voffA);
;             PG8_WAIT_V(8); PG8_WAIT_L(0); PG8_BAR; PG8_MMA(1, 0, At, B0); PG8_MMA(1, 1, At, B1); PG8_BAR; PG8_SCHED;
;         }
	s_add_i32 s66, s91, s3
	v_lshl_add_u64 v[144:145], v[144:145], 0, s[6:7]
	s_mov_b32 m0, s66
	ds_read_b128 v[188:191], v151 offset:49152
	ds_read_b128 v[192:195], v151 offset:50176
	ds_read_b128 v[196:199], v151 offset:51200
	ds_read_b128 v[200:203], v151 offset:52224
	ds_read_b128 v[204:207], v151 offset:53248
	ds_read_b128 v[208:211], v151 offset:54272
	ds_read_b128 v[212:215], v151 offset:55296
	ds_read_b128 v[216:219], v151 offset:56320
	global_load_lds_dwordx4 v[144:145], off
	s_add_i32 m0, s66, 0x2000
	s_add_u32 s62, s62, 0x80080
	v_lshl_add_u64 v[144:145], v[220:221], 0, s[6:7]
	s_addc_u32 s63, s63, 0
	s_add_i32 s66, s92, s3
	global_load_lds_dwordx4 v[144:145], off
	v_lshl_add_u64 v[144:145], s[62:63], 0, v[132:133]
	s_mov_b32 m0, s66
	s_nop 0
	global_load_lds_dwordx4 v[144:145], off
	v_lshl_add_u64 v[144:145], s[62:63], 0, v[128:129]
	s_add_i32 m0, s66, 0x2000
	s_nop 0
	global_load_lds_dwordx4 v[144:145], off
	v_lshl_add_u64 v[144:145], v[222:223], 0, s[6:7]
	s_mov_b32 m0, s70
	s_nop 0
	global_load_lds_dwordx4 v[144:145], off
	v_lshl_add_u64 v[144:145], v[224:225], 0, s[6:7]
	s_mov_b32 m0, s71
	s_nop 0
	global_load_lds_dwordx4 v[144:145], off
	s_waitcnt vmcnt(8)
	s_waitcnt lgkmcnt(0)
	s_barrier
	s_waitcnt lgkmcnt(0)
	v_mfma_f32_16x16x32_bf16 v[60:63], v[152:155], v[188:191], v[60:63]
	v_mfma_f32_16x16x32_bf16 v[56:59], v[160:163], v[188:191], v[56:59]
	v_mfma_f32_16x16x32_bf16 v[44:47], v[152:155], v[196:199], v[44:47]
	v_mfma_f32_16x16x32_bf16 v[40:43], v[160:163], v[196:199], v[40:43]
	v_mfma_f32_16x16x32_bf16 v[28:31], v[152:155], v[204:207], v[28:31]
	v_mfma_f32_16x16x32_bf16 v[24:27], v[160:163], v[204:207], v[24:27]
	v_mfma_f32_16x16x32_bf16 v[12:15], v[152:155], v[212:215], v[12:15]
	v_mfma_f32_16x16x32_bf16 v[8:11], v[160:163], v[212:215], v[8:11]
	v_mfma_f32_16x16x32_bf16 v[60:63], v[156:159], v[192:195], v[60:63]
	v_mfma_f32_16x16x32_bf16 v[56:59], v[164:167], v[192:195], v[56:59]
	v_mfma_f32_16x16x32_bf16 v[44:47], v[156:159], v[200:203], v[44:47]
	v_mfma_f32_16x16x32_bf16 v[40:43], v[164:167], v[200:203], v[40:43]
	v_mfma_f32_16x16x32_bf16 v[28:31], v[156:159], v[208:211], v[28:31]
	v_mfma_f32_16x16x32_bf16 v[24:27], v[164:167], v[208:211], v[24:27]
	v_mfma_f32_16x16x32_bf16 v[12:15], v[156:159], v[216:219], v[12:15]
	v_mfma_f32_16x16x32_bf16 v[8:11], v[164:167], v[216:219], v[8:11]
	v_mfma_f32_16x16x32_bf16 v[52:55], v[168:171], v[188:191], v[52:55]
	v_mfma_f32_16x16x32_bf16 v[48:51], v[176:179], v[188:191], v[48:51]
	v_mfma_f32_16x16x32_bf16 v[36:39], v[168:171], v[196:199], v[36:39]
	v_mfma_f32_16x16x32_bf16 v[32:35], v[176:179], v[196:199], v[32:35]
	v_mfma_f32_16x16x32_bf16 v[20:23], v[168:171], v[204:207], v[20:23]
	v_mfma_f32_16x16x32_bf16 v[16:19], v[176:179], v[204:207], v[16:19]
	v_mfma_f32_16x16x32_bf16 v[4:7], v[168:171], v[212:215], v[4:7]
	v_mfma_f32_16x16x32_bf16 v[0:3], v[176:179], v[212:215], v[0:3]
	v_mfma_f32_16x16x32_bf16 v[52:55], v[172:175], v[192:195], v[52:55]
	v_mfma_f32_16x16x32_bf16 v[48:51], v[184:187], v[192:195], v[48:51]
	v_mfma_f32_16x16x32_bf16 v[36:39], v[172:175], v[200:203], v[36:39]
	v_mfma_f32_16x16x32_bf16 v[32:35], v[184:187], v[200:203], v[32:35]
	v_mfma_f32_16x16x32_bf16 v[20:23], v[172:175], v[208:211], v[20:23]
	v_mfma_f32_16x16x32_bf16 v[16:19], v[184:187], v[208:211], v[16:19]
	v_mfma_f32_16x16x32_bf16 v[4:7], v[172:175], v[216:219], v[4:7]
	v_mfma_f32_16x16x32_bf16 v[0:3], v[184:187], v[216:219], v[0:3]
	s_barrier
	s_add_i32 s90, s90, 2
	s_add_u32 s58, s58, 0x100
	s_addc_u32 s59, s59, 0
	s_add_u32 s88, s88, 0x100
	s_addc_u32 s89, s89, 0
	s_cmp_gt_u32 s90, 29
	s_cbranch_scc0 .LBB0_157
	s_and_b64 vcc, exec, s[14:15]
	s_cbranch_vccz .LBB0_160
	s_barrier

; #define PG8_STAGE(bufoff, gbase, voff) do { _Pragma("unroll") for (int _i = 0; _i < 2; ++_i) \
;         __builtin_amdgcn_global_load_lds((const unsigned*)((const char*)(gbase) + (voff)[_i]), (LAS unsigned*)(lds + (bufoff) + ldsw + _i * 8192), 16, 0, 0); } while (0)
; #define PG8_LDA(dst, b, h) do { _Pragma("unroll") for (int m = 0; m < 4; ++m) _Pragma("unroll") for (int k = 0; k < 2; ++k) dst[m][k] = *(const LAS bf16x8*)(lds + PG8_SA(b, h) + aoff + m * 2048 + k * 1024); } while (0)
; #define PG8_LDB(dst, b, h) do { _Pragma("unroll") for (int n = 0; n < 2; ++n) _Pragma("unroll") for (int k = 0; k < 2; ++k) dst[n][k] = *(const LAS bf16x8*)(lds + PG8_SB(b, h) + boff + n * 2048 + k * 1024); } while (0)
; #define PG8_WAIT_V(n) asm volatile("s_waitcnt vmcnt(" #n ")" ::: "memory")
; #define PG8_BAR __builtin_amdgcn_s_barrier()
; template <bool LT, class Epi>
; __device__ __forceinline__ void gemm_phase(LAS unsigned char* lds, const Gemm g, const StaticOrder& S, const Epi& E) {
;     ...
;         for (int t = 0; t < nt; t += 2) {
;             const bool last = (t == nt - 2);
;             const char* a1 = cA + (size_t)(t + 1) * kstep;
;             const char* a2 = last ? nA : cA + (size_t)(t + 2) * kstep; const char* b2 = last ? nB : cB + (size_t)(t + 2) * kstep;
;             const char* a3 = a2 + kstep; const char* b3 = b2 + kstep;
;             PG8_LDB(B0, 0, 0); PG8_LDB(B1, 0, 1); PG8_SCHED; PG8_LDA(At, 0, 0); PG8_STAGE(PG8_SA(1, 1), a1 + hstepA, voffA);
;             PG8_WAIT_V(8); PG8_WAIT_L(0); PG8_BAR; PG8_MMA(0, 0, At, B0); PG8_MMA(0, 1, At, B1); PG8_BAR; PG8_SCHED;
;             PG8_LDA(At, 0, 1); PG8_STAGE(PG8_SB(0, 0), b2, voffB); PG8_STAGE(PG8_SB(0, 1), b2 + hstepB, voffB); PG8_STAGE(PG8_SA(0, 0), a2, voffA);
;             PG8_WAIT_V(8); PG8_WAIT_L(0); PG8_BAR; PG8_MMA(1, 0, At, B0); PG8_MMA(1, 1, At, B1); PG8_BAR; PG8_SCHED;
;             PG8_LDB(B0, 1, 0); PG8_LDB(B1, 1, 1); PG8_SCHED; PG8_LDA(At, 1, 0); PG8_STAGE(PG8_SA(0, 1), a2 + hstepA, voffA);
;             PG8_WAIT_V(8); PG8_WAIT_L(0); PG8_BAR; PG8_MMA(0, 0, At, B0); PG8_MMA(0, 1, At, B1); PG8_BAR; PG8_SCHED;
;             PG8_LDA(At, 1, 1); PG8_STAGE(PG8_SB(1, 0), b3, voffB); PG8_STAGE(PG8_SB(1, 1), b3 + hstepB, voffB); PG8_STAGE(PG8_SA(1, 0), a3, voffA);
;             PG8_WAIT_V(8); PG8_WAIT_L(0); PG8_BAR; PG8_MMA(1, 0, At, B0); PG8_MMA(1, 1, At, B1); PG8_BAR; PG8_SCHED;
;         }
.LBB0_237:
	ds_read_b128 v[152:155], v149
	ds_read_b128 v[156:159], v149 offset:1024
	ds_read_b128 v[160:163], v149 offset:2048
	ds_read_b128 v[164:167], v149 offset:3072
	ds_read_b128 v[168:171], v150
	ds_read_b128 v[172:175], v150 offset:1024
	ds_read_b128 v[176:179], v150 offset:2048
	ds_read_b128 v[184:187], v150 offset:3072
	s_add_u32 s58, s54, 0x100
	s_addc_u32 s59, s55, 0
	s_cmpk_eq_i32 s88, 0x54
	s_cselect_b32 s67, s5, s59
	s_cselect_b32 s66, s4, s58
	s_cselect_b32 s63, s53, s77
	s_cselect_b32 s62, s52, s76
	v_lshl_add_u64 v[144:145], s[54:55], 0, v[136:137]
	s_add_i32 m0, s11, 0xc000
	ds_read_b128 v[188:191], v151
	ds_read_b128 v[192:195], v151 offset:1024
	ds_read_b128 v[196:199], v151 offset:2048
	ds_read_b128 v[200:203], v151 offset:3072
	ds_read_b128 v[204:207], v151 offset:4096
	ds_read_b128 v[208:211], v151 offset:5120
	ds_read_b128 v[212:215], v151 offset:6144
	ds_read_b128 v[216:219], v151 offset:7168
	global_load_lds_dwordx4 v[144:145], off
	v_lshl_add_u64 v[144:145], s[54:55], 0, v[138:139]
	s_add_i32 m0, s11, 0xe000
	s_nop 0
	global_load_lds_dwordx4 v[144:145], off
	s_waitcnt vmcnt(8)
	s_waitcnt lgkmcnt(0)
	s_barrier
	s_waitcnt lgkmcnt(0)
	v_mfma_f32_16x16x32_bf16 v[124:127], v[152:155], v[188:191], v[124:127]
	v_mfma_f32_16x16x32_bf16 v[120:123], v[160:163], v[188:191], v[120:123]
	v_mfma_f32_16x16x32_bf16 v[116:119], v[152:155], v[196:199], v[116:119]
	v_mfma_f32_16x16x32_bf16 v[108:111], v[160:163], v[196:199], v[108:111]
	v_mfma_f32_16x16x32_bf16 v[100:103], v[152:155], v[204:207], v[100:103]
	v_mfma_f32_16x16x32_bf16 v[92:95], v[160:163], v[204:207], v[92:95]
	v_mfma_f32_16x16x32_bf16 v[84:87], v[152:155], v[212:215], v[84:87]
	v_mfma_f32_16x16x32_bf16 v[76:79], v[160:163], v[212:215], v[76:79]
	v_mfma_f32_16x16x32_bf16 v[124:127], v[156:159], v[192:195], v[124:127]
	v_mfma_f32_16x16x32_bf16 v[120:123], v[164:167], v[192:195], v[120:123]
	v_mfma_f32_16x16x32_bf16 v[116:119], v[156:159], v[200:203], v[116:119]
	v_mfma_f32_16x16x32_bf16 v[108:111], v[164:167], v[200:203], v[108:111]
	v_mfma_f32_16x16x32_bf16 v[100:103], v[156:159], v[208:211], v[100:103]
	v_mfma_f32_16x16x32_bf16 v[92:95], v[164:167], v[208:211], v[92:95]
	v_mfma_f32_16x16x32_bf16 v[84:87], v[156:159], v[216:219], v[84:87]
	v_mfma_f32_16x16x32_bf16 v[76:79], v[164:167], v[216:219], v[76:79]
	v_mfma_f32_16x16x32_bf16 v[112:115], v[168:171], v[188:191], v[112:115]
	v_mfma_f32_16x16x32_bf16 v[104:107], v[176:179], v[188:191], v[104:107]
	v_mfma_f32_16x16x32_bf16 v[96:99], v[168:171], v[196:199], v[96:99]
	v_mfma_f32_16x16x32_bf16 v[88:91], v[176:179], v[196:199], v[88:91]
	v_mfma_f32_16x16x32_bf16 v[80:83], v[168:171], v[204:207], v[80:83]
	v_mfma_f32_16x16x32_bf16 v[72:75], v[176:179], v[204:207], v[72:75]
	v_mfma_f32_16x16x32_bf16 v[68:71], v[168:171], v[212:215], v[68:71]
	v_mfma_f32_16x16x32_bf16 v[64:67], v[176:179], v[212:215], v[64:67]
	v_mfma_f32_16x16x32_bf16 v[112:115], v[172:175], v[192:195], v[112:115]
	v_mfma_f32_16x16x32_bf16 v[104:107], v[184:187], v[192:195], v[104:107]
	v_mfma_f32_16x16x32_bf16 v[96:99], v[172:175], v[200:203], v[96:99]
	v_mfma_f32_16x16x32_bf16 v[88:91], v[184:187], v[200:203], v[88:91]
	v_mfma_f32_16x16x32_bf16 v[80:83], v[172:175], v[208:211], v[80:83]
	v_mfma_f32_16x16x32_bf16 v[72:75], v[184:187], v[208:211], v[72:75]
	v_mfma_f32_16x16x32_bf16 v[68:71], v[172:175], v[216:219], v[68:71]
	v_mfma_f32_16x16x32_bf16 v[64:67], v[184:187], v[216:219], v[64:67]
	s_barrier
	s_add_i32 s54, s70, s10
	v_lshl_add_u64 v[144:145], s[62:63], 0, v[130:131]
	s_mov_b32 m0, s54
	ds_read_b128 v[188:191], v151 offset:16384
	ds_read_b128 v[192:195], v151 offset:17408
	ds_read_b128 v[196:199], v151 offset:18432
	ds_read_b128 v[200:203], v151 offset:19456
	ds_read_b128 v[204:207], v151 offset:20480
	ds_read_b128 v[208:211], v151 offset:21504
	ds_read_b128 v[212:215], v151 offset:22528
	ds_read_b128 v[216:219], v151 offset:23552
	global_load_lds_dwordx4 v[144:145], off
	s_add_i32 m0, s54, 0x2000
	s_add_u32 s54, s62, 0x160000
	v_lshl_add_u64 v[220:221], s[62:63], 0, v[134:135]
	s_addc_u32 s55, s63, 0
	s_add_i32 s89, s71, s10
	global_load_lds_dwordx4 v[220:221], off
	v_lshl_add_u64 v[222:223], s[54:55], 0, v[130:131]
	s_mov_b32 m0, s89
	v_lshl_add_u64 v[224:225], s[66:67], 0, v[132:133]
	global_load_lds_dwordx4 v[222:223], off
	v_lshl_add_u64 v[222:223], s[54:55], 0, v[134:135]
	s_add_i32 m0, s89, 0x2000
	s_nop 0
	global_load_lds_dwordx4 v[222:223], off
	v_lshl_add_u64 v[222:223], s[66:67], 0, v[128:129]
	s_mov_b32 m0, s11
	s_nop 0
	global_load_lds_dwordx4 v[222:223], off
	s_mov_b32 m0, s14
	s_nop 0
	global_load_lds_dwordx4 v[224:225], off
	s_waitcnt vmcnt(8)
	s_waitcnt lgkmcnt(0)
	s_barrier
; #define PG8_STAGE(bufoff, gbase, voff) do { _Pragma("unroll") for (int _i = 0; _i < 2; ++_i) \
;         __builtin_amdgcn_global_load_lds((const unsigned*)((const char*)(gbase) + (voff)[_i]), (LAS unsigned*)(lds + (bufoff) + ldsw + _i * 8192), 16, 0, 0); } while (0)
; #define PG8_LDA(dst, b, h) do { _Pragma("unroll") for (int m = 0; m < 4; ++m) _Pragma("unroll") for (int k = 0; k < 2; ++k) dst[m][k] = *(const LAS bf16x8*)(lds + PG8_SA(b, h) + aoff + m * 2048 + k * 1024); } while (0)
; #define PG8_LDB(dst, b, h) do { _Pragma("unroll") for (int n = 0; n < 2; ++n) _Pragma("unroll") for (int k = 0; k < 2; ++k) dst[n][k] = *(const LAS bf16x8*)(lds + PG8_SB(b, h) + boff + n * 2048 + k * 1024); } while (0)
; #define PG8_WAIT_V(n) asm volatile("s_waitcnt vmcnt(" #n ")" ::: "memory")
; #define PG8_BAR __builtin_amdgcn_s_barrier()
; template <bool LT, class Epi>
; __device__ __forceinline__ void gemm_phase(LAS unsigned char* lds, const Gemm g, const StaticOrder& S, const Epi& E) {
;     ...
;         for (int t = 0; t < nt; t += 2) {
;             const bool last = (t == nt - 2);
;             const char* a1 = cA + (size_t)(t + 1) * kstep;
;             const char* a2 = last ? nA : cA + (size_t)(t + 2) * kstep; const char* b2 = last ? nB : cB + (size_t)(t + 2) * kstep;
;             const char* a3 = a2 + kstep; const char* b3 = b2 + kstep;
;             PG8_LDB(B0, 0, 0); PG8_LDB(B1, 0, 1); PG8_SCHED; PG8_LDA(At, 0, 0); PG8_STAGE(PG8_SA(1, 1), a1 + hstepA, voffA);
;             PG8_WAIT_V(8); PG8_WAIT_L(0); PG8_BAR; PG8_MMA(0, 0, At, B0); PG8_MMA(0, 1, At, B1); PG8_BAR; PG8_SCHED;
;             PG8_LDA(At, 0, 1); PG8_STAGE(PG8_SB(0, 0), b2, voffB); PG8_STAGE(PG8_SB(0, 1), b2 + hstepB, voffB); PG8_STAGE(PG8_SA(0, 0), a2, voffA);
;             PG8_WAIT_V(8); PG8_WAIT_L(0); PG8_BAR; PG8_MMA(1, 0, At, B0); PG8_MMA(1, 1, At, B1); PG8_BAR; PG8_SCHED;
;             PG8_LDB(B0, 1, 0); PG8_LDB(B1, 1, 1); PG8_SCHED; PG8_LDA(At, 1, 0); PG8_STAGE(PG8_SA(0, 1), a2 + hstepA, voffA);
;             PG8_WAIT_V(8); PG8_WAIT_L(0); PG8_BAR; PG8_MMA(0, 0, At, B0); PG8_MMA(0, 1, At, B1); PG8_BAR; PG8_SCHED;
;             PG8_LDA(At, 1, 1); PG8_STAGE(PG8_SB(1, 0), b3, voffB); PG8_STAGE(PG8_SB(1, 1), b3 + hstepB, voffB); PG8_STAGE(PG8_SA(1, 0), a3, voffA);
;             PG8_WAIT_V(8); PG8_WAIT_L(0); PG8_BAR; PG8_MMA(1, 0, At, B0); PG8_MMA(1, 1, At, B1); PG8_BAR; PG8_SCHED;
;         }
	s_waitcnt lgkmcnt(0)
	v_mfma_f32_16x16x32_bf16 v[60:63], v[152:155], v[188:191], v[60:63]
	v_mfma_f32_16x16x32_bf16 v[56:59], v[160:163], v[188:191], v[56:59]
	v_mfma_f32_16x16x32_bf16 v[52:55], v[152:155], v[196:199], v[52:55]
	v_mfma_f32_16x16x32_bf16 v[44:47], v[160:163], v[196:199], v[44:47]
	v_mfma_f32_16x16x32_bf16 v[36:39], v[152:155], v[204:207], v[36:39]
	v_mfma_f32_16x16x32_bf16 v[28:31], v[160:163], v[204:207], v[28:31]
	v_mfma_f32_16x16x32_bf16 v[20:23], v[152:155], v[212:215], v[20:23]
	v_mfma_f32_16x16x32_bf16 v[12:15], v[160:163], v[212:215], v[12:15]
	v_mfma_f32_16x16x32_bf16 v[60:63], v[156:159], v[192:195], v[60:63]
	v_mfma_f32_16x16x32_bf16 v[56:59], v[164:167], v[192:195], v[56:59]
	v_mfma_f32_16x16x32_bf16 v[52:55], v[156:159], v[200:203], v[52:55]
	v_mfma_f32_16x16x32_bf16 v[44:47], v[164:167], v[200:203], v[44:47]
	v_mfma_f32_16x16x32_bf16 v[36:39], v[156:159], v[208:211], v[36:39]
	v_mfma_f32_16x16x32_bf16 v[28:31], v[164:167], v[208:211], v[28:31]
	v_mfma_f32_16x16x32_bf16 v[20:23], v[156:159], v[216:219], v[20:23]
	v_mfma_f32_16x16x32_bf16 v[12:15], v[164:167], v[216:219], v[12:15]
	v_mfma_f32_16x16x32_bf16 v[48:51], v[168:171], v[188:191], v[48:51]
	v_mfma_f32_16x16x32_bf16 v[40:43], v[176:179], v[188:191], v[40:43]
	v_mfma_f32_16x16x32_bf16 v[32:35], v[168:171], v[196:199], v[32:35]
	v_mfma_f32_16x16x32_bf16 v[24:27], v[176:179], v[196:199], v[24:27]
	v_mfma_f32_16x16x32_bf16 v[16:19], v[168:171], v[204:207], v[16:19]
	v_mfma_f32_16x16x32_bf16 v[8:11], v[176:179], v[204:207], v[8:11]
	v_mfma_f32_16x16x32_bf16 v[4:7], v[168:171], v[212:215], v[4:7]
	v_mfma_f32_16x16x32_bf16 v[0:3], v[176:179], v[212:215], v[0:3]
	v_mfma_f32_16x16x32_bf16 v[48:51], v[172:175], v[192:195], v[48:51]
	v_mfma_f32_16x16x32_bf16 v[40:43], v[184:187], v[192:195], v[40:43]
	v_mfma_f32_16x16x32_bf16 v[32:35], v[172:175], v[200:203], v[32:35]
	v_mfma_f32_16x16x32_bf16 v[24:27], v[184:187], v[200:203], v[24:27]
	v_mfma_f32_16x16x32_bf16 v[16:19], v[172:175], v[208:211], v[16:19]
	v_mfma_f32_16x16x32_bf16 v[8:11], v[184:187], v[208:211], v[8:11]
	v_mfma_f32_16x16x32_bf16 v[4:7], v[172:175], v[216:219], v[4:7]
	v_mfma_f32_16x16x32_bf16 v[0:3], v[184:187], v[216:219], v[0:3]
	s_barrier
	s_add_i32 s89, 0, 0x18000
	s_add_i32 s90, 0, 0x1c000
	v_add_u32_e32 v164, s89, v147
	v_add_u32_e32 v183, s90, v147
	ds_read_b128 v[152:155], v164
	ds_read_b128 v[156:159], v164 offset:1024
	ds_read_b128 v[160:163], v164 offset:2048
	ds_read_b128 v[164:167], v164 offset:3072
	ds_read_b128 v[168:171], v183
	ds_read_b128 v[172:175], v183 offset:1024
	ds_read_b128 v[176:179], v183 offset:2048
	ds_read_b128 v[184:187], v183 offset:3072
	s_add_u32 s54, s66, 0x160000
	s_addc_u32 s55, s67, 0
	s_mov_b32 m0, s15
	v_lshl_add_u64 v[226:227], s[54:55], 0, v[128:129]
	ds_read_b128 v[188:191], v151 offset:32768
	ds_read_b128 v[192:195], v151 offset:33792
	ds_read_b128 v[196:199], v151 offset:34816
	ds_read_b128 v[200:203], v151 offset:35840
	ds_read_b128 v[204:207], v151 offset:36864
	ds_read_b128 v[208:211], v151 offset:37888
	ds_read_b128 v[212:215], v151 offset:38912
	ds_read_b128 v[216:219], v151 offset:39936
	global_load_lds_dwordx4 v[226:227], off
	v_lshl_add_u64 v[226:227], s[54:55], 0, v[132:133]
	s_mov_b32 m0, s27
	s_nop 0
	global_load_lds_dwordx4 v[226:227], off
	s_waitcnt vmcnt(8)
	s_waitcnt lgkmcnt(0)
	s_barrier
	s_waitcnt lgkmcnt(0)
	v_mfma_f32_16x16x32_bf16 v[124:127], v[152:155], v[188:191], v[124:127]
	v_mfma_f32_16x16x32_bf16 v[120:123], v[160:163], v[188:191], v[120:123]
	v_mfma_f32_16x16x32_bf16 v[116:119], v[152:155], v[196:199], v[116:119]
	v_mfma_f32_16x16x32_bf16 v[108:111], v[160:163], v[196:199], v[108:111]
	v_mfma_f32_16x16x32_bf16 v[100:103], v[152:155], v[204:207], v[100:103]
	v_mfma_f32_16x16x32_bf16 v[92:95], v[160:163], v[204:207], v[92:95]
	v_mfma_f32_16x16x32_bf16 v[84:87], v[152:155], v[212:215], v[84:87]
	v_mfma_f32_16x16x32_bf16 v[76:79], v[160:163], v[212:215], v[76:79]
	v_mfma_f32_16x16x32_bf16 v[124:127], v[156:159], v[192:195], v[124:127]
	v_mfma_f32_16x16x32_bf16 v[120:123], v[164:167], v[192:195], v[120:123]
	v_mfma_f32_16x16x32_bf16 v[116:119], v[156:159], v[200:203], v[116:119]
	v_mfma_f32_16x16x32_bf16 v[108:111], v[164:167], v[200:203], v[108:111]
	v_mfma_f32_16x16x32_bf16 v[100:103], v[156:159], v[208:211], v[100:103]
	v_mfma_f32_16x16x32_bf16 v[92:95], v[164:167], v[208:211], v[92:95]
	v_mfma_f32_16x16x32_bf16 v[84:87], v[156:159], v[216:219], v[84:87]
	v_mfma_f32_16x16x32_bf16 v[76:79], v[164:167], v[216:219], v[76:79]
	v_mfma_f32_16x16x32_bf16 v[112:115], v[168:171], v[188:191], v[112:115]
	v_mfma_f32_16x16x32_bf16 v[104:107], v[176:179], v[188:191], v[104:107]
	v_mfma_f32_16x16x32_bf16 v[96:99], v[168:171], v[196:199], v[96:99]
	v_mfma_f32_16x16x32_bf16 v[88:91], v[176:179], v[196:199], v[88:91]
	v_mfma_f32_16x16x32_bf16 v[80:83], v[168:171], v[204:207], v[80:83]
	v_mfma_f32_16x16x32_bf16 v[72:75], v[176:179], v[204:207], v[72:75]
	v_mfma_f32_16x16x32_bf16 v[68:71], v[168:171], v[212:215], v[68:71]
	v_mfma_f32_16x16x32_bf16 v[64:67], v[176:179], v[212:215], v[64:67]
	v_mfma_f32_16x16x32_bf16 v[112:115], v[172:175], v[192:195], v[112:115]
	v_mfma_f32_16x16x32_bf16 v[104:107], v[184:187], v[192:195], v[104:107]
	v_mfma_f32_16x16x32_bf16 v[96:99], v[172:175], v[200:203], v[96:99]
	v_mfma_f32_16x16x32_bf16 v[88:91], v[184:187], v[200:203], v[88:91]
	v_mfma_f32_16x16x32_bf16 v[80:83], v[172:175], v[208:211], v[80:83]
	v_mfma_f32_16x16x32_bf16 v[72:75], v[184:187], v[208:211], v[72:75]
	v_mfma_f32_16x16x32_bf16 v[68:71], v[172:175], v[216:219], v[68:71]
	v_mfma_f32_16x16x32_bf16 v[64:67], v[184:187], v[216:219], v[64:67]
	s_barrier
; #define PG8_STAGE(bufoff, gbase, voff) do { _Pragma("unroll") for (int _i = 0; _i < 2; ++_i) \
;         __builtin_amdgcn_global_load_lds((const unsigned*)((const char*)(gbase) + (voff)[_i]), (LAS unsigned*)(lds + (bufoff) + ldsw + _i * 8192), 16, 0, 0); } while (0)
; #define PG8_LDA(dst, b, h) do { _Pragma("unroll") for (int m = 0; m < 4; ++m) _Pragma("unroll") for (int k = 0; k < 2; ++k) dst[m][k] = *(const LAS bf16x8*)(lds + PG8_SA(b, h) + aoff + m * 2048 + k * 1024); } while (0)
; #define PG8_LDB(dst, b, h) do { _Pragma("unroll") for (int n = 0; n < 2; ++n) _Pragma("unroll") for (int k = 0; k < 2; ++k) dst[n][k] = *(const LAS bf16x8*)(lds + PG8_SB(b, h) + boff + n * 2048 + k * 1024); } while (0)
; #define PG8_WAIT_V(n) asm volatile("s_waitcnt vmcnt(" #n ")" ::: "memory")
; #define PG8_BAR __builtin_amdgcn_s_barrier()
; template <bool LT, class Epi>
; __device__ __forceinline__ void gemm_phase(LAS unsigned char* lds, const Gemm g, const StaticOrder& S, const Epi& E) {
;     ...
;         for (int t = 0; t < nt; t += 2) {
;             const bool last = (t == nt - 2);
;             const char* a1 = cA + (size_t)(t + 1) * kstep;
;             const char* a2 = last ? nA : cA + (size_t)(t + 2) * kstep; const char* b2 = last ? nB : cB + (size_t)(t + 2) * kstep;
;             const char* a3 = a2 + kstep; const char* b3 = b2 + kstep;
;             PG8_LDB(B0, 0, 0); PG8_LDB(B1, 0, 1); PG8_SCHED; PG8_LDA(At, 0, 0); PG8_STAGE(PG8_SA(1, 1), a1 + hstepA, voffA);
;             PG8_WAIT_V(8); PG8_WAIT_L(0); PG8_BAR; PG8_MMA(0, 0, At, B0); PG8_MMA(0, 1, At, B1); PG8_BAR; PG8_SCHED;
;             PG8_LDA(At, 0, 1); PG8_STAGE(PG8_SB(0, 0), b2, voffB); PG8_STAGE(PG8_SB(0, 1), b2 + hstepB, voffB); PG8_STAGE(PG8_SA(0, 0), a2, voffA);
;             PG8_WAIT_V(8); PG8_WAIT_L(0); PG8_BAR; PG8_MMA(1, 0, At, B0); PG8_MMA(1, 1, At, B1); PG8_BAR; PG8_SCHED;
;             PG8_LDB(B0, 1, 0); PG8_LDB(B1, 1, 1); PG8_SCHED; PG8_LDA(At, 1, 0); PG8_STAGE(PG8_SA(0, 1), a2 + hstepA, voffA);
;             PG8_WAIT_V(8); PG8_WAIT_L(0); PG8_BAR; PG8_MMA(0, 0, At, B0); PG8_MMA(0, 1, At, B1); PG8_BAR; PG8_SCHED;
;             PG8_LDA(At, 1, 1); PG8_STAGE(PG8_SB(1, 0), b3, voffB); PG8_STAGE(PG8_SB(1, 1), b3 + hstepB, voffB); PG8_STAGE(PG8_SA(1, 0), a3, voffA);
;             PG8_WAIT_V(8); PG8_WAIT_L(0); PG8_BAR; PG8_MMA(1, 0, At, B0); PG8_MMA(1, 1, At, B1); PG8_BAR; PG8_SCHED;
;         }
	s_add_i32 s54, s89, s10
	v_lshl_add_u64 v[144:145], v[144:145], 0, s[44:45]
	s_mov_b32 m0, s54
	ds_read_b128 v[188:191], v151 offset:49152
	ds_read_b128 v[192:195], v151 offset:50176
	ds_read_b128 v[196:199], v151 offset:51200
	ds_read_b128 v[200:203], v151 offset:52224
	ds_read_b128 v[204:207], v151 offset:53248
	ds_read_b128 v[208:211], v151 offset:54272
	ds_read_b128 v[212:215], v151 offset:55296
	ds_read_b128 v[216:219], v151 offset:56320
	global_load_lds_dwordx4 v[144:145], off
	s_add_i32 m0, s54, 0x2000
	s_add_u32 s54, s62, 0x160080
	v_lshl_add_u64 v[144:145], v[220:221], 0, s[44:45]
	s_addc_u32 s55, s63, 0
	s_add_i32 s62, s90, s10
	global_load_lds_dwordx4 v[144:145], off
	v_lshl_add_u64 v[144:145], s[54:55], 0, v[130:131]
	s_mov_b32 m0, s62
	s_nop 0
	global_load_lds_dwordx4 v[144:145], off
	v_lshl_add_u64 v[144:145], s[54:55], 0, v[134:135]
	s_add_i32 m0, s62, 0x2000
	s_nop 0
	global_load_lds_dwordx4 v[144:145], off
	v_lshl_add_u64 v[144:145], v[222:223], 0, s[44:45]
	s_mov_b32 m0, s42
	s_nop 0
	global_load_lds_dwordx4 v[144:145], off
	v_lshl_add_u64 v[144:145], v[224:225], 0, s[44:45]
	s_mov_b32 m0, s43
	s_nop 0
	global_load_lds_dwordx4 v[144:145], off
	s_waitcnt vmcnt(8)
	s_waitcnt lgkmcnt(0)
	s_barrier
	s_waitcnt lgkmcnt(0)
	v_mfma_f32_16x16x32_bf16 v[60:63], v[152:155], v[188:191], v[60:63]
	v_mfma_f32_16x16x32_bf16 v[56:59], v[160:163], v[188:191], v[56:59]
	v_mfma_f32_16x16x32_bf16 v[52:55], v[152:155], v[196:199], v[52:55]
	v_mfma_f32_16x16x32_bf16 v[44:47], v[160:163], v[196:199], v[44:47]
	v_mfma_f32_16x16x32_bf16 v[36:39], v[152:155], v[204:207], v[36:39]
	v_mfma_f32_16x16x32_bf16 v[28:31], v[160:163], v[204:207], v[28:31]
	v_mfma_f32_16x16x32_bf16 v[20:23], v[152:155], v[212:215], v[20:23]
	v_mfma_f32_16x16x32_bf16 v[12:15], v[160:163], v[212:215], v[12:15]
	v_mfma_f32_16x16x32_bf16 v[60:63], v[156:159], v[192:195], v[60:63]
	v_mfma_f32_16x16x32_bf16 v[56:59], v[164:167], v[192:195], v[56:59]
	v_mfma_f32_16x16x32_bf16 v[52:55], v[156:159], v[200:203], v[52:55]
	v_mfma_f32_16x16x32_bf16 v[44:47], v[164:167], v[200:203], v[44:47]
	v_mfma_f32_16x16x32_bf16 v[36:39], v[156:159], v[208:211], v[36:39]
	v_mfma_f32_16x16x32_bf16 v[28:31], v[164:167], v[208:211], v[28:31]
	v_mfma_f32_16x16x32_bf16 v[20:23], v[156:159], v[216:219], v[20:23]
	v_mfma_f32_16x16x32_bf16 v[12:15], v[164:167], v[216:219], v[12:15]
	v_mfma_f32_16x16x32_bf16 v[48:51], v[168:171], v[188:191], v[48:51]
	v_mfma_f32_16x16x32_bf16 v[40:43], v[176:179], v[188:191], v[40:43]
	v_mfma_f32_16x16x32_bf16 v[32:35], v[168:171], v[196:199], v[32:35]
	v_mfma_f32_16x16x32_bf16 v[24:27], v[176:179], v[196:199], v[24:27]
	v_mfma_f32_16x16x32_bf16 v[16:19], v[168:171], v[204:207], v[16:19]
	v_mfma_f32_16x16x32_bf16 v[8:11], v[176:179], v[204:207], v[8:11]
	v_mfma_f32_16x16x32_bf16 v[4:7], v[168:171], v[212:215], v[4:7]
	v_mfma_f32_16x16x32_bf16 v[0:3], v[176:179], v[212:215], v[0:3]
	v_mfma_f32_16x16x32_bf16 v[48:51], v[172:175], v[192:195], v[48:51]
	v_mfma_f32_16x16x32_bf16 v[40:43], v[184:187], v[192:195], v[40:43]
	v_mfma_f32_16x16x32_bf16 v[32:35], v[172:175], v[200:203], v[32:35]
	v_mfma_f32_16x16x32_bf16 v[24:27], v[184:187], v[200:203], v[24:27]
	v_mfma_f32_16x16x32_bf16 v[16:19], v[172:175], v[208:211], v[16:19]
	v_mfma_f32_16x16x32_bf16 v[8:11], v[184:187], v[208:211], v[8:11]
	v_mfma_f32_16x16x32_bf16 v[4:7], v[172:175], v[216:219], v[4:7]
	v_mfma_f32_16x16x32_bf16 v[0:3], v[184:187], v[216:219], v[0:3]
	s_barrier
	s_add_i32 s88, s88, 2
	s_add_u32 s76, s76, 0x100
	s_addc_u32 s77, s77, 0
	s_cmpk_gt_u32 s88, 0x55
	s_mov_b64 s[54:55], s[58:59]
	s_cbranch_scc0 .LBB0_237
	s_and_b64 vcc, exec, s[46:47]
	s_cbranch_vccz .LBB0_240
	s_barrier

; #define PG8_STAGE(bufoff, gbase, voff) do { _Pragma("unroll") for (int _i = 0; _i < 2; ++_i) \
;         __builtin_amdgcn_global_load_lds((const unsigned*)((const char*)(gbase) + (voff)[_i]), (LAS unsigned*)(lds + (bufoff) + ldsw + _i * 8192), 16, 0, 0); } while (0)
; #define PG8_LDA(dst, b, h) do { _Pragma("unroll") for (int m = 0; m < 4; ++m) _Pragma("unroll") for (int k = 0; k < 2; ++k) dst[m][k] = *(const LAS bf16x8*)(lds + PG8_SA(b, h) + aoff + m * 2048 + k * 1024); } while (0)
; #define PG8_LDB(dst, b, h) do { _Pragma("unroll") for (int n = 0; n < 2; ++n) _Pragma("unroll") for (int k = 0; k < 2; ++k) dst[n][k] = *(const LAS bf16x8*)(lds + PG8_SB(b, h) + boff + n * 2048 + k * 1024); } while (0)
; #define PG8_WAIT_V(n) asm volatile("s_waitcnt vmcnt(" #n ")" ::: "memory")
; #define PG8_BAR __builtin_amdgcn_s_barrier()
; template <bool LT, class Epi>
; __device__ __forceinline__ void gemm_phase(LAS unsigned char* lds, const Gemm g, const StaticOrder& S, const Epi& E) {
;     ...
;         for (int t = 0; t < nt; t += 2) {
;             const bool last = (t == nt - 2);
;             const char* a1 = cA + (size_t)(t + 1) * kstep;
;             const char* a2 = last ? nA : cA + (size_t)(t + 2) * kstep; const char* b2 = last ? nB : cB + (size_t)(t + 2) * kstep;
;             const char* a3 = a2 + kstep; const char* b3 = b2 + kstep;
;             PG8_LDB(B0, 0, 0); PG8_LDB(B1, 0, 1); PG8_SCHED; PG8_LDA(At, 0, 0); PG8_STAGE(PG8_SA(1, 1), a1 + hstepA, voffA);
;             PG8_WAIT_V(8); PG8_WAIT_L(0); PG8_BAR; PG8_MMA(0, 0, At, B0); PG8_MMA(0, 1, At, B1); PG8_BAR; PG8_SCHED;
;             PG8_LDA(At, 0, 1); PG8_STAGE(PG8_SB(0, 0), b2, voffB); PG8_STAGE(PG8_SB(0, 1), b2 + hstepB, voffB); PG8_STAGE(PG8_SA(0, 0), a2, voffA);
;             PG8_WAIT_V(8); PG8_WAIT_L(0); PG8_BAR; PG8_MMA(1, 0, At, B0); PG8_MMA(1, 1, At, B1); PG8_BAR; PG8_SCHED;
;             PG8_LDB(B0, 1, 0); PG8_LDB(B1, 1, 1); PG8_SCHED; PG8_LDA(At, 1, 0); PG8_STAGE(PG8_SA(0, 1), a2 + hstepA, voffA);
;             PG8_WAIT_V(8); PG8_WAIT_L(0); PG8_BAR; PG8_MMA(0, 0, At, B0); PG8_MMA(0, 1, At, B1); PG8_BAR; PG8_SCHED;
;             PG8_LDA(At, 1, 1); PG8_STAGE(PG8_SB(1, 0), b3, voffB); PG8_STAGE(PG8_SB(1, 1), b3 + hstepB, voffB); PG8_STAGE(PG8_SA(1, 0), a3, voffA);
;             PG8_WAIT_V(8); PG8_WAIT_L(0); PG8_BAR; PG8_MMA(1, 0, At, B0); PG8_MMA(1, 1, At, B1); PG8_BAR; PG8_SCHED;
;         }
.LBB0_366:
	ds_read_b128 v[150:153], v172
	ds_read_b128 v[176:179], v172 offset:1024
	ds_read_b128 v[184:187], v172 offset:2048
	ds_read_b128 v[188:191], v172 offset:3072
	ds_read_b128 v[192:195], v173
	ds_read_b128 v[196:199], v173 offset:1024
	ds_read_b128 v[200:203], v173 offset:2048
	ds_read_b128 v[204:207], v173 offset:3072
	s_add_u32 s70, s68, 0x100
	s_addc_u32 s71, s69, 0
	s_cmp_eq_u32 vcc_lo, 28
	s_cselect_b32 s75, s14, s71
	s_cselect_b32 s74, s15, s70
	s_cselect_b32 s73, s46, s57
	s_cselect_b32 s72, s47, s55
	v_lshl_add_u64 v[154:155], s[68:69], 0, v[140:141]
	s_add_i32 m0, s43, 0xc000
	ds_read_b128 v[208:211], v174
	ds_read_b128 v[212:215], v174 offset:1024
	ds_read_b128 v[216:219], v174 offset:2048
	ds_read_b128 v[220:223], v174 offset:3072
	ds_read_b128 v[224:227], v174 offset:4096
	ds_read_b128 v[228:231], v174 offset:5120
	ds_read_b128 v[232:235], v174 offset:6144
	ds_read_b128 v[236:239], v174 offset:7168
	global_load_lds_dwordx4 v[154:155], off
	v_lshl_add_u64 v[154:155], s[68:69], 0, v[142:143]
	s_add_i32 m0, s43, 0xe000
	s_nop 0
	global_load_lds_dwordx4 v[154:155], off
	s_waitcnt vmcnt(8)
	s_waitcnt lgkmcnt(0)
	s_barrier
	s_waitcnt lgkmcnt(0)
	v_mfma_f32_16x16x32_bf16 v[124:127], v[150:153], v[208:211], v[124:127]
	v_mfma_f32_16x16x32_bf16 v[120:123], v[184:187], v[208:211], v[120:123]
	v_mfma_f32_16x16x32_bf16 v[112:115], v[150:153], v[216:219], v[112:115]
	v_mfma_f32_16x16x32_bf16 v[104:107], v[184:187], v[216:219], v[104:107]
	v_mfma_f32_16x16x32_bf16 v[96:99], v[150:153], v[224:227], v[96:99]
	v_mfma_f32_16x16x32_bf16 v[88:91], v[184:187], v[224:227], v[88:91]
	v_mfma_f32_16x16x32_bf16 v[80:83], v[150:153], v[232:235], v[80:83]
	v_mfma_f32_16x16x32_bf16 v[72:75], v[184:187], v[232:235], v[72:75]
	v_mfma_f32_16x16x32_bf16 v[124:127], v[176:179], v[212:215], v[124:127]
	v_mfma_f32_16x16x32_bf16 v[120:123], v[188:191], v[212:215], v[120:123]
	v_mfma_f32_16x16x32_bf16 v[112:115], v[176:179], v[220:223], v[112:115]
	v_mfma_f32_16x16x32_bf16 v[104:107], v[188:191], v[220:223], v[104:107]
	v_mfma_f32_16x16x32_bf16 v[96:99], v[176:179], v[228:231], v[96:99]
	v_mfma_f32_16x16x32_bf16 v[88:91], v[188:191], v[228:231], v[88:91]
	v_mfma_f32_16x16x32_bf16 v[80:83], v[176:179], v[236:239], v[80:83]
	v_mfma_f32_16x16x32_bf16 v[72:75], v[188:191], v[236:239], v[72:75]
	v_mfma_f32_16x16x32_bf16 v[116:119], v[192:195], v[208:211], v[116:119]
	v_mfma_f32_16x16x32_bf16 v[108:111], v[200:203], v[208:211], v[108:111]
	v_mfma_f32_16x16x32_bf16 v[100:103], v[192:195], v[216:219], v[100:103]
	v_mfma_f32_16x16x32_bf16 v[92:95], v[200:203], v[216:219], v[92:95]
	v_mfma_f32_16x16x32_bf16 v[84:87], v[192:195], v[224:227], v[84:87]
	v_mfma_f32_16x16x32_bf16 v[76:79], v[200:203], v[224:227], v[76:79]
	v_mfma_f32_16x16x32_bf16 v[68:71], v[192:195], v[232:235], v[68:71]
	v_mfma_f32_16x16x32_bf16 v[64:67], v[200:203], v[232:235], v[64:67]
	v_mfma_f32_16x16x32_bf16 v[116:119], v[196:199], v[212:215], v[116:119]
	v_mfma_f32_16x16x32_bf16 v[108:111], v[204:207], v[212:215], v[108:111]
	v_mfma_f32_16x16x32_bf16 v[100:103], v[196:199], v[220:223], v[100:103]
	v_mfma_f32_16x16x32_bf16 v[92:95], v[204:207], v[220:223], v[92:95]
	v_mfma_f32_16x16x32_bf16 v[84:87], v[196:199], v[228:231], v[84:87]
	v_mfma_f32_16x16x32_bf16 v[76:79], v[204:207], v[228:231], v[76:79]
	v_mfma_f32_16x16x32_bf16 v[68:71], v[196:199], v[236:239], v[68:71]
	v_mfma_f32_16x16x32_bf16 v[64:67], v[204:207], v[236:239], v[64:67]
	s_barrier
	s_add_i32 s68, s95, s42
	v_lshl_add_u64 v[154:155], s[72:73], 0, v[136:137]
	s_mov_b32 m0, s68
	ds_read_b128 v[208:211], v174 offset:16384
	ds_read_b128 v[212:215], v174 offset:17408
	ds_read_b128 v[216:219], v174 offset:18432
	ds_read_b128 v[220:223], v174 offset:19456
	ds_read_b128 v[224:227], v174 offset:20480
	ds_read_b128 v[228:231], v174 offset:21504
	ds_read_b128 v[232:235], v174 offset:22528
	ds_read_b128 v[236:239], v174 offset:23552
	global_load_lds_dwordx4 v[154:155], off
	s_add_i32 m0, s68, 0x2000
	s_add_u32 s68, s72, 0x80000
	v_lshl_add_u64 v[240:241], s[72:73], 0, v[138:139]
	s_addc_u32 s69, s73, 0
	s_add_i32 vcc_hi, s33, s42
	global_load_lds_dwordx4 v[240:241], off
	v_lshl_add_u64 v[242:243], s[68:69], 0, v[136:137]
	s_mov_b32 m0, vcc_hi
	v_lshl_add_u64 v[244:245], s[74:75], 0, v[130:131]
	global_load_lds_dwordx4 v[242:243], off
	v_lshl_add_u64 v[242:243], s[68:69], 0, v[138:139]
	s_add_i32 m0, vcc_hi, 0x2000
	s_nop 0
	global_load_lds_dwordx4 v[242:243], off
	v_lshl_add_u64 v[242:243], s[74:75], 0, v[128:129]
	s_mov_b32 m0, s43
	s_nop 0
	global_load_lds_dwordx4 v[242:243], off
	s_mov_b32 m0, s67
	s_nop 0
	global_load_lds_dwordx4 v[244:245], off
	s_waitcnt vmcnt(8)
	s_waitcnt lgkmcnt(0)
	s_barrier
; #define PG8_STAGE(bufoff, gbase, voff) do { _Pragma("unroll") for (int _i = 0; _i < 2; ++_i) \
;         __builtin_amdgcn_global_load_lds((const unsigned*)((const char*)(gbase) + (voff)[_i]), (LAS unsigned*)(lds + (bufoff) + ldsw + _i * 8192), 16, 0, 0); } while (0)
; #define PG8_LDA(dst, b, h) do { _Pragma("unroll") for (int m = 0; m < 4; ++m) _Pragma("unroll") for (int k = 0; k < 2; ++k) dst[m][k] = *(const LAS bf16x8*)(lds + PG8_SA(b, h) + aoff + m * 2048 + k * 1024); } while (0)
; #define PG8_LDB(dst, b, h) do { _Pragma("unroll") for (int n = 0; n < 2; ++n) _Pragma("unroll") for (int k = 0; k < 2; ++k) dst[n][k] = *(const LAS bf16x8*)(lds + PG8_SB(b, h) + boff + n * 2048 + k * 1024); } while (0)
; #define PG8_WAIT_V(n) asm volatile("s_waitcnt vmcnt(" #n ")" ::: "memory")
; #define PG8_BAR __builtin_amdgcn_s_barrier()
; template <bool LT, class Epi>
; __device__ __forceinline__ void gemm_phase(LAS unsigned char* lds, const Gemm g, const StaticOrder& S, const Epi& E) {
;     ...
;         for (int t = 0; t < nt; t += 2) {
;             const bool last = (t == nt - 2);
;             const char* a1 = cA + (size_t)(t + 1) * kstep;
;             const char* a2 = last ? nA : cA + (size_t)(t + 2) * kstep; const char* b2 = last ? nB : cB + (size_t)(t + 2) * kstep;
;             const char* a3 = a2 + kstep; const char* b3 = b2 + kstep;
;             PG8_LDB(B0, 0, 0); PG8_LDB(B1, 0, 1); PG8_SCHED; PG8_LDA(At, 0, 0); PG8_STAGE(PG8_SA(1, 1), a1 + hstepA, voffA);
;             PG8_WAIT_V(8); PG8_WAIT_L(0); PG8_BAR; PG8_MMA(0, 0, At, B0); PG8_MMA(0, 1, At, B1); PG8_BAR; PG8_SCHED;
;             PG8_LDA(At, 0, 1); PG8_STAGE(PG8_SB(0, 0), b2, voffB); PG8_STAGE(PG8_SB(0, 1), b2 + hstepB, voffB); PG8_STAGE(PG8_SA(0, 0), a2, voffA);
;             PG8_WAIT_V(8); PG8_WAIT_L(0); PG8_BAR; PG8_MMA(1, 0, At, B0); PG8_MMA(1, 1, At, B1); PG8_BAR; PG8_SCHED;
;             PG8_LDB(B0, 1, 0); PG8_LDB(B1, 1, 1); PG8_SCHED; PG8_LDA(At, 1, 0); PG8_STAGE(PG8_SA(0, 1), a2 + hstepA, voffA);
;             PG8_WAIT_V(8); PG8_WAIT_L(0); PG8_BAR; PG8_MMA(0, 0, At, B0); PG8_MMA(0, 1, At, B1); PG8_BAR; PG8_SCHED;
;             PG8_LDA(At, 1, 1); PG8_STAGE(PG8_SB(1, 0), b3, voffB); PG8_STAGE(PG8_SB(1, 1), b3 + hstepB, voffB); PG8_STAGE(PG8_SA(1, 0), a3, voffA);
;             PG8_WAIT_V(8); PG8_WAIT_L(0); PG8_BAR; PG8_MMA(1, 0, At, B0); PG8_MMA(1, 1, At, B1); PG8_BAR; PG8_SCHED;
;         }
	s_waitcnt lgkmcnt(0)
	v_mfma_f32_16x16x32_bf16 v[60:63], v[150:153], v[208:211], v[60:63]
	v_mfma_f32_16x16x32_bf16 v[56:59], v[184:187], v[208:211], v[56:59]
	v_mfma_f32_16x16x32_bf16 v[48:51], v[150:153], v[216:219], v[48:51]
	v_mfma_f32_16x16x32_bf16 v[40:43], v[184:187], v[216:219], v[40:43]
	v_mfma_f32_16x16x32_bf16 v[32:35], v[150:153], v[224:227], v[32:35]
	v_mfma_f32_16x16x32_bf16 v[24:27], v[184:187], v[224:227], v[24:27]
	v_mfma_f32_16x16x32_bf16 v[16:19], v[150:153], v[232:235], v[16:19]
	v_mfma_f32_16x16x32_bf16 v[8:11], v[184:187], v[232:235], v[8:11]
	v_mfma_f32_16x16x32_bf16 v[60:63], v[176:179], v[212:215], v[60:63]
	v_mfma_f32_16x16x32_bf16 v[56:59], v[188:191], v[212:215], v[56:59]
	v_mfma_f32_16x16x32_bf16 v[48:51], v[176:179], v[220:223], v[48:51]
	v_mfma_f32_16x16x32_bf16 v[40:43], v[188:191], v[220:223], v[40:43]
	v_mfma_f32_16x16x32_bf16 v[32:35], v[176:179], v[228:231], v[32:35]
	v_mfma_f32_16x16x32_bf16 v[24:27], v[188:191], v[228:231], v[24:27]
	v_mfma_f32_16x16x32_bf16 v[16:19], v[176:179], v[236:239], v[16:19]
	v_mfma_f32_16x16x32_bf16 v[8:11], v[188:191], v[236:239], v[8:11]
	v_mfma_f32_16x16x32_bf16 v[52:55], v[192:195], v[208:211], v[52:55]
	v_mfma_f32_16x16x32_bf16 v[44:47], v[200:203], v[208:211], v[44:47]
	v_mfma_f32_16x16x32_bf16 v[36:39], v[192:195], v[216:219], v[36:39]
	v_mfma_f32_16x16x32_bf16 v[28:31], v[200:203], v[216:219], v[28:31]
	v_mfma_f32_16x16x32_bf16 v[20:23], v[192:195], v[224:227], v[20:23]
	v_mfma_f32_16x16x32_bf16 v[12:15], v[200:203], v[224:227], v[12:15]
	v_mfma_f32_16x16x32_bf16 v[4:7], v[192:195], v[232:235], v[4:7]
	v_mfma_f32_16x16x32_bf16 v[0:3], v[200:203], v[232:235], v[0:3]
	v_mfma_f32_16x16x32_bf16 v[52:55], v[196:199], v[212:215], v[52:55]
	v_mfma_f32_16x16x32_bf16 v[44:47], v[204:207], v[212:215], v[44:47]
	v_mfma_f32_16x16x32_bf16 v[36:39], v[196:199], v[220:223], v[36:39]
	v_mfma_f32_16x16x32_bf16 v[28:31], v[204:207], v[220:223], v[28:31]
	v_mfma_f32_16x16x32_bf16 v[20:23], v[196:199], v[228:231], v[20:23]
	v_mfma_f32_16x16x32_bf16 v[12:15], v[204:207], v[228:231], v[12:15]
	v_mfma_f32_16x16x32_bf16 v[4:7], v[196:199], v[236:239], v[4:7]
	v_mfma_f32_16x16x32_bf16 v[0:3], v[204:207], v[236:239], v[0:3]
	s_barrier
	s_add_i32 vcc_hi, 0, 0x18000
	v_add_u32_e32 v132, vcc_hi, v169
	s_add_i32 s12, 0, 0x1c000
	ds_read_b128 v[150:153], v132
	ds_read_b128 v[176:179], v132 offset:1024
	ds_read_b128 v[184:187], v132 offset:2048
	ds_read_b128 v[188:191], v132 offset:3072
	v_add_u32_e32 v132, s12, v169
	ds_read_b128 v[192:195], v132
	ds_read_b128 v[196:199], v132 offset:1024
	ds_read_b128 v[200:203], v132 offset:2048
	ds_read_b128 v[204:207], v132 offset:3072
	s_add_u32 s68, s74, 0x80000
	s_addc_u32 s69, s75, 0
	s_mov_b32 m0, s76
	v_lshl_add_u64 v[246:247], s[68:69], 0, v[128:129]
	ds_read_b128 v[208:211], v174 offset:32768
	ds_read_b128 v[212:215], v174 offset:33792
	ds_read_b128 v[216:219], v174 offset:34816
	ds_read_b128 v[220:223], v174 offset:35840
	ds_read_b128 v[224:227], v174 offset:36864
	ds_read_b128 v[228:231], v174 offset:37888
	ds_read_b128 v[232:235], v174 offset:38912
	ds_read_b128 v[236:239], v174 offset:39936
	global_load_lds_dwordx4 v[246:247], off
	v_lshl_add_u64 v[246:247], s[68:69], 0, v[130:131]
	s_mov_b32 m0, s77
	s_nop 0
	global_load_lds_dwordx4 v[246:247], off
	s_waitcnt vmcnt(8)
	s_waitcnt lgkmcnt(0)
	s_barrier
	s_waitcnt lgkmcnt(0)
	v_mfma_f32_16x16x32_bf16 v[124:127], v[150:153], v[208:211], v[124:127]
	v_mfma_f32_16x16x32_bf16 v[120:123], v[184:187], v[208:211], v[120:123]
	v_mfma_f32_16x16x32_bf16 v[112:115], v[150:153], v[216:219], v[112:115]
	v_mfma_f32_16x16x32_bf16 v[104:107], v[184:187], v[216:219], v[104:107]
	v_mfma_f32_16x16x32_bf16 v[96:99], v[150:153], v[224:227], v[96:99]
	v_mfma_f32_16x16x32_bf16 v[88:91], v[184:187], v[224:227], v[88:91]
	v_mfma_f32_16x16x32_bf16 v[80:83], v[150:153], v[232:235], v[80:83]
	v_mfma_f32_16x16x32_bf16 v[72:75], v[184:187], v[232:235], v[72:75]
	v_mfma_f32_16x16x32_bf16 v[124:127], v[176:179], v[212:215], v[124:127]
	v_mfma_f32_16x16x32_bf16 v[120:123], v[188:191], v[212:215], v[120:123]
	v_mfma_f32_16x16x32_bf16 v[112:115], v[176:179], v[220:223], v[112:115]
	v_mfma_f32_16x16x32_bf16 v[104:107], v[188:191], v[220:223], v[104:107]
	v_mfma_f32_16x16x32_bf16 v[96:99], v[176:179], v[228:231], v[96:99]
	v_mfma_f32_16x16x32_bf16 v[88:91], v[188:191], v[228:231], v[88:91]
	v_mfma_f32_16x16x32_bf16 v[80:83], v[176:179], v[236:239], v[80:83]
	v_mfma_f32_16x16x32_bf16 v[72:75], v[188:191], v[236:239], v[72:75]
	v_mfma_f32_16x16x32_bf16 v[116:119], v[192:195], v[208:211], v[116:119]
	v_mfma_f32_16x16x32_bf16 v[108:111], v[200:203], v[208:211], v[108:111]
	v_mfma_f32_16x16x32_bf16 v[100:103], v[192:195], v[216:219], v[100:103]
	v_mfma_f32_16x16x32_bf16 v[92:95], v[200:203], v[216:219], v[92:95]
	v_mfma_f32_16x16x32_bf16 v[84:87], v[192:195], v[224:227], v[84:87]
	v_mfma_f32_16x16x32_bf16 v[76:79], v[200:203], v[224:227], v[76:79]
	v_mfma_f32_16x16x32_bf16 v[68:71], v[192:195], v[232:235], v[68:71]
	v_mfma_f32_16x16x32_bf16 v[64:67], v[200:203], v[232:235], v[64:67]
	v_mfma_f32_16x16x32_bf16 v[116:119], v[196:199], v[212:215], v[116:119]
	v_mfma_f32_16x16x32_bf16 v[108:111], v[204:207], v[212:215], v[108:111]
	v_mfma_f32_16x16x32_bf16 v[100:103], v[196:199], v[220:223], v[100:103]
	v_mfma_f32_16x16x32_bf16 v[92:95], v[204:207], v[220:223], v[92:95]
	v_mfma_f32_16x16x32_bf16 v[84:87], v[196:199], v[228:231], v[84:87]
	v_mfma_f32_16x16x32_bf16 v[76:79], v[204:207], v[228:231], v[76:79]
	v_mfma_f32_16x16x32_bf16 v[68:71], v[196:199], v[236:239], v[68:71]
	v_mfma_f32_16x16x32_bf16 v[64:67], v[204:207], v[236:239], v[64:67]
	s_barrier
; #define PG8_STAGE(bufoff, gbase, voff) do { _Pragma("unroll") for (int _i = 0; _i < 2; ++_i) \
;         __builtin_amdgcn_global_load_lds((const unsigned*)((const char*)(gbase) + (voff)[_i]), (LAS unsigned*)(lds + (bufoff) + ldsw + _i * 8192), 16, 0, 0); } while (0)
; #define PG8_LDA(dst, b, h) do { _Pragma("unroll") for (int m = 0; m < 4; ++m) _Pragma("unroll") for (int k = 0; k < 2; ++k) dst[m][k] = *(const LAS bf16x8*)(lds + PG8_SA(b, h) + aoff + m * 2048 + k * 1024); } while (0)
; #define PG8_LDB(dst, b, h) do { _Pragma("unroll") for (int n = 0; n < 2; ++n) _Pragma("unroll") for (int k = 0; k < 2; ++k) dst[n][k] = *(const LAS bf16x8*)(lds + PG8_SB(b, h) + boff + n * 2048 + k * 1024); } while (0)
; #define PG8_WAIT_V(n) asm volatile("s_waitcnt vmcnt(" #n ")" ::: "memory")
; #define PG8_BAR __builtin_amdgcn_s_barrier()
; template <bool LT, class Epi>
; __device__ __forceinline__ void gemm_phase(LAS unsigned char* lds, const Gemm g, const StaticOrder& S, const Epi& E) {
;     ...
;         for (int t = 0; t < nt; t += 2) {
;             const bool last = (t == nt - 2);
;             const char* a1 = cA + (size_t)(t + 1) * kstep;
;             const char* a2 = last ? nA : cA + (size_t)(t + 2) * kstep; const char* b2 = last ? nB : cB + (size_t)(t + 2) * kstep;
;             const char* a3 = a2 + kstep; const char* b3 = b2 + kstep;
;             PG8_LDB(B0, 0, 0); PG8_LDB(B1, 0, 1); PG8_SCHED; PG8_LDA(At, 0, 0); PG8_STAGE(PG8_SA(1, 1), a1 + hstepA, voffA);
;             PG8_WAIT_V(8); PG8_WAIT_L(0); PG8_BAR; PG8_MMA(0, 0, At, B0); PG8_MMA(0, 1, At, B1); PG8_BAR; PG8_SCHED;
;             PG8_LDA(At, 0, 1); PG8_STAGE(PG8_SB(0, 0), b2, voffB); PG8_STAGE(PG8_SB(0, 1), b2 + hstepB, voffB); PG8_STAGE(PG8_SA(0, 0), a2, voffA);
;             PG8_WAIT_V(8); PG8_WAIT_L(0); PG8_BAR; PG8_MMA(1, 0, At, B0); PG8_MMA(1, 1, At, B1); PG8_BAR; PG8_SCHED;
;             PG8_LDB(B0, 1, 0); PG8_LDB(B1, 1, 1); PG8_SCHED; PG8_LDA(At, 1, 0); PG8_STAGE(PG8_SA(0, 1), a2 + hstepA, voffA);
;             PG8_WAIT_V(8); PG8_WAIT_L(0); PG8_BAR; PG8_MMA(0, 0, At, B0); PG8_MMA(0, 1, At, B1); PG8_BAR; PG8_SCHED;
;             PG8_LDA(At, 1, 1); PG8_STAGE(PG8_SB(1, 0), b3, voffB); PG8_STAGE(PG8_SB(1, 1), b3 + hstepB, voffB); PG8_STAGE(PG8_SA(1, 0), a3, voffA);
;             PG8_WAIT_V(8); PG8_WAIT_L(0); PG8_BAR; PG8_MMA(1, 0, At, B0); PG8_MMA(1, 1, At, B1); PG8_BAR; PG8_SCHED;
;         }
	s_add_i32 s13, vcc_hi, s42
	v_lshl_add_u64 v[154:155], v[154:155], 0, s[20:21]
	s_mov_b32 m0, s13
	ds_read_b128 v[208:211], v174 offset:49152
	ds_read_b128 v[212:215], v174 offset:50176
	ds_read_b128 v[216:219], v174 offset:51200
	ds_read_b128 v[220:223], v174 offset:52224
	ds_read_b128 v[224:227], v174 offset:53248
	ds_read_b128 v[228:231], v174 offset:54272
	ds_read_b128 v[232:235], v174 offset:55296
	ds_read_b128 v[236:239], v174 offset:56320
	global_load_lds_dwordx4 v[154:155], off
	s_add_i32 m0, s13, 0x2000
	s_add_u32 s68, s72, 0x80080
	v_lshl_add_u64 v[154:155], v[240:241], 0, s[20:21]
	s_addc_u32 s69, s73, 0
	s_add_i32 s12, s12, s42
	global_load_lds_dwordx4 v[154:155], off
	v_lshl_add_u64 v[154:155], s[68:69], 0, v[136:137]
	s_mov_b32 m0, s12
	s_nop 0
	global_load_lds_dwordx4 v[154:155], off
	v_lshl_add_u64 v[154:155], s[68:69], 0, v[138:139]
	s_add_i32 m0, s12, 0x2000
	s_nop 0
	global_load_lds_dwordx4 v[154:155], off
	v_lshl_add_u64 v[154:155], v[242:243], 0, s[20:21]
	s_mov_b32 m0, s90
	s_nop 0
	global_load_lds_dwordx4 v[154:155], off
	v_lshl_add_u64 v[154:155], v[244:245], 0, s[20:21]
	s_mov_b32 m0, s91
	s_nop 0
	global_load_lds_dwordx4 v[154:155], off
	s_waitcnt vmcnt(8)
	s_waitcnt lgkmcnt(0)
	s_barrier
	s_waitcnt lgkmcnt(0)
	v_mfma_f32_16x16x32_bf16 v[60:63], v[150:153], v[208:211], v[60:63]
	v_mfma_f32_16x16x32_bf16 v[56:59], v[184:187], v[208:211], v[56:59]
	v_mfma_f32_16x16x32_bf16 v[48:51], v[150:153], v[216:219], v[48:51]
	v_mfma_f32_16x16x32_bf16 v[40:43], v[184:187], v[216:219], v[40:43]
	v_mfma_f32_16x16x32_bf16 v[32:35], v[150:153], v[224:227], v[32:35]
	v_mfma_f32_16x16x32_bf16 v[24:27], v[184:187], v[224:227], v[24:27]
	v_mfma_f32_16x16x32_bf16 v[16:19], v[150:153], v[232:235], v[16:19]
	v_mfma_f32_16x16x32_bf16 v[8:11], v[184:187], v[232:235], v[8:11]
	v_mfma_f32_16x16x32_bf16 v[60:63], v[176:179], v[212:215], v[60:63]
	v_mfma_f32_16x16x32_bf16 v[56:59], v[188:191], v[212:215], v[56:59]
	v_mfma_f32_16x16x32_bf16 v[48:51], v[176:179], v[220:223], v[48:51]
	v_mfma_f32_16x16x32_bf16 v[40:43], v[188:191], v[220:223], v[40:43]
	v_mfma_f32_16x16x32_bf16 v[32:35], v[176:179], v[228:231], v[32:35]
	v_mfma_f32_16x16x32_bf16 v[24:27], v[188:191], v[228:231], v[24:27]
	v_mfma_f32_16x16x32_bf16 v[16:19], v[176:179], v[236:239], v[16:19]
	v_mfma_f32_16x16x32_bf16 v[8:11], v[188:191], v[236:239], v[8:11]
	v_mfma_f32_16x16x32_bf16 v[52:55], v[192:195], v[208:211], v[52:55]
	v_mfma_f32_16x16x32_bf16 v[44:47], v[200:203], v[208:211], v[44:47]
	v_mfma_f32_16x16x32_bf16 v[36:39], v[192:195], v[216:219], v[36:39]
	v_mfma_f32_16x16x32_bf16 v[28:31], v[200:203], v[216:219], v[28:31]
	v_mfma_f32_16x16x32_bf16 v[20:23], v[192:195], v[224:227], v[20:23]
	v_mfma_f32_16x16x32_bf16 v[12:15], v[200:203], v[224:227], v[12:15]
	v_mfma_f32_16x16x32_bf16 v[4:7], v[192:195], v[232:235], v[4:7]
	v_mfma_f32_16x16x32_bf16 v[0:3], v[200:203], v[232:235], v[0:3]
	v_mfma_f32_16x16x32_bf16 v[52:55], v[196:199], v[212:215], v[52:55]
	v_mfma_f32_16x16x32_bf16 v[44:47], v[204:207], v[212:215], v[44:47]
	v_mfma_f32_16x16x32_bf16 v[36:39], v[196:199], v[220:223], v[36:39]
	v_mfma_f32_16x16x32_bf16 v[28:31], v[204:207], v[220:223], v[28:31]
	v_mfma_f32_16x16x32_bf16 v[20:23], v[196:199], v[228:231], v[20:23]
	v_mfma_f32_16x16x32_bf16 v[12:15], v[204:207], v[228:231], v[12:15]
	v_mfma_f32_16x16x32_bf16 v[4:7], v[196:199], v[236:239], v[4:7]
	v_mfma_f32_16x16x32_bf16 v[0:3], v[204:207], v[236:239], v[0:3]
	s_barrier
	s_add_i32 vcc_lo, vcc_lo, 2
	s_add_u32 s55, s55, 0x100
	s_addc_u32 s57, s57, 0
	s_cmp_gt_u32 vcc_lo, 29
	s_mov_b64 s[68:69], s[70:71]
	s_cbranch_scc0 .LBB0_366
	s_and_b64 vcc, exec, s[52:53]
	s_cbranch_vccz .LBB0_369
	s_barrier

; #define PG8_STAGE(bufoff, gbase, voff) do { _Pragma("unroll") for (int _i = 0; _i < 2; ++_i) \
;         __builtin_amdgcn_global_load_lds((const unsigned*)((const char*)(gbase) + (voff)[_i]), (LAS unsigned*)(lds + (bufoff) + ldsw + _i * 8192), 16, 0, 0); } while (0)
; #define PG8_LDA(dst, b, h) do { _Pragma("unroll") for (int m = 0; m < 4; ++m) _Pragma("unroll") for (int k = 0; k < 2; ++k) dst[m][k] = *(const LAS bf16x8*)(lds + PG8_SA(b, h) + aoff + m * 2048 + k * 1024); } while (0)
; #define PG8_LDB(dst, b, h) do { _Pragma("unroll") for (int n = 0; n < 2; ++n) _Pragma("unroll") for (int k = 0; k < 2; ++k) dst[n][k] = *(const LAS bf16x8*)(lds + PG8_SB(b, h) + boff + n * 2048 + k * 1024); } while (0)
; #define PG8_WAIT_V(n) asm volatile("s_waitcnt vmcnt(" #n ")" ::: "memory")
; #define PG8_BAR __builtin_amdgcn_s_barrier()
; template <bool LT, class Epi>
; __device__ __forceinline__ void gemm_phase(LAS unsigned char* lds, const Gemm g, const StaticOrder& S, const Epi& E) {
;     ...
;         for (int t = 0; t < nt; t += 2) {
;             const bool last = (t == nt - 2);
;             const char* a1 = cA + (size_t)(t + 1) * kstep;
;             const char* a2 = last ? nA : cA + (size_t)(t + 2) * kstep; const char* b2 = last ? nB : cB + (size_t)(t + 2) * kstep;
;             const char* a3 = a2 + kstep; const char* b3 = b2 + kstep;
;             PG8_LDB(B0, 0, 0); PG8_LDB(B1, 0, 1); PG8_SCHED; PG8_LDA(At, 0, 0); PG8_STAGE(PG8_SA(1, 1), a1 + hstepA, voffA);
;             PG8_WAIT_V(8); PG8_WAIT_L(0); PG8_BAR; PG8_MMA(0, 0, At, B0); PG8_MMA(0, 1, At, B1); PG8_BAR; PG8_SCHED;
;             PG8_LDA(At, 0, 1); PG8_STAGE(PG8_SB(0, 0), b2, voffB); PG8_STAGE(PG8_SB(0, 1), b2 + hstepB, voffB); PG8_STAGE(PG8_SA(0, 0), a2, voffA);
;             PG8_WAIT_V(8); PG8_WAIT_L(0); PG8_BAR; PG8_MMA(1, 0, At, B0); PG8_MMA(1, 1, At, B1); PG8_BAR; PG8_SCHED;
;             PG8_LDB(B0, 1, 0); PG8_LDB(B1, 1, 1); PG8_SCHED; PG8_LDA(At, 1, 0); PG8_STAGE(PG8_SA(0, 1), a2 + hstepA, voffA);
;             PG8_WAIT_V(8); PG8_WAIT_L(0); PG8_BAR; PG8_MMA(0, 0, At, B0); PG8_MMA(0, 1, At, B1); PG8_BAR; PG8_SCHED;
;             PG8_LDA(At, 1, 1); PG8_STAGE(PG8_SB(1, 0), b3, voffB); PG8_STAGE(PG8_SB(1, 1), b3 + hstepB, voffB); PG8_STAGE(PG8_SA(1, 0), a3, voffA);
;             PG8_WAIT_V(8); PG8_WAIT_L(0); PG8_BAR; PG8_MMA(1, 0, At, B0); PG8_MMA(1, 1, At, B1); PG8_BAR; PG8_SCHED;
;         }
.LBB0_535:
	ds_read_b128 v[96:99], v166
	ds_read_b128 v[100:103], v166 offset:1024
	ds_read_b128 v[170:173], v166 offset:2048
	ds_read_b128 v[174:177], v166 offset:3072
	ds_read_b128 v[184:187], v167
	ds_read_b128 v[188:191], v167 offset:1024
	ds_read_b128 v[192:195], v167 offset:2048
	ds_read_b128 v[196:199], v167 offset:3072
	s_add_u32 s62, s58, 0x100
	s_addc_u32 s63, s59, 0
	s_cmp_eq_u32 s35, 28
	s_cselect_b32 s69, s10, s63
	s_cselect_b32 s68, s11, s62
	s_cselect_b32 s67, s14, s33
	s_cselect_b32 s66, s15, s19
	v_lshl_add_u64 v[152:153], s[58:59], 0, v[148:149]
	s_add_i32 m0, s57, 0xc000
	ds_read_b128 v[200:203], v168
	ds_read_b128 v[204:207], v168 offset:1024
	ds_read_b128 v[208:211], v168 offset:2048
	ds_read_b128 v[212:215], v168 offset:3072
	ds_read_b128 v[216:219], v168 offset:4096
	ds_read_b128 v[220:223], v168 offset:5120
	ds_read_b128 v[224:227], v168 offset:6144
	ds_read_b128 v[228:231], v168 offset:7168
	global_load_lds_dwordx4 v[152:153], off
	v_lshl_add_u64 v[152:153], s[58:59], 0, v[150:151]
	s_add_i32 m0, s57, 0xe000
	s_nop 0
	global_load_lds_dwordx4 v[152:153], off
	s_waitcnt vmcnt(8)
	s_waitcnt lgkmcnt(0)
	s_barrier
	s_waitcnt lgkmcnt(0)
	v_mfma_f32_16x16x32_bf16 v[132:135], v[96:99], v[200:203], v[132:135]
	v_mfma_f32_16x16x32_bf16 v[128:131], v[170:173], v[200:203], v[128:131]
	v_mfma_f32_16x16x32_bf16 v[124:127], v[96:99], v[208:211], v[124:127]
	v_mfma_f32_16x16x32_bf16 v[120:123], v[170:173], v[208:211], v[120:123]
	v_mfma_f32_16x16x32_bf16 v[116:119], v[96:99], v[216:219], v[116:119]
	v_mfma_f32_16x16x32_bf16 v[112:115], v[170:173], v[216:219], v[112:115]
	v_mfma_f32_16x16x32_bf16 v[108:111], v[96:99], v[224:227], v[108:111]
	v_mfma_f32_16x16x32_bf16 v[104:107], v[170:173], v[224:227], v[104:107]
	v_mfma_f32_16x16x32_bf16 v[132:135], v[100:103], v[204:207], v[132:135]
	v_mfma_f32_16x16x32_bf16 v[128:131], v[174:177], v[204:207], v[128:131]
	v_mfma_f32_16x16x32_bf16 v[124:127], v[100:103], v[212:215], v[124:127]
	v_mfma_f32_16x16x32_bf16 v[120:123], v[174:177], v[212:215], v[120:123]
	v_mfma_f32_16x16x32_bf16 v[116:119], v[100:103], v[220:223], v[116:119]
	v_mfma_f32_16x16x32_bf16 v[112:115], v[174:177], v[220:223], v[112:115]
	v_mfma_f32_16x16x32_bf16 v[108:111], v[100:103], v[228:231], v[108:111]
	v_mfma_f32_16x16x32_bf16 v[104:107], v[174:177], v[228:231], v[104:107]
	v_mfma_f32_16x16x32_bf16 v[60:63], v[184:187], v[200:203], v[60:63]
	v_mfma_f32_16x16x32_bf16 v[56:59], v[192:195], v[200:203], v[56:59]
	v_mfma_f32_16x16x32_bf16 v[52:55], v[184:187], v[208:211], v[52:55]
	v_mfma_f32_16x16x32_bf16 v[48:51], v[192:195], v[208:211], v[48:51]
	v_mfma_f32_16x16x32_bf16 v[44:47], v[184:187], v[216:219], v[44:47]
	v_mfma_f32_16x16x32_bf16 v[40:43], v[192:195], v[216:219], v[40:43]
	v_mfma_f32_16x16x32_bf16 v[36:39], v[184:187], v[224:227], v[36:39]
	v_mfma_f32_16x16x32_bf16 v[32:35], v[192:195], v[224:227], v[32:35]
	v_mfma_f32_16x16x32_bf16 v[60:63], v[188:191], v[204:207], v[60:63]
	v_mfma_f32_16x16x32_bf16 v[56:59], v[196:199], v[204:207], v[56:59]
	v_mfma_f32_16x16x32_bf16 v[52:55], v[188:191], v[212:215], v[52:55]
	v_mfma_f32_16x16x32_bf16 v[48:51], v[196:199], v[212:215], v[48:51]
	v_mfma_f32_16x16x32_bf16 v[44:47], v[188:191], v[220:223], v[44:47]
	v_mfma_f32_16x16x32_bf16 v[40:43], v[196:199], v[220:223], v[40:43]
	v_mfma_f32_16x16x32_bf16 v[36:39], v[188:191], v[228:231], v[36:39]
	v_mfma_f32_16x16x32_bf16 v[32:35], v[196:199], v[228:231], v[32:35]
	s_barrier
	s_add_i32 s12, s87, s70
	v_lshl_add_u64 v[152:153], s[66:67], 0, v[136:137]
	s_mov_b32 m0, s12
	ds_read_b128 v[200:203], v168 offset:16384
	ds_read_b128 v[204:207], v168 offset:17408
	ds_read_b128 v[208:211], v168 offset:18432
	ds_read_b128 v[212:215], v168 offset:19456
	ds_read_b128 v[216:219], v168 offset:20480
	ds_read_b128 v[220:223], v168 offset:21504
	ds_read_b128 v[224:227], v168 offset:22528
	ds_read_b128 v[228:231], v168 offset:23552
	global_load_lds_dwordx4 v[152:153], off
	s_add_i32 m0, s12, 0x2000
	s_add_u32 s46, s66, 0x80000
	v_lshl_add_u64 v[178:179], s[66:67], 0, v[138:139]
	s_addc_u32 s47, s67, 0
	s_add_i32 s12, s88, s70
	global_load_lds_dwordx4 v[178:179], off
	v_lshl_add_u64 v[232:233], s[46:47], 0, v[136:137]
	s_mov_b32 m0, s12
	v_lshl_add_u64 v[234:235], s[68:69], 0, v[142:143]
	global_load_lds_dwordx4 v[232:233], off
	v_lshl_add_u64 v[232:233], s[46:47], 0, v[138:139]
	s_add_i32 m0, s12, 0x2000
	s_nop 0
	global_load_lds_dwordx4 v[232:233], off
	v_lshl_add_u64 v[232:233], s[68:69], 0, v[140:141]
	s_mov_b32 m0, s57
	s_nop 0
	global_load_lds_dwordx4 v[232:233], off
	s_mov_b32 m0, s71
	s_nop 0
	global_load_lds_dwordx4 v[234:235], off
	s_waitcnt vmcnt(8)
	s_waitcnt lgkmcnt(0)
	s_barrier
; #define PG8_STAGE(bufoff, gbase, voff) do { _Pragma("unroll") for (int _i = 0; _i < 2; ++_i) \
;         __builtin_amdgcn_global_load_lds((const unsigned*)((const char*)(gbase) + (voff)[_i]), (LAS unsigned*)(lds + (bufoff) + ldsw + _i * 8192), 16, 0, 0); } while (0)
; #define PG8_LDA(dst, b, h) do { _Pragma("unroll") for (int m = 0; m < 4; ++m) _Pragma("unroll") for (int k = 0; k < 2; ++k) dst[m][k] = *(const LAS bf16x8*)(lds + PG8_SA(b, h) + aoff + m * 2048 + k * 1024); } while (0)
; #define PG8_LDB(dst, b, h) do { _Pragma("unroll") for (int n = 0; n < 2; ++n) _Pragma("unroll") for (int k = 0; k < 2; ++k) dst[n][k] = *(const LAS bf16x8*)(lds + PG8_SB(b, h) + boff + n * 2048 + k * 1024); } while (0)
; #define PG8_MMA(ai, bj, At, Bt) do { __builtin_amdgcn_s_setprio(1); _Pragma("unroll") for (int m = 0; m < 4; ++m) _Pragma("unroll") for (int n = 0; n < 2; ++n) _Pragma("unroll") for (int k = 0; k < 2; ++k) \
;         acc[ai][bj][m][n] = __builtin_amdgcn_mfma_f32_16x16x32_bf16(Bt[n][k], At[m][k], acc[ai][bj][m][n], 0, 0, 0); __builtin_amdgcn_s_setprio(0); } while (0)
; #define PG8_WAIT_V(n) asm volatile("s_waitcnt vmcnt(" #n ")" ::: "memory")
; #define PG8_WAIT_L(n) asm volatile("s_waitcnt lgkmcnt(" #n ")" ::: "memory")
; #define PG8_BAR __builtin_amdgcn_s_barrier()
; #define PG8_SCHED __builtin_amdgcn_sched_barrier(0)
; template <bool LT, class Epi>
; __device__ __forceinline__ void gemm_phase(LAS unsigned char* lds, const Gemm g, const StaticOrder& S, const Epi& E) {
;     ...
;             PG8_WAIT_V(8); PG8_WAIT_L(0); PG8_BAR; PG8_MMA(1, 0, At, B0); PG8_MMA(1, 1, At, B1); PG8_BAR; PG8_SCHED;
;             PG8_LDB(B0, 1, 0); PG8_LDB(B1, 1, 1); PG8_SCHED; PG8_LDA(At, 1, 0); PG8_STAGE(PG8_SA(0, 1), a2 + hstepA, voffA);
;             PG8_WAIT_V(8); PG8_WAIT_L(0); PG8_BAR; PG8_MMA(0, 0, At, B0); PG8_MMA(0, 1, At, B1); PG8_BAR; PG8_SCHED;
	s_waitcnt lgkmcnt(0)
	v_mfma_f32_16x16x32_bf16 v[92:95], v[96:99], v[200:203], v[92:95]
	v_mfma_f32_16x16x32_bf16 v[88:91], v[170:173], v[200:203], v[88:91]
	v_mfma_f32_16x16x32_bf16 v[84:87], v[96:99], v[208:211], v[84:87]
	v_mfma_f32_16x16x32_bf16 v[80:83], v[170:173], v[208:211], v[80:83]
	v_mfma_f32_16x16x32_bf16 v[76:79], v[96:99], v[216:219], v[76:79]
	v_mfma_f32_16x16x32_bf16 v[72:75], v[170:173], v[216:219], v[72:75]
	v_mfma_f32_16x16x32_bf16 v[68:71], v[96:99], v[224:227], v[68:71]
	v_mfma_f32_16x16x32_bf16 v[64:67], v[170:173], v[224:227], v[64:67]
	v_mfma_f32_16x16x32_bf16 v[92:95], v[100:103], v[204:207], v[92:95]
	v_mfma_f32_16x16x32_bf16 v[88:91], v[174:177], v[204:207], v[88:91]
	v_mfma_f32_16x16x32_bf16 v[84:87], v[100:103], v[212:215], v[84:87]
	v_mfma_f32_16x16x32_bf16 v[80:83], v[174:177], v[212:215], v[80:83]
	v_mfma_f32_16x16x32_bf16 v[76:79], v[100:103], v[220:223], v[76:79]
	v_mfma_f32_16x16x32_bf16 v[72:75], v[174:177], v[220:223], v[72:75]
	v_mfma_f32_16x16x32_bf16 v[68:71], v[100:103], v[228:231], v[68:71]
	v_mfma_f32_16x16x32_bf16 v[64:67], v[174:177], v[228:231], v[64:67]
	v_mfma_f32_16x16x32_bf16 v[28:31], v[184:187], v[200:203], v[28:31]
	v_mfma_f32_16x16x32_bf16 v[24:27], v[192:195], v[200:203], v[24:27]
	v_mfma_f32_16x16x32_bf16 v[20:23], v[184:187], v[208:211], v[20:23]
	v_mfma_f32_16x16x32_bf16 v[16:19], v[192:195], v[208:211], v[16:19]
	v_mfma_f32_16x16x32_bf16 v[12:15], v[184:187], v[216:219], v[12:15]
	v_mfma_f32_16x16x32_bf16 v[8:11], v[192:195], v[216:219], v[8:11]
	v_mfma_f32_16x16x32_bf16 v[4:7], v[184:187], v[224:227], v[4:7]
	v_mfma_f32_16x16x32_bf16 v[0:3], v[192:195], v[224:227], v[0:3]
	v_mfma_f32_16x16x32_bf16 v[28:31], v[188:191], v[204:207], v[28:31]
	v_mfma_f32_16x16x32_bf16 v[24:27], v[196:199], v[204:207], v[24:27]
	v_mfma_f32_16x16x32_bf16 v[20:23], v[188:191], v[212:215], v[20:23]
	v_mfma_f32_16x16x32_bf16 v[16:19], v[196:199], v[212:215], v[16:19]
	v_mfma_f32_16x16x32_bf16 v[12:15], v[188:191], v[220:223], v[12:15]
	v_mfma_f32_16x16x32_bf16 v[8:11], v[196:199], v[220:223], v[8:11]
	v_mfma_f32_16x16x32_bf16 v[4:7], v[188:191], v[228:231], v[4:7]
	v_mfma_f32_16x16x32_bf16 v[0:3], v[196:199], v[228:231], v[0:3]
	s_barrier
	s_add_i32 s12, 0, 0x18000
	v_add_u32_e32 v169, s12, v165
	s_add_i32 s13, 0, 0x1c000
	ds_read_b128 v[96:99], v169
	ds_read_b128 v[100:103], v169 offset:1024
	ds_read_b128 v[170:173], v169 offset:2048
	ds_read_b128 v[174:177], v169 offset:3072
	v_add_u32_e32 v169, s13, v165
	ds_read_b128 v[184:187], v169
	ds_read_b128 v[188:191], v169 offset:1024
	ds_read_b128 v[192:195], v169 offset:2048
	ds_read_b128 v[196:199], v169 offset:3072
	s_add_u32 s46, s68, 0x40000
	s_addc_u32 s47, s69, 0
	s_mov_b32 m0, s72
	v_lshl_add_u64 v[236:237], s[46:47], 0, v[140:141]
	ds_read_b128 v[200:203], v168 offset:32768
	ds_read_b128 v[204:207], v168 offset:33792
	ds_read_b128 v[208:211], v168 offset:34816
	ds_read_b128 v[212:215], v168 offset:35840
	ds_read_b128 v[216:219], v168 offset:36864
	ds_read_b128 v[220:223], v168 offset:37888
	ds_read_b128 v[224:227], v168 offset:38912
	ds_read_b128 v[228:231], v168 offset:39936
	global_load_lds_dwordx4 v[236:237], off
	v_lshl_add_u64 v[236:237], s[46:47], 0, v[142:143]
	s_mov_b32 m0, s73
	s_nop 0
	global_load_lds_dwordx4 v[236:237], off
	s_waitcnt vmcnt(8)
	s_waitcnt lgkmcnt(0)
	s_barrier
	s_waitcnt lgkmcnt(0)
	v_mfma_f32_16x16x32_bf16 v[132:135], v[96:99], v[200:203], v[132:135]
	v_mfma_f32_16x16x32_bf16 v[128:131], v[170:173], v[200:203], v[128:131]
	v_mfma_f32_16x16x32_bf16 v[124:127], v[96:99], v[208:211], v[124:127]
	v_mfma_f32_16x16x32_bf16 v[120:123], v[170:173], v[208:211], v[120:123]
	v_mfma_f32_16x16x32_bf16 v[116:119], v[96:99], v[216:219], v[116:119]
	v_mfma_f32_16x16x32_bf16 v[112:115], v[170:173], v[216:219], v[112:115]
	v_mfma_f32_16x16x32_bf16 v[108:111], v[96:99], v[224:227], v[108:111]
	v_mfma_f32_16x16x32_bf16 v[104:107], v[170:173], v[224:227], v[104:107]
	v_mfma_f32_16x16x32_bf16 v[132:135], v[100:103], v[204:207], v[132:135]
	v_mfma_f32_16x16x32_bf16 v[128:131], v[174:177], v[204:207], v[128:131]
	v_mfma_f32_16x16x32_bf16 v[124:127], v[100:103], v[212:215], v[124:127]
	v_mfma_f32_16x16x32_bf16 v[120:123], v[174:177], v[212:215], v[120:123]
	v_mfma_f32_16x16x32_bf16 v[116:119], v[100:103], v[220:223], v[116:119]
	v_mfma_f32_16x16x32_bf16 v[112:115], v[174:177], v[220:223], v[112:115]
	v_mfma_f32_16x16x32_bf16 v[108:111], v[100:103], v[228:231], v[108:111]
	v_mfma_f32_16x16x32_bf16 v[104:107], v[174:177], v[228:231], v[104:107]
	v_mfma_f32_16x16x32_bf16 v[60:63], v[184:187], v[200:203], v[60:63]
	v_mfma_f32_16x16x32_bf16 v[56:59], v[192:195], v[200:203], v[56:59]
	v_mfma_f32_16x16x32_bf16 v[52:55], v[184:187], v[208:211], v[52:55]
	v_mfma_f32_16x16x32_bf16 v[48:51], v[192:195], v[208:211], v[48:51]
	v_mfma_f32_16x16x32_bf16 v[44:47], v[184:187], v[216:219], v[44:47]
	v_mfma_f32_16x16x32_bf16 v[40:43], v[192:195], v[216:219], v[40:43]
	v_mfma_f32_16x16x32_bf16 v[36:39], v[184:187], v[224:227], v[36:39]
	v_mfma_f32_16x16x32_bf16 v[32:35], v[192:195], v[224:227], v[32:35]
	v_mfma_f32_16x16x32_bf16 v[60:63], v[188:191], v[204:207], v[60:63]
	v_mfma_f32_16x16x32_bf16 v[56:59], v[196:199], v[204:207], v[56:59]
	v_mfma_f32_16x16x32_bf16 v[52:55], v[188:191], v[212:215], v[52:55]
	v_mfma_f32_16x16x32_bf16 v[48:51], v[196:199], v[212:215], v[48:51]
	v_mfma_f32_16x16x32_bf16 v[44:47], v[188:191], v[220:223], v[44:47]
	v_mfma_f32_16x16x32_bf16 v[40:43], v[196:199], v[220:223], v[40:43]
	v_mfma_f32_16x16x32_bf16 v[36:39], v[188:191], v[228:231], v[36:39]
	v_mfma_f32_16x16x32_bf16 v[32:35], v[196:199], v[228:231], v[32:35]
	s_barrier
; #define PG8_STAGE(bufoff, gbase, voff) do { _Pragma("unroll") for (int _i = 0; _i < 2; ++_i) \
;         __builtin_amdgcn_global_load_lds((const unsigned*)((const char*)(gbase) + (voff)[_i]), (LAS unsigned*)(lds + (bufoff) + ldsw + _i * 8192), 16, 0, 0); } while (0)
; #define PG8_LDA(dst, b, h) do { _Pragma("unroll") for (int m = 0; m < 4; ++m) _Pragma("unroll") for (int k = 0; k < 2; ++k) dst[m][k] = *(const LAS bf16x8*)(lds + PG8_SA(b, h) + aoff + m * 2048 + k * 1024); } while (0)
; #define PG8_MMA(ai, bj, At, Bt) do { __builtin_amdgcn_s_setprio(1); _Pragma("unroll") for (int m = 0; m < 4; ++m) _Pragma("unroll") for (int n = 0; n < 2; ++n) _Pragma("unroll") for (int k = 0; k < 2; ++k) \
;         acc[ai][bj][m][n] = __builtin_amdgcn_mfma_f32_16x16x32_bf16(Bt[n][k], At[m][k], acc[ai][bj][m][n], 0, 0, 0); __builtin_amdgcn_s_setprio(0); } while (0)
; #define PG8_WAIT_V(n) asm volatile("s_waitcnt vmcnt(" #n ")" ::: "memory")
; #define PG8_WAIT_L(n) asm volatile("s_waitcnt lgkmcnt(" #n ")" ::: "memory")
; #define PG8_BAR __builtin_amdgcn_s_barrier()
; #define PG8_SCHED __builtin_amdgcn_sched_barrier(0)
; template <bool LT, class Epi>
; __device__ __forceinline__ void gemm_phase(LAS unsigned char* lds, const Gemm g, const StaticOrder& S, const Epi& E) {
;     ...
;         for (int t = 0; t < nt; t += 2) {
;     ...
;             PG8_LDA(At, 1, 1); PG8_STAGE(PG8_SB(1, 0), b3, voffB); PG8_STAGE(PG8_SB(1, 1), b3 + hstepB, voffB); PG8_STAGE(PG8_SA(1, 0), a3, voffA);
;             PG8_WAIT_V(8); PG8_WAIT_L(0); PG8_BAR; PG8_MMA(1, 0, At, B0); PG8_MMA(1, 1, At, B1); PG8_BAR; PG8_SCHED;
	s_add_i32 s12, s12, s70
	v_lshl_add_u64 v[152:153], v[152:153], 0, s[4:5]
	s_mov_b32 m0, s12
	ds_read_b128 v[200:203], v168 offset:49152
	ds_read_b128 v[204:207], v168 offset:50176
	ds_read_b128 v[208:211], v168 offset:51200
	ds_read_b128 v[212:215], v168 offset:52224
	ds_read_b128 v[216:219], v168 offset:53248
	ds_read_b128 v[220:223], v168 offset:54272
	ds_read_b128 v[224:227], v168 offset:55296
	ds_read_b128 v[228:231], v168 offset:56320
	global_load_lds_dwordx4 v[152:153], off
	s_add_i32 m0, s12, 0x2000
	s_add_u32 s46, s66, 0x80080
	v_lshl_add_u64 v[152:153], v[178:179], 0, s[4:5]
	s_addc_u32 s47, s67, 0
	s_add_i32 s12, s13, s70
	global_load_lds_dwordx4 v[152:153], off
	v_lshl_add_u64 v[152:153], s[46:47], 0, v[136:137]
	s_mov_b32 m0, s12
	s_nop 0
	global_load_lds_dwordx4 v[152:153], off
	v_lshl_add_u64 v[152:153], s[46:47], 0, v[138:139]
	s_add_i32 m0, s12, 0x2000
	s_nop 0
	global_load_lds_dwordx4 v[152:153], off
	v_lshl_add_u64 v[152:153], v[232:233], 0, s[4:5]
	s_mov_b32 m0, s75
	s_nop 0
	global_load_lds_dwordx4 v[152:153], off
	v_lshl_add_u64 v[152:153], v[234:235], 0, s[4:5]
	s_mov_b32 m0, s76
	s_nop 0
	global_load_lds_dwordx4 v[152:153], off
	s_waitcnt vmcnt(8)
	s_waitcnt lgkmcnt(0)
	s_barrier
	s_waitcnt lgkmcnt(0)
	v_mfma_f32_16x16x32_bf16 v[92:95], v[96:99], v[200:203], v[92:95]
	v_mfma_f32_16x16x32_bf16 v[88:91], v[170:173], v[200:203], v[88:91]
	v_mfma_f32_16x16x32_bf16 v[84:87], v[96:99], v[208:211], v[84:87]
	v_mfma_f32_16x16x32_bf16 v[80:83], v[170:173], v[208:211], v[80:83]
	v_mfma_f32_16x16x32_bf16 v[76:79], v[96:99], v[216:219], v[76:79]
	v_mfma_f32_16x16x32_bf16 v[72:75], v[170:173], v[216:219], v[72:75]
	v_mfma_f32_16x16x32_bf16 v[68:71], v[96:99], v[224:227], v[68:71]
	v_mfma_f32_16x16x32_bf16 v[64:67], v[170:173], v[224:227], v[64:67]
	v_mfma_f32_16x16x32_bf16 v[92:95], v[100:103], v[204:207], v[92:95]
	v_mfma_f32_16x16x32_bf16 v[88:91], v[174:177], v[204:207], v[88:91]
	v_mfma_f32_16x16x32_bf16 v[84:87], v[100:103], v[212:215], v[84:87]
	v_mfma_f32_16x16x32_bf16 v[80:83], v[174:177], v[212:215], v[80:83]
	v_mfma_f32_16x16x32_bf16 v[76:79], v[100:103], v[220:223], v[76:79]
	v_mfma_f32_16x16x32_bf16 v[72:75], v[174:177], v[220:223], v[72:75]
	v_mfma_f32_16x16x32_bf16 v[68:71], v[100:103], v[228:231], v[68:71]
	v_mfma_f32_16x16x32_bf16 v[64:67], v[174:177], v[228:231], v[64:67]
	v_mfma_f32_16x16x32_bf16 v[28:31], v[184:187], v[200:203], v[28:31]
	v_mfma_f32_16x16x32_bf16 v[24:27], v[192:195], v[200:203], v[24:27]
	v_mfma_f32_16x16x32_bf16 v[20:23], v[184:187], v[208:211], v[20:23]
	v_mfma_f32_16x16x32_bf16 v[16:19], v[192:195], v[208:211], v[16:19]
	v_mfma_f32_16x16x32_bf16 v[12:15], v[184:187], v[216:219], v[12:15]
	v_mfma_f32_16x16x32_bf16 v[8:11], v[192:195], v[216:219], v[8:11]
	v_mfma_f32_16x16x32_bf16 v[4:7], v[184:187], v[224:227], v[4:7]
	v_mfma_f32_16x16x32_bf16 v[0:3], v[192:195], v[224:227], v[0:3]
	v_mfma_f32_16x16x32_bf16 v[28:31], v[188:191], v[204:207], v[28:31]
	v_mfma_f32_16x16x32_bf16 v[24:27], v[196:199], v[204:207], v[24:27]
	v_mfma_f32_16x16x32_bf16 v[20:23], v[188:191], v[212:215], v[20:23]
	v_mfma_f32_16x16x32_bf16 v[16:19], v[196:199], v[212:215], v[16:19]
	v_mfma_f32_16x16x32_bf16 v[12:15], v[188:191], v[220:223], v[12:15]
	v_mfma_f32_16x16x32_bf16 v[8:11], v[196:199], v[220:223], v[8:11]
	v_mfma_f32_16x16x32_bf16 v[4:7], v[188:191], v[228:231], v[4:7]
	v_mfma_f32_16x16x32_bf16 v[0:3], v[196:199], v[228:231], v[0:3]
	s_barrier
	s_add_i32 s35, s35, 2
	s_add_u32 s19, s19, 0x100
	s_addc_u32 s33, s33, 0
	s_cmp_gt_u32 s35, 29
	s_mov_b64 s[58:59], s[62:63]
	s_cbranch_scc0 .LBB0_535
	s_and_b64 vcc, exec, s[8:9]
	s_cbranch_vccz .LBB0_538
	s_barrier

; #define PG8_STAGE(bufoff, gbase, voff) do { _Pragma("unroll") for (int _i = 0; _i < 2; ++_i) \
;         __builtin_amdgcn_global_load_lds((const unsigned*)((const char*)(gbase) + (voff)[_i]), (LAS unsigned*)(lds + (bufoff) + ldsw + _i * 8192), 16, 0, 0); } while (0)
; #define PG8_LDA(dst, b, h) do { _Pragma("unroll") for (int m = 0; m < 4; ++m) _Pragma("unroll") for (int k = 0; k < 2; ++k) dst[m][k] = *(const LAS bf16x8*)(lds + PG8_SA(b, h) + aoff + m * 2048 + k * 1024); } while (0)
; #define PG8_LDB(dst, b, h) do { _Pragma("unroll") for (int n = 0; n < 2; ++n) _Pragma("unroll") for (int k = 0; k < 2; ++k) dst[n][k] = *(const LAS bf16x8*)(lds + PG8_SB(b, h) + boff + n * 2048 + k * 1024); } while (0)
; #define PG8_MMA(ai, bj, At, Bt) do { __builtin_amdgcn_s_setprio(1); _Pragma("unroll") for (int m = 0; m < 4; ++m) _Pragma("unroll") for (int n = 0; n < 2; ++n) _Pragma("unroll") for (int k = 0; k < 2; ++k) \
;         acc[ai][bj][m][n] = __builtin_amdgcn_mfma_f32_16x16x32_bf16(Bt[n][k], At[m][k], acc[ai][bj][m][n], 0, 0, 0); __builtin_amdgcn_s_setprio(0); } while (0)
; #define PG8_WAIT_V(n) asm volatile("s_waitcnt vmcnt(" #n ")" ::: "memory")
; #define PG8_WAIT_L(n) asm volatile("s_waitcnt lgkmcnt(" #n ")" ::: "memory")
; #define PG8_BAR __builtin_amdgcn_s_barrier()
; #define PG8_SCHED __builtin_amdgcn_sched_barrier(0)
; template <bool LT, class Epi>
; __device__ __forceinline__ void gemm_phase(LAS unsigned char* lds, const Gemm g, const StaticOrder& S, const Epi& E) {
;     ...
;             const bool last = (t == nt - 2);
;             const char* a1 = cA + (size_t)(t + 1) * kstep;
;             const char* a2 = last ? nA : cA + (size_t)(t + 2) * kstep; const char* b2 = last ? nB : cB + (size_t)(t + 2) * kstep;
;             const char* a3 = a2 + kstep; const char* b3 = b2 + kstep;
;             PG8_LDB(B0, 0, 0); PG8_LDB(B1, 0, 1); PG8_SCHED; PG8_LDA(At, 0, 0); PG8_STAGE(PG8_SA(1, 1), a1 + hstepA, voffA);
;             PG8_WAIT_V(8); PG8_WAIT_L(0); PG8_BAR; PG8_MMA(0, 0, At, B0); PG8_MMA(0, 1, At, B1); PG8_BAR; PG8_SCHED;
;             PG8_LDA(At, 0, 1); PG8_STAGE(PG8_SB(0, 0), b2, voffB); PG8_STAGE(PG8_SB(0, 1), b2 + hstepB, voffB); PG8_STAGE(PG8_SA(0, 0), a2, voffA);
.LBB0_559:
	ds_read_b128 v[96:99], v156
	ds_read_b128 v[100:103], v156 offset:1024
	ds_read_b128 v[164:167], v156 offset:2048
	ds_read_b128 v[168:171], v156 offset:3072
	ds_read_b128 v[172:175], v157
	ds_read_b128 v[176:179], v157 offset:1024
	ds_read_b128 v[184:187], v157 offset:2048
	ds_read_b128 v[188:191], v157 offset:3072
	s_add_u32 s58, s56, 0x100
	s_addc_u32 s59, s57, 0
	s_cmp_eq_u32 s33, 28
	s_cselect_b32 s67, s10, s59
	s_cselect_b32 s66, s11, s58
	s_cselect_b32 s63, s14, s25
	s_cselect_b32 s62, s15, s19
	v_lshl_add_u64 v[152:153], s[56:57], 0, v[148:149]
	s_add_i32 m0, s55, 0xc000
	ds_read_b128 v[192:195], v158
	ds_read_b128 v[196:199], v158 offset:1024
	ds_read_b128 v[200:203], v158 offset:2048
	ds_read_b128 v[204:207], v158 offset:3072
	ds_read_b128 v[208:211], v158 offset:4096
	ds_read_b128 v[212:215], v158 offset:5120
	ds_read_b128 v[216:219], v158 offset:6144
	ds_read_b128 v[220:223], v158 offset:7168
	global_load_lds_dwordx4 v[152:153], off
	v_lshl_add_u64 v[152:153], s[56:57], 0, v[150:151]
	s_add_i32 m0, s55, 0xe000
	s_nop 0
	global_load_lds_dwordx4 v[152:153], off
	s_waitcnt vmcnt(8)
	s_waitcnt lgkmcnt(0)
	s_barrier
	s_waitcnt lgkmcnt(0)
	v_mfma_f32_16x16x32_bf16 v[132:135], v[96:99], v[192:195], v[132:135]
	v_mfma_f32_16x16x32_bf16 v[128:131], v[164:167], v[192:195], v[128:131]
	v_mfma_f32_16x16x32_bf16 v[124:127], v[96:99], v[200:203], v[124:127]
	v_mfma_f32_16x16x32_bf16 v[120:123], v[164:167], v[200:203], v[120:123]
	v_mfma_f32_16x16x32_bf16 v[116:119], v[96:99], v[208:211], v[116:119]
	v_mfma_f32_16x16x32_bf16 v[112:115], v[164:167], v[208:211], v[112:115]
	v_mfma_f32_16x16x32_bf16 v[108:111], v[96:99], v[216:219], v[108:111]
	v_mfma_f32_16x16x32_bf16 v[104:107], v[164:167], v[216:219], v[104:107]
	v_mfma_f32_16x16x32_bf16 v[132:135], v[100:103], v[196:199], v[132:135]
	v_mfma_f32_16x16x32_bf16 v[128:131], v[168:171], v[196:199], v[128:131]
	v_mfma_f32_16x16x32_bf16 v[124:127], v[100:103], v[204:207], v[124:127]
	v_mfma_f32_16x16x32_bf16 v[120:123], v[168:171], v[204:207], v[120:123]
	v_mfma_f32_16x16x32_bf16 v[116:119], v[100:103], v[212:215], v[116:119]
	v_mfma_f32_16x16x32_bf16 v[112:115], v[168:171], v[212:215], v[112:115]
	v_mfma_f32_16x16x32_bf16 v[108:111], v[100:103], v[220:223], v[108:111]
	v_mfma_f32_16x16x32_bf16 v[104:107], v[168:171], v[220:223], v[104:107]
	v_mfma_f32_16x16x32_bf16 v[60:63], v[172:175], v[192:195], v[60:63]
	v_mfma_f32_16x16x32_bf16 v[56:59], v[184:187], v[192:195], v[56:59]
	v_mfma_f32_16x16x32_bf16 v[52:55], v[172:175], v[200:203], v[52:55]
	v_mfma_f32_16x16x32_bf16 v[48:51], v[184:187], v[200:203], v[48:51]
	v_mfma_f32_16x16x32_bf16 v[44:47], v[172:175], v[208:211], v[44:47]
	v_mfma_f32_16x16x32_bf16 v[40:43], v[184:187], v[208:211], v[40:43]
	v_mfma_f32_16x16x32_bf16 v[36:39], v[172:175], v[216:219], v[36:39]
	v_mfma_f32_16x16x32_bf16 v[32:35], v[184:187], v[216:219], v[32:35]
	v_mfma_f32_16x16x32_bf16 v[60:63], v[176:179], v[196:199], v[60:63]
	v_mfma_f32_16x16x32_bf16 v[56:59], v[188:191], v[196:199], v[56:59]
	v_mfma_f32_16x16x32_bf16 v[52:55], v[176:179], v[204:207], v[52:55]
	v_mfma_f32_16x16x32_bf16 v[48:51], v[188:191], v[204:207], v[48:51]
	v_mfma_f32_16x16x32_bf16 v[44:47], v[176:179], v[212:215], v[44:47]
	v_mfma_f32_16x16x32_bf16 v[40:43], v[188:191], v[212:215], v[40:43]
	v_mfma_f32_16x16x32_bf16 v[36:39], v[176:179], v[220:223], v[36:39]
	v_mfma_f32_16x16x32_bf16 v[32:35], v[188:191], v[220:223], v[32:35]
	s_barrier
	s_add_i32 s12, s86, s69
	v_lshl_add_u64 v[152:153], s[62:63], 0, v[136:137]
	s_mov_b32 m0, s12
	ds_read_b128 v[192:195], v158 offset:16384
	ds_read_b128 v[196:199], v158 offset:17408
	ds_read_b128 v[200:203], v158 offset:18432
	ds_read_b128 v[204:207], v158 offset:19456
	ds_read_b128 v[208:211], v158 offset:20480
	ds_read_b128 v[212:215], v158 offset:21504
	ds_read_b128 v[216:219], v158 offset:22528
	ds_read_b128 v[220:223], v158 offset:23552
	global_load_lds_dwordx4 v[152:153], off
	s_add_i32 m0, s12, 0x2000
	s_add_u32 s46, s62, 0x80000
	v_lshl_add_u64 v[160:161], s[62:63], 0, v[138:139]
	s_addc_u32 s47, s63, 0
	s_add_i32 s12, s87, s69
	global_load_lds_dwordx4 v[160:161], off
	v_lshl_add_u64 v[224:225], s[46:47], 0, v[136:137]
	s_mov_b32 m0, s12
	v_lshl_add_u64 v[226:227], s[66:67], 0, v[142:143]
	global_load_lds_dwordx4 v[224:225], off
	v_lshl_add_u64 v[224:225], s[46:47], 0, v[138:139]
	s_add_i32 m0, s12, 0x2000
	s_nop 0
	global_load_lds_dwordx4 v[224:225], off
	v_lshl_add_u64 v[224:225], s[66:67], 0, v[140:141]
	s_mov_b32 m0, s55
	s_nop 0
	global_load_lds_dwordx4 v[224:225], off
	s_mov_b32 m0, s70
	s_nop 0
	global_load_lds_dwordx4 v[226:227], off
	s_waitcnt vmcnt(8)
	s_waitcnt lgkmcnt(0)
	s_barrier
; #define PG8_STAGE(bufoff, gbase, voff) do { _Pragma("unroll") for (int _i = 0; _i < 2; ++_i) \
;         __builtin_amdgcn_global_load_lds((const unsigned*)((const char*)(gbase) + (voff)[_i]), (LAS unsigned*)(lds + (bufoff) + ldsw + _i * 8192), 16, 0, 0); } while (0)
; #define PG8_LDA(dst, b, h) do { _Pragma("unroll") for (int m = 0; m < 4; ++m) _Pragma("unroll") for (int k = 0; k < 2; ++k) dst[m][k] = *(const LAS bf16x8*)(lds + PG8_SA(b, h) + aoff + m * 2048 + k * 1024); } while (0)
; #define PG8_LDB(dst, b, h) do { _Pragma("unroll") for (int n = 0; n < 2; ++n) _Pragma("unroll") for (int k = 0; k < 2; ++k) dst[n][k] = *(const LAS bf16x8*)(lds + PG8_SB(b, h) + boff + n * 2048 + k * 1024); } while (0)
; #define PG8_MMA(ai, bj, At, Bt) do { __builtin_amdgcn_s_setprio(1); _Pragma("unroll") for (int m = 0; m < 4; ++m) _Pragma("unroll") for (int n = 0; n < 2; ++n) _Pragma("unroll") for (int k = 0; k < 2; ++k) \
;         acc[ai][bj][m][n] = __builtin_amdgcn_mfma_f32_16x16x32_bf16(Bt[n][k], At[m][k], acc[ai][bj][m][n], 0, 0, 0); __builtin_amdgcn_s_setprio(0); } while (0)
; #define PG8_WAIT_V(n) asm volatile("s_waitcnt vmcnt(" #n ")" ::: "memory")
; #define PG8_WAIT_L(n) asm volatile("s_waitcnt lgkmcnt(" #n ")" ::: "memory")
; #define PG8_BAR __builtin_amdgcn_s_barrier()
; #define PG8_SCHED __builtin_amdgcn_sched_barrier(0)
; template <bool LT, class Epi>
; __device__ __forceinline__ void gemm_phase(LAS unsigned char* lds, const Gemm g, const StaticOrder& S, const Epi& E) {
;     ...
;             PG8_WAIT_V(8); PG8_WAIT_L(0); PG8_BAR; PG8_MMA(1, 0, At, B0); PG8_MMA(1, 1, At, B1); PG8_BAR; PG8_SCHED;
;             PG8_LDB(B0, 1, 0); PG8_LDB(B1, 1, 1); PG8_SCHED; PG8_LDA(At, 1, 0); PG8_STAGE(PG8_SA(0, 1), a2 + hstepA, voffA);
;             PG8_WAIT_V(8); PG8_WAIT_L(0); PG8_BAR; PG8_MMA(0, 0, At, B0); PG8_MMA(0, 1, At, B1); PG8_BAR; PG8_SCHED;
	s_waitcnt lgkmcnt(0)
	v_mfma_f32_16x16x32_bf16 v[92:95], v[96:99], v[192:195], v[92:95]
	v_mfma_f32_16x16x32_bf16 v[88:91], v[164:167], v[192:195], v[88:91]
	v_mfma_f32_16x16x32_bf16 v[84:87], v[96:99], v[200:203], v[84:87]
	v_mfma_f32_16x16x32_bf16 v[80:83], v[164:167], v[200:203], v[80:83]
	v_mfma_f32_16x16x32_bf16 v[76:79], v[96:99], v[208:211], v[76:79]
	v_mfma_f32_16x16x32_bf16 v[72:75], v[164:167], v[208:211], v[72:75]
	v_mfma_f32_16x16x32_bf16 v[68:71], v[96:99], v[216:219], v[68:71]
	v_mfma_f32_16x16x32_bf16 v[64:67], v[164:167], v[216:219], v[64:67]
	v_mfma_f32_16x16x32_bf16 v[92:95], v[100:103], v[196:199], v[92:95]
	v_mfma_f32_16x16x32_bf16 v[88:91], v[168:171], v[196:199], v[88:91]
	v_mfma_f32_16x16x32_bf16 v[84:87], v[100:103], v[204:207], v[84:87]
	v_mfma_f32_16x16x32_bf16 v[80:83], v[168:171], v[204:207], v[80:83]
	v_mfma_f32_16x16x32_bf16 v[76:79], v[100:103], v[212:215], v[76:79]
	v_mfma_f32_16x16x32_bf16 v[72:75], v[168:171], v[212:215], v[72:75]
	v_mfma_f32_16x16x32_bf16 v[68:71], v[100:103], v[220:223], v[68:71]
	v_mfma_f32_16x16x32_bf16 v[64:67], v[168:171], v[220:223], v[64:67]
	v_mfma_f32_16x16x32_bf16 v[28:31], v[172:175], v[192:195], v[28:31]
	v_mfma_f32_16x16x32_bf16 v[24:27], v[184:187], v[192:195], v[24:27]
	v_mfma_f32_16x16x32_bf16 v[20:23], v[172:175], v[200:203], v[20:23]
	v_mfma_f32_16x16x32_bf16 v[16:19], v[184:187], v[200:203], v[16:19]
	v_mfma_f32_16x16x32_bf16 v[12:15], v[172:175], v[208:211], v[12:15]
	v_mfma_f32_16x16x32_bf16 v[8:11], v[184:187], v[208:211], v[8:11]
	v_mfma_f32_16x16x32_bf16 v[4:7], v[172:175], v[216:219], v[4:7]
	v_mfma_f32_16x16x32_bf16 v[0:3], v[184:187], v[216:219], v[0:3]
	v_mfma_f32_16x16x32_bf16 v[28:31], v[176:179], v[196:199], v[28:31]
	v_mfma_f32_16x16x32_bf16 v[24:27], v[188:191], v[196:199], v[24:27]
	v_mfma_f32_16x16x32_bf16 v[20:23], v[176:179], v[204:207], v[20:23]
	v_mfma_f32_16x16x32_bf16 v[16:19], v[188:191], v[204:207], v[16:19]
	v_mfma_f32_16x16x32_bf16 v[12:15], v[176:179], v[212:215], v[12:15]
	v_mfma_f32_16x16x32_bf16 v[8:11], v[188:191], v[212:215], v[8:11]
	v_mfma_f32_16x16x32_bf16 v[4:7], v[176:179], v[220:223], v[4:7]
	v_mfma_f32_16x16x32_bf16 v[0:3], v[188:191], v[220:223], v[0:3]
	s_barrier
	s_add_i32 s12, 0, 0x18000
	v_add_u32_e32 v159, s12, v162
	s_add_i32 s13, 0, 0x1c000
	ds_read_b128 v[96:99], v159
	ds_read_b128 v[100:103], v159 offset:1024
	ds_read_b128 v[164:167], v159 offset:2048
	ds_read_b128 v[168:171], v159 offset:3072
	v_add_u32_e32 v159, s13, v162
	ds_read_b128 v[172:175], v159
	ds_read_b128 v[176:179], v159 offset:1024
	ds_read_b128 v[184:187], v159 offset:2048
	ds_read_b128 v[188:191], v159 offset:3072
	s_add_u32 s46, s66, 0x40000
	s_addc_u32 s47, s67, 0
	s_mov_b32 m0, s71
	v_lshl_add_u64 v[228:229], s[46:47], 0, v[140:141]
	ds_read_b128 v[192:195], v158 offset:32768
	ds_read_b128 v[196:199], v158 offset:33792
	ds_read_b128 v[200:203], v158 offset:34816
	ds_read_b128 v[204:207], v158 offset:35840
	ds_read_b128 v[208:211], v158 offset:36864
	ds_read_b128 v[212:215], v158 offset:37888
	ds_read_b128 v[216:219], v158 offset:38912
	ds_read_b128 v[220:223], v158 offset:39936
	global_load_lds_dwordx4 v[228:229], off
	v_lshl_add_u64 v[228:229], s[46:47], 0, v[142:143]
	s_mov_b32 m0, s72
	s_nop 0
	global_load_lds_dwordx4 v[228:229], off
	s_waitcnt vmcnt(8)
	s_waitcnt lgkmcnt(0)
	s_barrier
	s_waitcnt lgkmcnt(0)
	v_mfma_f32_16x16x32_bf16 v[132:135], v[96:99], v[192:195], v[132:135]
	v_mfma_f32_16x16x32_bf16 v[128:131], v[164:167], v[192:195], v[128:131]
	v_mfma_f32_16x16x32_bf16 v[124:127], v[96:99], v[200:203], v[124:127]
	v_mfma_f32_16x16x32_bf16 v[120:123], v[164:167], v[200:203], v[120:123]
	v_mfma_f32_16x16x32_bf16 v[116:119], v[96:99], v[208:211], v[116:119]
	v_mfma_f32_16x16x32_bf16 v[112:115], v[164:167], v[208:211], v[112:115]
	v_mfma_f32_16x16x32_bf16 v[108:111], v[96:99], v[216:219], v[108:111]
	v_mfma_f32_16x16x32_bf16 v[104:107], v[164:167], v[216:219], v[104:107]
	v_mfma_f32_16x16x32_bf16 v[132:135], v[100:103], v[196:199], v[132:135]
	v_mfma_f32_16x16x32_bf16 v[128:131], v[168:171], v[196:199], v[128:131]
	v_mfma_f32_16x16x32_bf16 v[124:127], v[100:103], v[204:207], v[124:127]
	v_mfma_f32_16x16x32_bf16 v[120:123], v[168:171], v[204:207], v[120:123]
	v_mfma_f32_16x16x32_bf16 v[116:119], v[100:103], v[212:215], v[116:119]
	v_mfma_f32_16x16x32_bf16 v[112:115], v[168:171], v[212:215], v[112:115]
	v_mfma_f32_16x16x32_bf16 v[108:111], v[100:103], v[220:223], v[108:111]
	v_mfma_f32_16x16x32_bf16 v[104:107], v[168:171], v[220:223], v[104:107]
	v_mfma_f32_16x16x32_bf16 v[60:63], v[172:175], v[192:195], v[60:63]
	v_mfma_f32_16x16x32_bf16 v[56:59], v[184:187], v[192:195], v[56:59]
	v_mfma_f32_16x16x32_bf16 v[52:55], v[172:175], v[200:203], v[52:55]
	v_mfma_f32_16x16x32_bf16 v[48:51], v[184:187], v[200:203], v[48:51]
	v_mfma_f32_16x16x32_bf16 v[44:47], v[172:175], v[208:211], v[44:47]
	v_mfma_f32_16x16x32_bf16 v[40:43], v[184:187], v[208:211], v[40:43]
	v_mfma_f32_16x16x32_bf16 v[36:39], v[172:175], v[216:219], v[36:39]
	v_mfma_f32_16x16x32_bf16 v[32:35], v[184:187], v[216:219], v[32:35]
	v_mfma_f32_16x16x32_bf16 v[60:63], v[176:179], v[196:199], v[60:63]
	v_mfma_f32_16x16x32_bf16 v[56:59], v[188:191], v[196:199], v[56:59]
	v_mfma_f32_16x16x32_bf16 v[52:55], v[176:179], v[204:207], v[52:55]
	v_mfma_f32_16x16x32_bf16 v[48:51], v[188:191], v[204:207], v[48:51]
	v_mfma_f32_16x16x32_bf16 v[44:47], v[176:179], v[212:215], v[44:47]
	v_mfma_f32_16x16x32_bf16 v[40:43], v[188:191], v[212:215], v[40:43]
	v_mfma_f32_16x16x32_bf16 v[36:39], v[176:179], v[220:223], v[36:39]
	v_mfma_f32_16x16x32_bf16 v[32:35], v[188:191], v[220:223], v[32:35]
	s_barrier
; #define PG8_STAGE(bufoff, gbase, voff) do { _Pragma("unroll") for (int _i = 0; _i < 2; ++_i) \
;         __builtin_amdgcn_global_load_lds((const unsigned*)((const char*)(gbase) + (voff)[_i]), (LAS unsigned*)(lds + (bufoff) + ldsw + _i * 8192), 16, 0, 0); } while (0)
; #define PG8_LDA(dst, b, h) do { _Pragma("unroll") for (int m = 0; m < 4; ++m) _Pragma("unroll") for (int k = 0; k < 2; ++k) dst[m][k] = *(const LAS bf16x8*)(lds + PG8_SA(b, h) + aoff + m * 2048 + k * 1024); } while (0)
; #define PG8_MMA(ai, bj, At, Bt) do { __builtin_amdgcn_s_setprio(1); _Pragma("unroll") for (int m = 0; m < 4; ++m) _Pragma("unroll") for (int n = 0; n < 2; ++n) _Pragma("unroll") for (int k = 0; k < 2; ++k) \
;         acc[ai][bj][m][n] = __builtin_amdgcn_mfma_f32_16x16x32_bf16(Bt[n][k], At[m][k], acc[ai][bj][m][n], 0, 0, 0); __builtin_amdgcn_s_setprio(0); } while (0)
; #define PG8_WAIT_V(n) asm volatile("s_waitcnt vmcnt(" #n ")" ::: "memory")
; #define PG8_WAIT_L(n) asm volatile("s_waitcnt lgkmcnt(" #n ")" ::: "memory")
; #define PG8_BAR __builtin_amdgcn_s_barrier()
; #define PG8_SCHED __builtin_amdgcn_sched_barrier(0)
; template <bool LT, class Epi>
; __device__ __forceinline__ void gemm_phase(LAS unsigned char* lds, const Gemm g, const StaticOrder& S, const Epi& E) {
;     ...
;         for (int t = 0; t < nt; t += 2) {
;     ...
;             PG8_LDA(At, 1, 1); PG8_STAGE(PG8_SB(1, 0), b3, voffB); PG8_STAGE(PG8_SB(1, 1), b3 + hstepB, voffB); PG8_STAGE(PG8_SA(1, 0), a3, voffA);
;             PG8_WAIT_V(8); PG8_WAIT_L(0); PG8_BAR; PG8_MMA(1, 0, At, B0); PG8_MMA(1, 1, At, B1); PG8_BAR; PG8_SCHED;
	s_add_i32 s12, s12, s69
	v_lshl_add_u64 v[152:153], v[152:153], 0, s[4:5]
	s_mov_b32 m0, s12
	ds_read_b128 v[192:195], v158 offset:49152
	ds_read_b128 v[196:199], v158 offset:50176
	ds_read_b128 v[200:203], v158 offset:51200
	ds_read_b128 v[204:207], v158 offset:52224
	ds_read_b128 v[208:211], v158 offset:53248
	ds_read_b128 v[212:215], v158 offset:54272
	ds_read_b128 v[216:219], v158 offset:55296
	ds_read_b128 v[220:223], v158 offset:56320
	global_load_lds_dwordx4 v[152:153], off
	s_add_i32 m0, s12, 0x2000
	s_add_u32 s46, s62, 0x80080
	v_lshl_add_u64 v[152:153], v[160:161], 0, s[4:5]
	s_addc_u32 s47, s63, 0
	s_add_i32 s12, s13, s69
	global_load_lds_dwordx4 v[152:153], off
	v_lshl_add_u64 v[152:153], s[46:47], 0, v[136:137]
	s_mov_b32 m0, s12
	s_nop 0
	global_load_lds_dwordx4 v[152:153], off
	v_lshl_add_u64 v[152:153], s[46:47], 0, v[138:139]
	s_add_i32 m0, s12, 0x2000
	s_nop 0
	global_load_lds_dwordx4 v[152:153], off
	v_lshl_add_u64 v[152:153], v[224:225], 0, s[4:5]
	s_mov_b32 m0, s74
	s_nop 0
	global_load_lds_dwordx4 v[152:153], off
	v_lshl_add_u64 v[152:153], v[226:227], 0, s[4:5]
	s_mov_b32 m0, s75
	s_nop 0
	global_load_lds_dwordx4 v[152:153], off
	s_waitcnt vmcnt(8)
	s_waitcnt lgkmcnt(0)
	s_barrier
	s_waitcnt lgkmcnt(0)
	v_mfma_f32_16x16x32_bf16 v[92:95], v[96:99], v[192:195], v[92:95]
	v_mfma_f32_16x16x32_bf16 v[88:91], v[164:167], v[192:195], v[88:91]
	v_mfma_f32_16x16x32_bf16 v[84:87], v[96:99], v[200:203], v[84:87]
	v_mfma_f32_16x16x32_bf16 v[80:83], v[164:167], v[200:203], v[80:83]
	v_mfma_f32_16x16x32_bf16 v[76:79], v[96:99], v[208:211], v[76:79]
	v_mfma_f32_16x16x32_bf16 v[72:75], v[164:167], v[208:211], v[72:75]
	v_mfma_f32_16x16x32_bf16 v[68:71], v[96:99], v[216:219], v[68:71]
	v_mfma_f32_16x16x32_bf16 v[64:67], v[164:167], v[216:219], v[64:67]
	v_mfma_f32_16x16x32_bf16 v[92:95], v[100:103], v[196:199], v[92:95]
	v_mfma_f32_16x16x32_bf16 v[88:91], v[168:171], v[196:199], v[88:91]
	v_mfma_f32_16x16x32_bf16 v[84:87], v[100:103], v[204:207], v[84:87]
	v_mfma_f32_16x16x32_bf16 v[80:83], v[168:171], v[204:207], v[80:83]
	v_mfma_f32_16x16x32_bf16 v[76:79], v[100:103], v[212:215], v[76:79]
	v_mfma_f32_16x16x32_bf16 v[72:75], v[168:171], v[212:215], v[72:75]
	v_mfma_f32_16x16x32_bf16 v[68:71], v[100:103], v[220:223], v[68:71]
	v_mfma_f32_16x16x32_bf16 v[64:67], v[168:171], v[220:223], v[64:67]
	v_mfma_f32_16x16x32_bf16 v[28:31], v[172:175], v[192:195], v[28:31]
	v_mfma_f32_16x16x32_bf16 v[24:27], v[184:187], v[192:195], v[24:27]
	v_mfma_f32_16x16x32_bf16 v[20:23], v[172:175], v[200:203], v[20:23]
	v_mfma_f32_16x16x32_bf16 v[16:19], v[184:187], v[200:203], v[16:19]
	v_mfma_f32_16x16x32_bf16 v[12:15], v[172:175], v[208:211], v[12:15]
	v_mfma_f32_16x16x32_bf16 v[8:11], v[184:187], v[208:211], v[8:11]
	v_mfma_f32_16x16x32_bf16 v[4:7], v[172:175], v[216:219], v[4:7]
	v_mfma_f32_16x16x32_bf16 v[0:3], v[184:187], v[216:219], v[0:3]
	v_mfma_f32_16x16x32_bf16 v[28:31], v[176:179], v[196:199], v[28:31]
	v_mfma_f32_16x16x32_bf16 v[24:27], v[188:191], v[196:199], v[24:27]
	v_mfma_f32_16x16x32_bf16 v[20:23], v[176:179], v[204:207], v[20:23]
	v_mfma_f32_16x16x32_bf16 v[16:19], v[188:191], v[204:207], v[16:19]
	v_mfma_f32_16x16x32_bf16 v[12:15], v[176:179], v[212:215], v[12:15]
	v_mfma_f32_16x16x32_bf16 v[8:11], v[188:191], v[212:215], v[8:11]
	v_mfma_f32_16x16x32_bf16 v[4:7], v[176:179], v[220:223], v[4:7]
	v_mfma_f32_16x16x32_bf16 v[0:3], v[188:191], v[220:223], v[0:3]
	s_barrier
	s_add_i32 s33, s33, 2
	s_add_u32 s19, s19, 0x100
	s_addc_u32 s25, s25, 0
	s_cmp_gt_u32 s33, 29
	s_mov_b64 s[56:57], s[58:59]
	s_cbranch_scc0 .LBB0_559
	s_and_b64 vcc, exec, s[6:7]
	s_cbranch_vccz .LBB0_562
	s_barrier

; #define PG8_STAGE(bufoff, gbase, voff) do { _Pragma("unroll") for (int _i = 0; _i < 2; ++_i) \
;         __builtin_amdgcn_global_load_lds((const unsigned*)((const char*)(gbase) + (voff)[_i]), (LAS unsigned*)(lds + (bufoff) + ldsw + _i * 8192), 16, 0, 0); } while (0)
; #define PG8_LDA(dst, b, h) do { _Pragma("unroll") for (int m = 0; m < 4; ++m) _Pragma("unroll") for (int k = 0; k < 2; ++k) dst[m][k] = *(const LAS bf16x8*)(lds + PG8_SA(b, h) + aoff + m * 2048 + k * 1024); } while (0)
; #define PG8_LDB(dst, b, h) do { _Pragma("unroll") for (int n = 0; n < 2; ++n) _Pragma("unroll") for (int k = 0; k < 2; ++k) dst[n][k] = *(const LAS bf16x8*)(lds + PG8_SB(b, h) + boff + n * 2048 + k * 1024); } while (0)
; #define PG8_MMA(ai, bj, At, Bt) do { __builtin_amdgcn_s_setprio(1); _Pragma("unroll") for (int m = 0; m < 4; ++m) _Pragma("unroll") for (int n = 0; n < 2; ++n) _Pragma("unroll") for (int k = 0; k < 2; ++k) \
;         acc[ai][bj][m][n] = __builtin_amdgcn_mfma_f32_16x16x32_bf16(Bt[n][k], At[m][k], acc[ai][bj][m][n], 0, 0, 0); __builtin_amdgcn_s_setprio(0); } while (0)
; #define PG8_WAIT_V(n) asm volatile("s_waitcnt vmcnt(" #n ")" ::: "memory")
; #define PG8_WAIT_L(n) asm volatile("s_waitcnt lgkmcnt(" #n ")" ::: "memory")
; #define PG8_BAR __builtin_amdgcn_s_barrier()
; #define PG8_SCHED __builtin_amdgcn_sched_barrier(0)
; template <bool LT, class Epi>
; __device__ __forceinline__ void gemm_phase(LAS unsigned char* lds, const Gemm g, const StaticOrder& S, const Epi& E) {
;     ...
;             const bool last = (t == nt - 2);
;             const char* a1 = cA + (size_t)(t + 1) * kstep;
;             const char* a2 = last ? nA : cA + (size_t)(t + 2) * kstep; const char* b2 = last ? nB : cB + (size_t)(t + 2) * kstep;
;             const char* a3 = a2 + kstep; const char* b3 = b2 + kstep;
;             PG8_LDB(B0, 0, 0); PG8_LDB(B1, 0, 1); PG8_SCHED; PG8_LDA(At, 0, 0); PG8_STAGE(PG8_SA(1, 1), a1 + hstepA, voffA);
;             PG8_WAIT_V(8); PG8_WAIT_L(0); PG8_BAR; PG8_MMA(0, 0, At, B0); PG8_MMA(0, 1, At, B1); PG8_BAR; PG8_SCHED;
;             PG8_LDA(At, 0, 1); PG8_STAGE(PG8_SB(0, 0), b2, voffB); PG8_STAGE(PG8_SB(0, 1), b2 + hstepB, voffB); PG8_STAGE(PG8_SA(0, 0), a2, voffA);
.LBB0_1624:
	ds_read_b128 v[144:147], v153
	ds_read_b128 v[156:159], v153 offset:1024
	ds_read_b128 v[160:163], v153 offset:2048
	ds_read_b128 v[164:167], v153 offset:3072
	ds_read_b128 v[168:171], v154
	ds_read_b128 v[172:175], v154 offset:1024
	ds_read_b128 v[176:179], v154 offset:2048
	ds_read_b128 v[184:187], v154 offset:3072
	s_add_u32 s52, s56, 0xfffc0080
	s_addc_u32 s53, s57, -1
	s_cmp_eq_u32 s72, 12
	s_cselect_b32 s61, s35, s53
	s_cselect_b32 s60, s42, s52
	s_cselect_b32 s59, s25, s71
	s_cselect_b32 s58, s43, s70
	v_lshl_add_u64 v[148:149], s[56:57], 0, v[136:137]
	s_add_i32 m0, s19, 0xc000
	ds_read_b128 v[188:191], v155
	ds_read_b128 v[192:195], v155 offset:1024
	ds_read_b128 v[196:199], v155 offset:2048
	ds_read_b128 v[200:203], v155 offset:3072
	ds_read_b128 v[204:207], v155 offset:4096
	ds_read_b128 v[208:211], v155 offset:5120
	ds_read_b128 v[212:215], v155 offset:6144
	ds_read_b128 v[216:219], v155 offset:7168
	global_load_lds_dwordx4 v[148:149], off
	v_lshl_add_u64 v[148:149], s[56:57], 0, v[138:139]
	s_add_i32 m0, s19, 0xe000
	s_nop 0
	global_load_lds_dwordx4 v[148:149], off
	s_waitcnt vmcnt(8)
	s_waitcnt lgkmcnt(0)
	s_barrier
	s_waitcnt lgkmcnt(0)
	v_mfma_f32_16x16x32_bf16 v[116:119], v[144:147], v[188:191], v[116:119]
	v_mfma_f32_16x16x32_bf16 v[112:115], v[160:163], v[188:191], v[112:115]
	v_mfma_f32_16x16x32_bf16 v[100:103], v[144:147], v[196:199], v[100:103]
	v_mfma_f32_16x16x32_bf16 v[96:99], v[160:163], v[196:199], v[96:99]
	v_mfma_f32_16x16x32_bf16 v[84:87], v[144:147], v[204:207], v[84:87]
	v_mfma_f32_16x16x32_bf16 v[80:83], v[160:163], v[204:207], v[80:83]
	v_mfma_f32_16x16x32_bf16 v[68:71], v[144:147], v[212:215], v[68:71]
	v_mfma_f32_16x16x32_bf16 v[64:67], v[160:163], v[212:215], v[64:67]
	v_mfma_f32_16x16x32_bf16 v[116:119], v[156:159], v[192:195], v[116:119]
	v_mfma_f32_16x16x32_bf16 v[112:115], v[164:167], v[192:195], v[112:115]
	v_mfma_f32_16x16x32_bf16 v[100:103], v[156:159], v[200:203], v[100:103]
	v_mfma_f32_16x16x32_bf16 v[96:99], v[164:167], v[200:203], v[96:99]
	v_mfma_f32_16x16x32_bf16 v[84:87], v[156:159], v[208:211], v[84:87]
	v_mfma_f32_16x16x32_bf16 v[80:83], v[164:167], v[208:211], v[80:83]
	v_mfma_f32_16x16x32_bf16 v[68:71], v[156:159], v[216:219], v[68:71]
	v_mfma_f32_16x16x32_bf16 v[64:67], v[164:167], v[216:219], v[64:67]
	v_mfma_f32_16x16x32_bf16 v[124:127], v[168:171], v[188:191], v[124:127]
	v_mfma_f32_16x16x32_bf16 v[120:123], v[176:179], v[188:191], v[120:123]
	v_mfma_f32_16x16x32_bf16 v[108:111], v[168:171], v[196:199], v[108:111]
	v_mfma_f32_16x16x32_bf16 v[104:107], v[176:179], v[196:199], v[104:107]
	v_mfma_f32_16x16x32_bf16 v[92:95], v[168:171], v[204:207], v[92:95]
	v_mfma_f32_16x16x32_bf16 v[88:91], v[176:179], v[204:207], v[88:91]
	v_mfma_f32_16x16x32_bf16 v[76:79], v[168:171], v[212:215], v[76:79]
	v_mfma_f32_16x16x32_bf16 v[72:75], v[176:179], v[212:215], v[72:75]
	v_mfma_f32_16x16x32_bf16 v[124:127], v[172:175], v[192:195], v[124:127]
	v_mfma_f32_16x16x32_bf16 v[120:123], v[184:187], v[192:195], v[120:123]
	v_mfma_f32_16x16x32_bf16 v[108:111], v[172:175], v[200:203], v[108:111]
	v_mfma_f32_16x16x32_bf16 v[104:107], v[184:187], v[200:203], v[104:107]
	v_mfma_f32_16x16x32_bf16 v[92:95], v[172:175], v[208:211], v[92:95]
	v_mfma_f32_16x16x32_bf16 v[88:91], v[184:187], v[208:211], v[88:91]
	v_mfma_f32_16x16x32_bf16 v[76:79], v[172:175], v[216:219], v[76:79]
	v_mfma_f32_16x16x32_bf16 v[72:75], v[184:187], v[216:219], v[72:75]
	s_barrier
	s_add_i32 s52, s67, s18
	v_lshl_add_u64 v[148:149], s[58:59], 0, v[130:131]
	s_mov_b32 m0, s52
	ds_read_b128 v[188:191], v155 offset:16384
	ds_read_b128 v[192:195], v155 offset:17408
	ds_read_b128 v[196:199], v155 offset:18432
	ds_read_b128 v[200:203], v155 offset:19456
	ds_read_b128 v[204:207], v155 offset:20480
	ds_read_b128 v[208:211], v155 offset:21504
	ds_read_b128 v[212:215], v155 offset:22528
	ds_read_b128 v[216:219], v155 offset:23552
	global_load_lds_dwordx4 v[148:149], off
	s_add_i32 m0, s52, 0x2000
	s_add_u32 s52, s58, 0x40000
	v_lshl_add_u64 v[220:221], s[58:59], 0, v[134:135]
	s_addc_u32 s53, s59, 0
	s_add_i32 s73, s68, s18
	global_load_lds_dwordx4 v[220:221], off
	v_lshl_add_u64 v[222:223], s[52:53], 0, v[130:131]
	s_mov_b32 m0, s73
	v_lshl_add_u64 v[224:225], s[60:61], 0, v[132:133]
	global_load_lds_dwordx4 v[222:223], off
	v_lshl_add_u64 v[222:223], s[52:53], 0, v[134:135]
	s_add_i32 m0, s73, 0x2000
	s_nop 0
	global_load_lds_dwordx4 v[222:223], off
	v_lshl_add_u64 v[222:223], s[60:61], 0, v[128:129]
	s_mov_b32 m0, s19
	s_nop 0
	global_load_lds_dwordx4 v[222:223], off
	s_mov_b32 m0, s27
	s_nop 0
	global_load_lds_dwordx4 v[224:225], off
	s_waitcnt vmcnt(8)
	s_waitcnt lgkmcnt(0)
	s_barrier
; #define PG8_STAGE(bufoff, gbase, voff) do { _Pragma("unroll") for (int _i = 0; _i < 2; ++_i) \
;         __builtin_amdgcn_global_load_lds((const unsigned*)((const char*)(gbase) + (voff)[_i]), (LAS unsigned*)(lds + (bufoff) + ldsw + _i * 8192), 16, 0, 0); } while (0)
; #define PG8_LDA(dst, b, h) do { _Pragma("unroll") for (int m = 0; m < 4; ++m) _Pragma("unroll") for (int k = 0; k < 2; ++k) dst[m][k] = *(const LAS bf16x8*)(lds + PG8_SA(b, h) + aoff + m * 2048 + k * 1024); } while (0)
; #define PG8_LDB(dst, b, h) do { _Pragma("unroll") for (int n = 0; n < 2; ++n) _Pragma("unroll") for (int k = 0; k < 2; ++k) dst[n][k] = *(const LAS bf16x8*)(lds + PG8_SB(b, h) + boff + n * 2048 + k * 1024); } while (0)
; #define PG8_MMA(ai, bj, At, Bt) do { __builtin_amdgcn_s_setprio(1); _Pragma("unroll") for (int m = 0; m < 4; ++m) _Pragma("unroll") for (int n = 0; n < 2; ++n) _Pragma("unroll") for (int k = 0; k < 2; ++k) \
;         acc[ai][bj][m][n] = __builtin_amdgcn_mfma_f32_16x16x32_bf16(Bt[n][k], At[m][k], acc[ai][bj][m][n], 0, 0, 0); __builtin_amdgcn_s_setprio(0); } while (0)
; #define PG8_WAIT_V(n) asm volatile("s_waitcnt vmcnt(" #n ")" ::: "memory")
; #define PG8_WAIT_L(n) asm volatile("s_waitcnt lgkmcnt(" #n ")" ::: "memory")
; #define PG8_BAR __builtin_amdgcn_s_barrier()
; #define PG8_SCHED __builtin_amdgcn_sched_barrier(0)
; template <bool LT, class Epi>
; __device__ __forceinline__ void gemm_phase(LAS unsigned char* lds, const Gemm g, const StaticOrder& S, const Epi& E) {
;     ...
;             PG8_WAIT_V(8); PG8_WAIT_L(0); PG8_BAR; PG8_MMA(1, 0, At, B0); PG8_MMA(1, 1, At, B1); PG8_BAR; PG8_SCHED;
;             PG8_LDB(B0, 1, 0); PG8_LDB(B1, 1, 1); PG8_SCHED; PG8_LDA(At, 1, 0); PG8_STAGE(PG8_SA(0, 1), a2 + hstepA, voffA);
;             PG8_WAIT_V(8); PG8_WAIT_L(0); PG8_BAR; PG8_MMA(0, 0, At, B0); PG8_MMA(0, 1, At, B1); PG8_BAR; PG8_SCHED;
	s_waitcnt lgkmcnt(0)
	v_mfma_f32_16x16x32_bf16 v[52:55], v[144:147], v[188:191], v[52:55]
	v_mfma_f32_16x16x32_bf16 v[48:51], v[160:163], v[188:191], v[48:51]
	v_mfma_f32_16x16x32_bf16 v[36:39], v[144:147], v[196:199], v[36:39]
	v_mfma_f32_16x16x32_bf16 v[32:35], v[160:163], v[196:199], v[32:35]
	v_mfma_f32_16x16x32_bf16 v[20:23], v[144:147], v[204:207], v[20:23]
	v_mfma_f32_16x16x32_bf16 v[16:19], v[160:163], v[204:207], v[16:19]
	v_mfma_f32_16x16x32_bf16 v[4:7], v[144:147], v[212:215], v[4:7]
	v_mfma_f32_16x16x32_bf16 v[0:3], v[160:163], v[212:215], v[0:3]
	v_mfma_f32_16x16x32_bf16 v[52:55], v[156:159], v[192:195], v[52:55]
	v_mfma_f32_16x16x32_bf16 v[48:51], v[164:167], v[192:195], v[48:51]
	v_mfma_f32_16x16x32_bf16 v[36:39], v[156:159], v[200:203], v[36:39]
	v_mfma_f32_16x16x32_bf16 v[32:35], v[164:167], v[200:203], v[32:35]
	v_mfma_f32_16x16x32_bf16 v[20:23], v[156:159], v[208:211], v[20:23]
	v_mfma_f32_16x16x32_bf16 v[16:19], v[164:167], v[208:211], v[16:19]
	v_mfma_f32_16x16x32_bf16 v[4:7], v[156:159], v[216:219], v[4:7]
	v_mfma_f32_16x16x32_bf16 v[0:3], v[164:167], v[216:219], v[0:3]
	v_mfma_f32_16x16x32_bf16 v[60:63], v[168:171], v[188:191], v[60:63]
	v_mfma_f32_16x16x32_bf16 v[56:59], v[176:179], v[188:191], v[56:59]
	v_mfma_f32_16x16x32_bf16 v[44:47], v[168:171], v[196:199], v[44:47]
	v_mfma_f32_16x16x32_bf16 v[40:43], v[176:179], v[196:199], v[40:43]
	v_mfma_f32_16x16x32_bf16 v[28:31], v[168:171], v[204:207], v[28:31]
	v_mfma_f32_16x16x32_bf16 v[24:27], v[176:179], v[204:207], v[24:27]
	v_mfma_f32_16x16x32_bf16 v[12:15], v[168:171], v[212:215], v[12:15]
	v_mfma_f32_16x16x32_bf16 v[8:11], v[176:179], v[212:215], v[8:11]
	v_mfma_f32_16x16x32_bf16 v[60:63], v[172:175], v[192:195], v[60:63]
	v_mfma_f32_16x16x32_bf16 v[56:59], v[184:187], v[192:195], v[56:59]
	v_mfma_f32_16x16x32_bf16 v[44:47], v[172:175], v[200:203], v[44:47]
	v_mfma_f32_16x16x32_bf16 v[40:43], v[184:187], v[200:203], v[40:43]
	v_mfma_f32_16x16x32_bf16 v[28:31], v[172:175], v[208:211], v[28:31]
	v_mfma_f32_16x16x32_bf16 v[24:27], v[184:187], v[208:211], v[24:27]
	v_mfma_f32_16x16x32_bf16 v[12:15], v[172:175], v[216:219], v[12:15]
	v_mfma_f32_16x16x32_bf16 v[8:11], v[184:187], v[216:219], v[8:11]
	s_barrier
	s_add_i32 s73, 0, 0x18000
	s_add_i32 s74, 0, 0x1c000
	v_add_u32_e32 v164, s73, v151
	v_add_u32_e32 v183, s74, v151
	ds_read_b128 v[144:147], v164
	ds_read_b128 v[156:159], v164 offset:1024
	ds_read_b128 v[160:163], v164 offset:2048
	ds_read_b128 v[164:167], v164 offset:3072
	ds_read_b128 v[168:171], v183
	ds_read_b128 v[172:175], v183 offset:1024
	ds_read_b128 v[176:179], v183 offset:2048
	ds_read_b128 v[184:187], v183 offset:3072
	s_add_u32 s52, s60, 0x40000
	s_addc_u32 s53, s61, 0
	s_mov_b32 m0, s33
	v_lshl_add_u64 v[226:227], s[52:53], 0, v[128:129]
	ds_read_b128 v[188:191], v155 offset:32768
	ds_read_b128 v[192:195], v155 offset:33792
	ds_read_b128 v[196:199], v155 offset:34816
	ds_read_b128 v[200:203], v155 offset:35840
	ds_read_b128 v[204:207], v155 offset:36864
	ds_read_b128 v[208:211], v155 offset:37888
	ds_read_b128 v[212:215], v155 offset:38912
	ds_read_b128 v[216:219], v155 offset:39936
	global_load_lds_dwordx4 v[226:227], off
	v_lshl_add_u64 v[226:227], s[52:53], 0, v[132:133]
	s_mov_b32 m0, s55
	s_nop 0
	global_load_lds_dwordx4 v[226:227], off
	s_waitcnt vmcnt(8)
	s_waitcnt lgkmcnt(0)
	s_barrier
	s_waitcnt lgkmcnt(0)
	v_mfma_f32_16x16x32_bf16 v[116:119], v[144:147], v[188:191], v[116:119]
	v_mfma_f32_16x16x32_bf16 v[112:115], v[160:163], v[188:191], v[112:115]
	v_mfma_f32_16x16x32_bf16 v[100:103], v[144:147], v[196:199], v[100:103]
	v_mfma_f32_16x16x32_bf16 v[96:99], v[160:163], v[196:199], v[96:99]
	v_mfma_f32_16x16x32_bf16 v[84:87], v[144:147], v[204:207], v[84:87]
	v_mfma_f32_16x16x32_bf16 v[80:83], v[160:163], v[204:207], v[80:83]
	v_mfma_f32_16x16x32_bf16 v[68:71], v[144:147], v[212:215], v[68:71]
	v_mfma_f32_16x16x32_bf16 v[64:67], v[160:163], v[212:215], v[64:67]
	v_mfma_f32_16x16x32_bf16 v[116:119], v[156:159], v[192:195], v[116:119]
	v_mfma_f32_16x16x32_bf16 v[112:115], v[164:167], v[192:195], v[112:115]
	v_mfma_f32_16x16x32_bf16 v[100:103], v[156:159], v[200:203], v[100:103]
	v_mfma_f32_16x16x32_bf16 v[96:99], v[164:167], v[200:203], v[96:99]
	v_mfma_f32_16x16x32_bf16 v[84:87], v[156:159], v[208:211], v[84:87]
	v_mfma_f32_16x16x32_bf16 v[80:83], v[164:167], v[208:211], v[80:83]
	v_mfma_f32_16x16x32_bf16 v[68:71], v[156:159], v[216:219], v[68:71]
	v_mfma_f32_16x16x32_bf16 v[64:67], v[164:167], v[216:219], v[64:67]
	v_mfma_f32_16x16x32_bf16 v[124:127], v[168:171], v[188:191], v[124:127]
	v_mfma_f32_16x16x32_bf16 v[120:123], v[176:179], v[188:191], v[120:123]
	v_mfma_f32_16x16x32_bf16 v[108:111], v[168:171], v[196:199], v[108:111]
	v_mfma_f32_16x16x32_bf16 v[104:107], v[176:179], v[196:199], v[104:107]
	v_mfma_f32_16x16x32_bf16 v[92:95], v[168:171], v[204:207], v[92:95]
	v_mfma_f32_16x16x32_bf16 v[88:91], v[176:179], v[204:207], v[88:91]
	v_mfma_f32_16x16x32_bf16 v[76:79], v[168:171], v[212:215], v[76:79]
	v_mfma_f32_16x16x32_bf16 v[72:75], v[176:179], v[212:215], v[72:75]
	v_mfma_f32_16x16x32_bf16 v[124:127], v[172:175], v[192:195], v[124:127]
	v_mfma_f32_16x16x32_bf16 v[120:123], v[184:187], v[192:195], v[120:123]
	v_mfma_f32_16x16x32_bf16 v[108:111], v[172:175], v[200:203], v[108:111]
	v_mfma_f32_16x16x32_bf16 v[104:107], v[184:187], v[200:203], v[104:107]
	v_mfma_f32_16x16x32_bf16 v[92:95], v[172:175], v[208:211], v[92:95]
	v_mfma_f32_16x16x32_bf16 v[88:91], v[184:187], v[208:211], v[88:91]
	v_mfma_f32_16x16x32_bf16 v[76:79], v[172:175], v[216:219], v[76:79]
	v_mfma_f32_16x16x32_bf16 v[72:75], v[184:187], v[216:219], v[72:75]
	s_barrier
; #define PG8_STAGE(bufoff, gbase, voff) do { _Pragma("unroll") for (int _i = 0; _i < 2; ++_i) \
;         __builtin_amdgcn_global_load_lds((const unsigned*)((const char*)(gbase) + (voff)[_i]), (LAS unsigned*)(lds + (bufoff) + ldsw + _i * 8192), 16, 0, 0); } while (0)
; #define PG8_LDA(dst, b, h) do { _Pragma("unroll") for (int m = 0; m < 4; ++m) _Pragma("unroll") for (int k = 0; k < 2; ++k) dst[m][k] = *(const LAS bf16x8*)(lds + PG8_SA(b, h) + aoff + m * 2048 + k * 1024); } while (0)
; #define PG8_MMA(ai, bj, At, Bt) do { __builtin_amdgcn_s_setprio(1); _Pragma("unroll") for (int m = 0; m < 4; ++m) _Pragma("unroll") for (int n = 0; n < 2; ++n) _Pragma("unroll") for (int k = 0; k < 2; ++k) \
;         acc[ai][bj][m][n] = __builtin_amdgcn_mfma_f32_16x16x32_bf16(Bt[n][k], At[m][k], acc[ai][bj][m][n], 0, 0, 0); __builtin_amdgcn_s_setprio(0); } while (0)
; #define PG8_WAIT_V(n) asm volatile("s_waitcnt vmcnt(" #n ")" ::: "memory")
; #define PG8_WAIT_L(n) asm volatile("s_waitcnt lgkmcnt(" #n ")" ::: "memory")
; #define PG8_BAR __builtin_amdgcn_s_barrier()
; #define PG8_SCHED __builtin_amdgcn_sched_barrier(0)
; template <bool LT, class Epi>
; __device__ __forceinline__ void gemm_phase(LAS unsigned char* lds, const Gemm g, const StaticOrder& S, const Epi& E) {
;     ...
;         for (int t = 0; t < nt; t += 2) {
;     ...
;             PG8_LDA(At, 1, 1); PG8_STAGE(PG8_SB(1, 0), b3, voffB); PG8_STAGE(PG8_SB(1, 1), b3 + hstepB, voffB); PG8_STAGE(PG8_SA(1, 0), a3, voffA);
;             PG8_WAIT_V(8); PG8_WAIT_L(0); PG8_BAR; PG8_MMA(1, 0, At, B0); PG8_MMA(1, 1, At, B1); PG8_BAR; PG8_SCHED;
	s_add_i32 s52, s73, s18
	v_lshl_add_u64 v[148:149], v[148:149], 0, s[6:7]
	s_mov_b32 m0, s52
	ds_read_b128 v[188:191], v155 offset:49152
	ds_read_b128 v[192:195], v155 offset:50176
	ds_read_b128 v[196:199], v155 offset:51200
	ds_read_b128 v[200:203], v155 offset:52224
	ds_read_b128 v[204:207], v155 offset:53248
	ds_read_b128 v[208:211], v155 offset:54272
	ds_read_b128 v[212:215], v155 offset:55296
	ds_read_b128 v[216:219], v155 offset:56320
	global_load_lds_dwordx4 v[148:149], off
	s_add_i32 m0, s52, 0x2000
	s_add_u32 s52, s58, 0x40080
	v_lshl_add_u64 v[148:149], v[220:221], 0, s[6:7]
	s_addc_u32 s53, s59, 0
	s_add_i32 s58, s74, s18
	global_load_lds_dwordx4 v[148:149], off
	v_lshl_add_u64 v[148:149], s[52:53], 0, v[130:131]
	s_mov_b32 m0, s58
	s_nop 0
	global_load_lds_dwordx4 v[148:149], off
	v_lshl_add_u64 v[148:149], s[52:53], 0, v[134:135]
	s_add_i32 m0, s58, 0x2000
	s_nop 0
	global_load_lds_dwordx4 v[148:149], off
	v_lshl_add_u64 v[148:149], v[222:223], 0, s[6:7]
	s_mov_b32 m0, s63
	s_nop 0
	global_load_lds_dwordx4 v[148:149], off
	v_lshl_add_u64 v[148:149], v[224:225], 0, s[6:7]
	s_mov_b32 m0, s64
	s_nop 0
	global_load_lds_dwordx4 v[148:149], off
	s_waitcnt vmcnt(8)
	s_waitcnt lgkmcnt(0)
	s_barrier
	s_waitcnt lgkmcnt(0)
	v_mfma_f32_16x16x32_bf16 v[52:55], v[144:147], v[188:191], v[52:55]
	v_mfma_f32_16x16x32_bf16 v[48:51], v[160:163], v[188:191], v[48:51]
	v_mfma_f32_16x16x32_bf16 v[36:39], v[144:147], v[196:199], v[36:39]
	v_mfma_f32_16x16x32_bf16 v[32:35], v[160:163], v[196:199], v[32:35]
	v_mfma_f32_16x16x32_bf16 v[20:23], v[144:147], v[204:207], v[20:23]
	v_mfma_f32_16x16x32_bf16 v[16:19], v[160:163], v[204:207], v[16:19]
	v_mfma_f32_16x16x32_bf16 v[4:7], v[144:147], v[212:215], v[4:7]
	v_mfma_f32_16x16x32_bf16 v[0:3], v[160:163], v[212:215], v[0:3]
	v_mfma_f32_16x16x32_bf16 v[52:55], v[156:159], v[192:195], v[52:55]
	v_mfma_f32_16x16x32_bf16 v[48:51], v[164:167], v[192:195], v[48:51]
	v_mfma_f32_16x16x32_bf16 v[36:39], v[156:159], v[200:203], v[36:39]
	v_mfma_f32_16x16x32_bf16 v[32:35], v[164:167], v[200:203], v[32:35]
	v_mfma_f32_16x16x32_bf16 v[20:23], v[156:159], v[208:211], v[20:23]
	v_mfma_f32_16x16x32_bf16 v[16:19], v[164:167], v[208:211], v[16:19]
	v_mfma_f32_16x16x32_bf16 v[4:7], v[156:159], v[216:219], v[4:7]
	v_mfma_f32_16x16x32_bf16 v[0:3], v[164:167], v[216:219], v[0:3]
	v_mfma_f32_16x16x32_bf16 v[60:63], v[168:171], v[188:191], v[60:63]
	v_mfma_f32_16x16x32_bf16 v[56:59], v[176:179], v[188:191], v[56:59]
	v_mfma_f32_16x16x32_bf16 v[44:47], v[168:171], v[196:199], v[44:47]
	v_mfma_f32_16x16x32_bf16 v[40:43], v[176:179], v[196:199], v[40:43]
	v_mfma_f32_16x16x32_bf16 v[28:31], v[168:171], v[204:207], v[28:31]
	v_mfma_f32_16x16x32_bf16 v[24:27], v[176:179], v[204:207], v[24:27]
	v_mfma_f32_16x16x32_bf16 v[12:15], v[168:171], v[212:215], v[12:15]
	v_mfma_f32_16x16x32_bf16 v[8:11], v[176:179], v[212:215], v[8:11]
	v_mfma_f32_16x16x32_bf16 v[60:63], v[172:175], v[192:195], v[60:63]
	v_mfma_f32_16x16x32_bf16 v[56:59], v[184:187], v[192:195], v[56:59]
	v_mfma_f32_16x16x32_bf16 v[44:47], v[172:175], v[200:203], v[44:47]
	v_mfma_f32_16x16x32_bf16 v[40:43], v[184:187], v[200:203], v[40:43]
	v_mfma_f32_16x16x32_bf16 v[28:31], v[172:175], v[208:211], v[28:31]
	v_mfma_f32_16x16x32_bf16 v[24:27], v[184:187], v[208:211], v[24:27]
	v_mfma_f32_16x16x32_bf16 v[12:15], v[172:175], v[216:219], v[12:15]
	v_mfma_f32_16x16x32_bf16 v[8:11], v[184:187], v[216:219], v[8:11]
	s_barrier
	s_add_i32 s72, s72, 2
	s_add_u32 s56, s56, 0x100
	s_addc_u32 s57, s57, 0
	s_add_u32 s70, s70, 0x100
	s_addc_u32 s71, s71, 0
	s_cmp_gt_u32 s72, 13
	s_cbranch_scc0 .LBB0_1624
	s_and_b64 vcc, exec, s[8:9]
	s_cbranch_vccz .LBB0_1627
	s_barrier

; #define PG8_STAGE(bufoff, gbase, voff) do { _Pragma("unroll") for (int _i = 0; _i < 2; ++_i) \
;         __builtin_amdgcn_global_load_lds((const unsigned*)((const char*)(gbase) + (voff)[_i]), (LAS unsigned*)(lds + (bufoff) + ldsw + _i * 8192), 16, 0, 0); } while (0)
; #define PG8_LDA(dst, b, h) do { _Pragma("unroll") for (int m = 0; m < 4; ++m) _Pragma("unroll") for (int k = 0; k < 2; ++k) dst[m][k] = *(const LAS bf16x8*)(lds + PG8_SA(b, h) + aoff + m * 2048 + k * 1024); } while (0)
; #define PG8_LDB(dst, b, h) do { _Pragma("unroll") for (int n = 0; n < 2; ++n) _Pragma("unroll") for (int k = 0; k < 2; ++k) dst[n][k] = *(const LAS bf16x8*)(lds + PG8_SB(b, h) + boff + n * 2048 + k * 1024); } while (0)
; #define PG8_MMA(ai, bj, At, Bt) do { __builtin_amdgcn_s_setprio(1); _Pragma("unroll") for (int m = 0; m < 4; ++m) _Pragma("unroll") for (int n = 0; n < 2; ++n) _Pragma("unroll") for (int k = 0; k < 2; ++k) \
;         acc[ai][bj][m][n] = __builtin_amdgcn_mfma_f32_16x16x32_bf16(Bt[n][k], At[m][k], acc[ai][bj][m][n], 0, 0, 0); __builtin_amdgcn_s_setprio(0); } while (0)
; #define PG8_WAIT_V(n) asm volatile("s_waitcnt vmcnt(" #n ")" ::: "memory")
; #define PG8_WAIT_L(n) asm volatile("s_waitcnt lgkmcnt(" #n ")" ::: "memory")
; #define PG8_BAR __builtin_amdgcn_s_barrier()
; #define PG8_SCHED __builtin_amdgcn_sched_barrier(0)
; template <bool LT, class Epi>
; __device__ __forceinline__ void gemm_phase(LAS unsigned char* lds, const Gemm g, const StaticOrder& S, const Epi& E) {
;     ...
;             const bool last = (t == nt - 2);
;             const char* a1 = cA + (size_t)(t + 1) * kstep;
;             const char* a2 = last ? nA : cA + (size_t)(t + 2) * kstep; const char* b2 = last ? nB : cB + (size_t)(t + 2) * kstep;
;             const char* a3 = a2 + kstep; const char* b3 = b2 + kstep;
;             PG8_LDB(B0, 0, 0); PG8_LDB(B1, 0, 1); PG8_SCHED; PG8_LDA(At, 0, 0); PG8_STAGE(PG8_SA(1, 1), a1 + hstepA, voffA);
;             PG8_WAIT_V(8); PG8_WAIT_L(0); PG8_BAR; PG8_MMA(0, 0, At, B0); PG8_MMA(0, 1, At, B1); PG8_BAR; PG8_SCHED;
;             PG8_LDA(At, 0, 1); PG8_STAGE(PG8_SB(0, 0), b2, voffB); PG8_STAGE(PG8_SB(0, 1), b2 + hstepB, voffB); PG8_STAGE(PG8_SA(0, 0), a2, voffA);
.LBB0_1700:
	ds_read_b128 v[144:147], v153
	ds_read_b128 v[156:159], v153 offset:1024
	ds_read_b128 v[160:163], v153 offset:2048
	ds_read_b128 v[164:167], v153 offset:3072
	ds_read_b128 v[168:171], v154
	ds_read_b128 v[172:175], v154 offset:1024
	ds_read_b128 v[176:179], v154 offset:2048
	ds_read_b128 v[184:187], v154 offset:3072
	s_add_u32 s52, s62, 0xfffc0080
	s_addc_u32 s53, s63, -1
	s_cmp_eq_u32 s78, 12
	s_cselect_b32 s67, s42, s53
	s_cselect_b32 s66, s43, s52
	s_cselect_b32 s65, s51, s77
	s_cselect_b32 s64, s55, s76
	v_lshl_add_u64 v[148:149], s[62:63], 0, v[136:137]
	s_add_i32 m0, s19, 0xc000
	ds_read_b128 v[188:191], v155
	ds_read_b128 v[192:195], v155 offset:1024
	ds_read_b128 v[196:199], v155 offset:2048
	ds_read_b128 v[200:203], v155 offset:3072
	ds_read_b128 v[204:207], v155 offset:4096
	ds_read_b128 v[208:211], v155 offset:5120
	ds_read_b128 v[212:215], v155 offset:6144
	ds_read_b128 v[216:219], v155 offset:7168
	global_load_lds_dwordx4 v[148:149], off
	v_lshl_add_u64 v[148:149], s[62:63], 0, v[138:139]
	s_add_i32 m0, s19, 0xe000
	s_nop 0
	global_load_lds_dwordx4 v[148:149], off
	s_waitcnt vmcnt(8)
	s_waitcnt lgkmcnt(0)
	s_barrier
	s_waitcnt lgkmcnt(0)
	v_mfma_f32_16x16x32_bf16 v[124:127], v[144:147], v[188:191], v[124:127]
	v_mfma_f32_16x16x32_bf16 v[120:123], v[160:163], v[188:191], v[120:123]
	v_mfma_f32_16x16x32_bf16 v[108:111], v[144:147], v[196:199], v[108:111]
	v_mfma_f32_16x16x32_bf16 v[104:107], v[160:163], v[196:199], v[104:107]
	v_mfma_f32_16x16x32_bf16 v[92:95], v[144:147], v[204:207], v[92:95]
	v_mfma_f32_16x16x32_bf16 v[88:91], v[160:163], v[204:207], v[88:91]
	v_mfma_f32_16x16x32_bf16 v[76:79], v[144:147], v[212:215], v[76:79]
	v_mfma_f32_16x16x32_bf16 v[72:75], v[160:163], v[212:215], v[72:75]
	v_mfma_f32_16x16x32_bf16 v[124:127], v[156:159], v[192:195], v[124:127]
	v_mfma_f32_16x16x32_bf16 v[120:123], v[164:167], v[192:195], v[120:123]
	v_mfma_f32_16x16x32_bf16 v[108:111], v[156:159], v[200:203], v[108:111]
	v_mfma_f32_16x16x32_bf16 v[104:107], v[164:167], v[200:203], v[104:107]
	v_mfma_f32_16x16x32_bf16 v[92:95], v[156:159], v[208:211], v[92:95]
	v_mfma_f32_16x16x32_bf16 v[88:91], v[164:167], v[208:211], v[88:91]
	v_mfma_f32_16x16x32_bf16 v[76:79], v[156:159], v[216:219], v[76:79]
	v_mfma_f32_16x16x32_bf16 v[72:75], v[164:167], v[216:219], v[72:75]
	v_mfma_f32_16x16x32_bf16 v[116:119], v[168:171], v[188:191], v[116:119]
	v_mfma_f32_16x16x32_bf16 v[112:115], v[176:179], v[188:191], v[112:115]
	v_mfma_f32_16x16x32_bf16 v[100:103], v[168:171], v[196:199], v[100:103]
	v_mfma_f32_16x16x32_bf16 v[96:99], v[176:179], v[196:199], v[96:99]
	v_mfma_f32_16x16x32_bf16 v[84:87], v[168:171], v[204:207], v[84:87]
	v_mfma_f32_16x16x32_bf16 v[80:83], v[176:179], v[204:207], v[80:83]
	v_mfma_f32_16x16x32_bf16 v[68:71], v[168:171], v[212:215], v[68:71]
	v_mfma_f32_16x16x32_bf16 v[64:67], v[176:179], v[212:215], v[64:67]
	v_mfma_f32_16x16x32_bf16 v[116:119], v[172:175], v[192:195], v[116:119]
	v_mfma_f32_16x16x32_bf16 v[112:115], v[184:187], v[192:195], v[112:115]
	v_mfma_f32_16x16x32_bf16 v[100:103], v[172:175], v[200:203], v[100:103]
	v_mfma_f32_16x16x32_bf16 v[96:99], v[184:187], v[200:203], v[96:99]
	v_mfma_f32_16x16x32_bf16 v[84:87], v[172:175], v[208:211], v[84:87]
	v_mfma_f32_16x16x32_bf16 v[80:83], v[184:187], v[208:211], v[80:83]
	v_mfma_f32_16x16x32_bf16 v[68:71], v[172:175], v[216:219], v[68:71]
	v_mfma_f32_16x16x32_bf16 v[64:67], v[184:187], v[216:219], v[64:67]
	s_barrier
	s_add_i32 s52, s73, s18
	v_lshl_add_u64 v[148:149], s[64:65], 0, v[130:131]
	s_mov_b32 m0, s52
	ds_read_b128 v[188:191], v155 offset:16384
	ds_read_b128 v[192:195], v155 offset:17408
	ds_read_b128 v[196:199], v155 offset:18432
	ds_read_b128 v[200:203], v155 offset:19456
	ds_read_b128 v[204:207], v155 offset:20480
	ds_read_b128 v[208:211], v155 offset:21504
	ds_read_b128 v[212:215], v155 offset:22528
	ds_read_b128 v[216:219], v155 offset:23552
	global_load_lds_dwordx4 v[148:149], off
	s_add_i32 m0, s52, 0x2000
	s_add_u32 s52, s64, 0x40000
	v_lshl_add_u64 v[220:221], s[64:65], 0, v[134:135]
	s_addc_u32 s53, s65, 0
	s_add_i32 s79, s74, s18
	global_load_lds_dwordx4 v[220:221], off
	v_lshl_add_u64 v[222:223], s[52:53], 0, v[130:131]
	s_mov_b32 m0, s79
	v_lshl_add_u64 v[224:225], s[66:67], 0, v[132:133]
	global_load_lds_dwordx4 v[222:223], off
	v_lshl_add_u64 v[222:223], s[52:53], 0, v[134:135]
	s_add_i32 m0, s79, 0x2000
	s_nop 0
	global_load_lds_dwordx4 v[222:223], off
	v_lshl_add_u64 v[222:223], s[66:67], 0, v[128:129]
	s_mov_b32 m0, s19
	s_nop 0
	global_load_lds_dwordx4 v[222:223], off
	s_mov_b32 m0, s27
	s_nop 0
	global_load_lds_dwordx4 v[224:225], off
	s_waitcnt vmcnt(8)
	s_waitcnt lgkmcnt(0)
	s_barrier
; #define PG8_STAGE(bufoff, gbase, voff) do { _Pragma("unroll") for (int _i = 0; _i < 2; ++_i) \
;         __builtin_amdgcn_global_load_lds((const unsigned*)((const char*)(gbase) + (voff)[_i]), (LAS unsigned*)(lds + (bufoff) + ldsw + _i * 8192), 16, 0, 0); } while (0)
; #define PG8_LDA(dst, b, h) do { _Pragma("unroll") for (int m = 0; m < 4; ++m) _Pragma("unroll") for (int k = 0; k < 2; ++k) dst[m][k] = *(const LAS bf16x8*)(lds + PG8_SA(b, h) + aoff + m * 2048 + k * 1024); } while (0)
; #define PG8_LDB(dst, b, h) do { _Pragma("unroll") for (int n = 0; n < 2; ++n) _Pragma("unroll") for (int k = 0; k < 2; ++k) dst[n][k] = *(const LAS bf16x8*)(lds + PG8_SB(b, h) + boff + n * 2048 + k * 1024); } while (0)
; #define PG8_MMA(ai, bj, At, Bt) do { __builtin_amdgcn_s_setprio(1); _Pragma("unroll") for (int m = 0; m < 4; ++m) _Pragma("unroll") for (int n = 0; n < 2; ++n) _Pragma("unroll") for (int k = 0; k < 2; ++k) \
;         acc[ai][bj][m][n] = __builtin_amdgcn_mfma_f32_16x16x32_bf16(Bt[n][k], At[m][k], acc[ai][bj][m][n], 0, 0, 0); __builtin_amdgcn_s_setprio(0); } while (0)
; #define PG8_WAIT_V(n) asm volatile("s_waitcnt vmcnt(" #n ")" ::: "memory")
; #define PG8_WAIT_L(n) asm volatile("s_waitcnt lgkmcnt(" #n ")" ::: "memory")
; #define PG8_BAR __builtin_amdgcn_s_barrier()
; #define PG8_SCHED __builtin_amdgcn_sched_barrier(0)
; template <bool LT, class Epi>
; __device__ __forceinline__ void gemm_phase(LAS unsigned char* lds, const Gemm g, const StaticOrder& S, const Epi& E) {
;     ...
;             PG8_WAIT_V(8); PG8_WAIT_L(0); PG8_BAR; PG8_MMA(1, 0, At, B0); PG8_MMA(1, 1, At, B1); PG8_BAR; PG8_SCHED;
;             PG8_LDB(B0, 1, 0); PG8_LDB(B1, 1, 1); PG8_SCHED; PG8_LDA(At, 1, 0); PG8_STAGE(PG8_SA(0, 1), a2 + hstepA, voffA);
;             PG8_WAIT_V(8); PG8_WAIT_L(0); PG8_BAR; PG8_MMA(0, 0, At, B0); PG8_MMA(0, 1, At, B1); PG8_BAR; PG8_SCHED;
	s_waitcnt lgkmcnt(0)
	v_mfma_f32_16x16x32_bf16 v[60:63], v[144:147], v[188:191], v[60:63]
	v_mfma_f32_16x16x32_bf16 v[56:59], v[160:163], v[188:191], v[56:59]
	v_mfma_f32_16x16x32_bf16 v[44:47], v[144:147], v[196:199], v[44:47]
	v_mfma_f32_16x16x32_bf16 v[40:43], v[160:163], v[196:199], v[40:43]
	v_mfma_f32_16x16x32_bf16 v[28:31], v[144:147], v[204:207], v[28:31]
	v_mfma_f32_16x16x32_bf16 v[24:27], v[160:163], v[204:207], v[24:27]
	v_mfma_f32_16x16x32_bf16 v[12:15], v[144:147], v[212:215], v[12:15]
	v_mfma_f32_16x16x32_bf16 v[8:11], v[160:163], v[212:215], v[8:11]
	v_mfma_f32_16x16x32_bf16 v[60:63], v[156:159], v[192:195], v[60:63]
	v_mfma_f32_16x16x32_bf16 v[56:59], v[164:167], v[192:195], v[56:59]
	v_mfma_f32_16x16x32_bf16 v[44:47], v[156:159], v[200:203], v[44:47]
	v_mfma_f32_16x16x32_bf16 v[40:43], v[164:167], v[200:203], v[40:43]
	v_mfma_f32_16x16x32_bf16 v[28:31], v[156:159], v[208:211], v[28:31]
	v_mfma_f32_16x16x32_bf16 v[24:27], v[164:167], v[208:211], v[24:27]
	v_mfma_f32_16x16x32_bf16 v[12:15], v[156:159], v[216:219], v[12:15]
	v_mfma_f32_16x16x32_bf16 v[8:11], v[164:167], v[216:219], v[8:11]
	v_mfma_f32_16x16x32_bf16 v[52:55], v[168:171], v[188:191], v[52:55]
	v_mfma_f32_16x16x32_bf16 v[48:51], v[176:179], v[188:191], v[48:51]
	v_mfma_f32_16x16x32_bf16 v[36:39], v[168:171], v[196:199], v[36:39]
	v_mfma_f32_16x16x32_bf16 v[32:35], v[176:179], v[196:199], v[32:35]
	v_mfma_f32_16x16x32_bf16 v[20:23], v[168:171], v[204:207], v[20:23]
	v_mfma_f32_16x16x32_bf16 v[16:19], v[176:179], v[204:207], v[16:19]
	v_mfma_f32_16x16x32_bf16 v[4:7], v[168:171], v[212:215], v[4:7]
	v_mfma_f32_16x16x32_bf16 v[0:3], v[176:179], v[212:215], v[0:3]
	v_mfma_f32_16x16x32_bf16 v[52:55], v[172:175], v[192:195], v[52:55]
	v_mfma_f32_16x16x32_bf16 v[48:51], v[184:187], v[192:195], v[48:51]
	v_mfma_f32_16x16x32_bf16 v[36:39], v[172:175], v[200:203], v[36:39]
	v_mfma_f32_16x16x32_bf16 v[32:35], v[184:187], v[200:203], v[32:35]
	v_mfma_f32_16x16x32_bf16 v[20:23], v[172:175], v[208:211], v[20:23]
	v_mfma_f32_16x16x32_bf16 v[16:19], v[184:187], v[208:211], v[16:19]
	v_mfma_f32_16x16x32_bf16 v[4:7], v[172:175], v[216:219], v[4:7]
	v_mfma_f32_16x16x32_bf16 v[0:3], v[184:187], v[216:219], v[0:3]
	s_barrier
	s_add_i32 s79, 0, 0x18000
	s_add_i32 s80, 0, 0x1c000
	v_add_u32_e32 v164, s79, v151
	v_add_u32_e32 v183, s80, v151
	ds_read_b128 v[144:147], v164
	ds_read_b128 v[156:159], v164 offset:1024
	ds_read_b128 v[160:163], v164 offset:2048
	ds_read_b128 v[164:167], v164 offset:3072
	ds_read_b128 v[168:171], v183
	ds_read_b128 v[172:175], v183 offset:1024
	ds_read_b128 v[176:179], v183 offset:2048
	ds_read_b128 v[184:187], v183 offset:3072
	s_add_u32 s52, s66, 0x40000
	s_addc_u32 s53, s67, 0
	s_mov_b32 m0, s33
	v_lshl_add_u64 v[226:227], s[52:53], 0, v[128:129]
	ds_read_b128 v[188:191], v155 offset:32768
	ds_read_b128 v[192:195], v155 offset:33792
	ds_read_b128 v[196:199], v155 offset:34816
	ds_read_b128 v[200:203], v155 offset:35840
	ds_read_b128 v[204:207], v155 offset:36864
	ds_read_b128 v[208:211], v155 offset:37888
	ds_read_b128 v[212:215], v155 offset:38912
	ds_read_b128 v[216:219], v155 offset:39936
	global_load_lds_dwordx4 v[226:227], off
	v_lshl_add_u64 v[226:227], s[52:53], 0, v[132:133]
	s_mov_b32 m0, s61
	s_nop 0
	global_load_lds_dwordx4 v[226:227], off
	s_waitcnt vmcnt(8)
	s_waitcnt lgkmcnt(0)
	s_barrier
	s_waitcnt lgkmcnt(0)
	v_mfma_f32_16x16x32_bf16 v[124:127], v[144:147], v[188:191], v[124:127]
	v_mfma_f32_16x16x32_bf16 v[120:123], v[160:163], v[188:191], v[120:123]
	v_mfma_f32_16x16x32_bf16 v[108:111], v[144:147], v[196:199], v[108:111]
	v_mfma_f32_16x16x32_bf16 v[104:107], v[160:163], v[196:199], v[104:107]
	v_mfma_f32_16x16x32_bf16 v[92:95], v[144:147], v[204:207], v[92:95]
	v_mfma_f32_16x16x32_bf16 v[88:91], v[160:163], v[204:207], v[88:91]
	v_mfma_f32_16x16x32_bf16 v[76:79], v[144:147], v[212:215], v[76:79]
	v_mfma_f32_16x16x32_bf16 v[72:75], v[160:163], v[212:215], v[72:75]
	v_mfma_f32_16x16x32_bf16 v[124:127], v[156:159], v[192:195], v[124:127]
	v_mfma_f32_16x16x32_bf16 v[120:123], v[164:167], v[192:195], v[120:123]
	v_mfma_f32_16x16x32_bf16 v[108:111], v[156:159], v[200:203], v[108:111]
	v_mfma_f32_16x16x32_bf16 v[104:107], v[164:167], v[200:203], v[104:107]
	v_mfma_f32_16x16x32_bf16 v[92:95], v[156:159], v[208:211], v[92:95]
	v_mfma_f32_16x16x32_bf16 v[88:91], v[164:167], v[208:211], v[88:91]
	v_mfma_f32_16x16x32_bf16 v[76:79], v[156:159], v[216:219], v[76:79]
	v_mfma_f32_16x16x32_bf16 v[72:75], v[164:167], v[216:219], v[72:75]
	v_mfma_f32_16x16x32_bf16 v[116:119], v[168:171], v[188:191], v[116:119]
	v_mfma_f32_16x16x32_bf16 v[112:115], v[176:179], v[188:191], v[112:115]
	v_mfma_f32_16x16x32_bf16 v[100:103], v[168:171], v[196:199], v[100:103]
	v_mfma_f32_16x16x32_bf16 v[96:99], v[176:179], v[196:199], v[96:99]
	v_mfma_f32_16x16x32_bf16 v[84:87], v[168:171], v[204:207], v[84:87]
	v_mfma_f32_16x16x32_bf16 v[80:83], v[176:179], v[204:207], v[80:83]
	v_mfma_f32_16x16x32_bf16 v[68:71], v[168:171], v[212:215], v[68:71]
	v_mfma_f32_16x16x32_bf16 v[64:67], v[176:179], v[212:215], v[64:67]
	v_mfma_f32_16x16x32_bf16 v[116:119], v[172:175], v[192:195], v[116:119]
	v_mfma_f32_16x16x32_bf16 v[112:115], v[184:187], v[192:195], v[112:115]
	v_mfma_f32_16x16x32_bf16 v[100:103], v[172:175], v[200:203], v[100:103]
	v_mfma_f32_16x16x32_bf16 v[96:99], v[184:187], v[200:203], v[96:99]
	v_mfma_f32_16x16x32_bf16 v[84:87], v[172:175], v[208:211], v[84:87]
	v_mfma_f32_16x16x32_bf16 v[80:83], v[184:187], v[208:211], v[80:83]
	v_mfma_f32_16x16x32_bf16 v[68:71], v[172:175], v[216:219], v[68:71]
	v_mfma_f32_16x16x32_bf16 v[64:67], v[184:187], v[216:219], v[64:67]
	s_barrier
; #define PG8_STAGE(bufoff, gbase, voff) do { _Pragma("unroll") for (int _i = 0; _i < 2; ++_i) \
;         __builtin_amdgcn_global_load_lds((const unsigned*)((const char*)(gbase) + (voff)[_i]), (LAS unsigned*)(lds + (bufoff) + ldsw + _i * 8192), 16, 0, 0); } while (0)
; #define PG8_LDA(dst, b, h) do { _Pragma("unroll") for (int m = 0; m < 4; ++m) _Pragma("unroll") for (int k = 0; k < 2; ++k) dst[m][k] = *(const LAS bf16x8*)(lds + PG8_SA(b, h) + aoff + m * 2048 + k * 1024); } while (0)
; #define PG8_MMA(ai, bj, At, Bt) do { __builtin_amdgcn_s_setprio(1); _Pragma("unroll") for (int m = 0; m < 4; ++m) _Pragma("unroll") for (int n = 0; n < 2; ++n) _Pragma("unroll") for (int k = 0; k < 2; ++k) \
;         acc[ai][bj][m][n] = __builtin_amdgcn_mfma_f32_16x16x32_bf16(Bt[n][k], At[m][k], acc[ai][bj][m][n], 0, 0, 0); __builtin_amdgcn_s_setprio(0); } while (0)
; #define PG8_WAIT_V(n) asm volatile("s_waitcnt vmcnt(" #n ")" ::: "memory")
; #define PG8_WAIT_L(n) asm volatile("s_waitcnt lgkmcnt(" #n ")" ::: "memory")
; #define PG8_BAR __builtin_amdgcn_s_barrier()
; #define PG8_SCHED __builtin_amdgcn_sched_barrier(0)
; template <bool LT, class Epi>
; __device__ __forceinline__ void gemm_phase(LAS unsigned char* lds, const Gemm g, const StaticOrder& S, const Epi& E) {
;     ...
;         for (int t = 0; t < nt; t += 2) {
;     ...
;             PG8_LDA(At, 1, 1); PG8_STAGE(PG8_SB(1, 0), b3, voffB); PG8_STAGE(PG8_SB(1, 1), b3 + hstepB, voffB); PG8_STAGE(PG8_SA(1, 0), a3, voffA);
;             PG8_WAIT_V(8); PG8_WAIT_L(0); PG8_BAR; PG8_MMA(1, 0, At, B0); PG8_MMA(1, 1, At, B1); PG8_BAR; PG8_SCHED;
	s_add_i32 s52, s79, s18
	v_lshl_add_u64 v[148:149], v[148:149], 0, s[6:7]
	s_mov_b32 m0, s52
	ds_read_b128 v[188:191], v155 offset:49152
	ds_read_b128 v[192:195], v155 offset:50176
	ds_read_b128 v[196:199], v155 offset:51200
	ds_read_b128 v[200:203], v155 offset:52224
	ds_read_b128 v[204:207], v155 offset:53248
	ds_read_b128 v[208:211], v155 offset:54272
	ds_read_b128 v[212:215], v155 offset:55296
	ds_read_b128 v[216:219], v155 offset:56320
	global_load_lds_dwordx4 v[148:149], off
	s_add_i32 m0, s52, 0x2000
	s_add_u32 s52, s64, 0x40080
	v_lshl_add_u64 v[148:149], v[220:221], 0, s[6:7]
	s_addc_u32 s53, s65, 0
	s_add_i32 s64, s80, s18
	global_load_lds_dwordx4 v[148:149], off
	v_lshl_add_u64 v[148:149], s[52:53], 0, v[130:131]
	s_mov_b32 m0, s64
	s_nop 0
	global_load_lds_dwordx4 v[148:149], off
	v_lshl_add_u64 v[148:149], s[52:53], 0, v[134:135]
	s_add_i32 m0, s64, 0x2000
	s_nop 0
	global_load_lds_dwordx4 v[148:149], off
	v_lshl_add_u64 v[148:149], v[222:223], 0, s[6:7]
	s_mov_b32 m0, s69
	s_nop 0
	global_load_lds_dwordx4 v[148:149], off
	v_lshl_add_u64 v[148:149], v[224:225], 0, s[6:7]
	s_mov_b32 m0, s70
	s_nop 0
	global_load_lds_dwordx4 v[148:149], off
	s_waitcnt vmcnt(8)
	s_waitcnt lgkmcnt(0)
	s_barrier
	s_waitcnt lgkmcnt(0)
	v_mfma_f32_16x16x32_bf16 v[60:63], v[144:147], v[188:191], v[60:63]
	v_mfma_f32_16x16x32_bf16 v[56:59], v[160:163], v[188:191], v[56:59]
	v_mfma_f32_16x16x32_bf16 v[44:47], v[144:147], v[196:199], v[44:47]
	v_mfma_f32_16x16x32_bf16 v[40:43], v[160:163], v[196:199], v[40:43]
	v_mfma_f32_16x16x32_bf16 v[28:31], v[144:147], v[204:207], v[28:31]
	v_mfma_f32_16x16x32_bf16 v[24:27], v[160:163], v[204:207], v[24:27]
	v_mfma_f32_16x16x32_bf16 v[12:15], v[144:147], v[212:215], v[12:15]
	v_mfma_f32_16x16x32_bf16 v[8:11], v[160:163], v[212:215], v[8:11]
	v_mfma_f32_16x16x32_bf16 v[60:63], v[156:159], v[192:195], v[60:63]
	v_mfma_f32_16x16x32_bf16 v[56:59], v[164:167], v[192:195], v[56:59]
	v_mfma_f32_16x16x32_bf16 v[44:47], v[156:159], v[200:203], v[44:47]
	v_mfma_f32_16x16x32_bf16 v[40:43], v[164:167], v[200:203], v[40:43]
	v_mfma_f32_16x16x32_bf16 v[28:31], v[156:159], v[208:211], v[28:31]
	v_mfma_f32_16x16x32_bf16 v[24:27], v[164:167], v[208:211], v[24:27]
	v_mfma_f32_16x16x32_bf16 v[12:15], v[156:159], v[216:219], v[12:15]
	v_mfma_f32_16x16x32_bf16 v[8:11], v[164:167], v[216:219], v[8:11]
	v_mfma_f32_16x16x32_bf16 v[52:55], v[168:171], v[188:191], v[52:55]
	v_mfma_f32_16x16x32_bf16 v[48:51], v[176:179], v[188:191], v[48:51]
	v_mfma_f32_16x16x32_bf16 v[36:39], v[168:171], v[196:199], v[36:39]
	v_mfma_f32_16x16x32_bf16 v[32:35], v[176:179], v[196:199], v[32:35]
	v_mfma_f32_16x16x32_bf16 v[20:23], v[168:171], v[204:207], v[20:23]
	v_mfma_f32_16x16x32_bf16 v[16:19], v[176:179], v[204:207], v[16:19]
	v_mfma_f32_16x16x32_bf16 v[4:7], v[168:171], v[212:215], v[4:7]
	v_mfma_f32_16x16x32_bf16 v[0:3], v[176:179], v[212:215], v[0:3]
	v_mfma_f32_16x16x32_bf16 v[52:55], v[172:175], v[192:195], v[52:55]
	v_mfma_f32_16x16x32_bf16 v[48:51], v[184:187], v[192:195], v[48:51]
	v_mfma_f32_16x16x32_bf16 v[36:39], v[172:175], v[200:203], v[36:39]
	v_mfma_f32_16x16x32_bf16 v[32:35], v[184:187], v[200:203], v[32:35]
	v_mfma_f32_16x16x32_bf16 v[20:23], v[172:175], v[208:211], v[20:23]
	v_mfma_f32_16x16x32_bf16 v[16:19], v[184:187], v[208:211], v[16:19]
	v_mfma_f32_16x16x32_bf16 v[4:7], v[172:175], v[216:219], v[4:7]
	v_mfma_f32_16x16x32_bf16 v[0:3], v[184:187], v[216:219], v[0:3]
	s_barrier
	s_add_i32 s78, s78, 2
	s_add_u32 s62, s62, 0x100
	s_addc_u32 s63, s63, 0
	s_add_u32 s76, s76, 0x100
	s_addc_u32 s77, s77, 0
	s_cmp_gt_u32 s78, 13
	s_cbranch_scc0 .LBB0_1700
	s_and_b64 vcc, exec, s[8:9]
	s_cbranch_vccz .LBB0_1703
	s_barrier

; #define PG8_STAGE(bufoff, gbase, voff) do { _Pragma("unroll") for (int _i = 0; _i < 2; ++_i) \
;         __builtin_amdgcn_global_load_lds((const unsigned*)((const char*)(gbase) + (voff)[_i]), (LAS unsigned*)(lds + (bufoff) + ldsw + _i * 8192), 16, 0, 0); } while (0)
; #define PG8_LDA(dst, b, h) do { _Pragma("unroll") for (int m = 0; m < 4; ++m) _Pragma("unroll") for (int k = 0; k < 2; ++k) dst[m][k] = *(const LAS bf16x8*)(lds + PG8_SA(b, h) + aoff + m * 2048 + k * 1024); } while (0)
; #define PG8_LDB(dst, b, h) do { _Pragma("unroll") for (int n = 0; n < 2; ++n) _Pragma("unroll") for (int k = 0; k < 2; ++k) dst[n][k] = *(const LAS bf16x8*)(lds + PG8_SB(b, h) + boff + n * 2048 + k * 1024); } while (0)
; #define PG8_MMA(ai, bj, At, Bt) do { __builtin_amdgcn_s_setprio(1); _Pragma("unroll") for (int m = 0; m < 4; ++m) _Pragma("unroll") for (int n = 0; n < 2; ++n) _Pragma("unroll") for (int k = 0; k < 2; ++k) \
;         acc[ai][bj][m][n] = __builtin_amdgcn_mfma_f32_16x16x32_bf16(Bt[n][k], At[m][k], acc[ai][bj][m][n], 0, 0, 0); __builtin_amdgcn_s_setprio(0); } while (0)
; #define PG8_WAIT_V(n) asm volatile("s_waitcnt vmcnt(" #n ")" ::: "memory")
; #define PG8_WAIT_L(n) asm volatile("s_waitcnt lgkmcnt(" #n ")" ::: "memory")
; #define PG8_BAR __builtin_amdgcn_s_barrier()
; #define PG8_SCHED __builtin_amdgcn_sched_barrier(0)
; template <bool LT, class Epi>
; __device__ __forceinline__ void gemm_phase(LAS unsigned char* lds, const Gemm g, const StaticOrder& S, const Epi& E) {
;     ...
;             const bool last = (t == nt - 2);
;             const char* a1 = cA + (size_t)(t + 1) * kstep;
;             const char* a2 = last ? nA : cA + (size_t)(t + 2) * kstep; const char* b2 = last ? nB : cB + (size_t)(t + 2) * kstep;
;             const char* a3 = a2 + kstep; const char* b3 = b2 + kstep;
;             PG8_LDB(B0, 0, 0); PG8_LDB(B1, 0, 1); PG8_SCHED; PG8_LDA(At, 0, 0); PG8_STAGE(PG8_SA(1, 1), a1 + hstepA, voffA);
;             PG8_WAIT_V(8); PG8_WAIT_L(0); PG8_BAR; PG8_MMA(0, 0, At, B0); PG8_MMA(0, 1, At, B1); PG8_BAR; PG8_SCHED;
;             PG8_LDA(At, 0, 1); PG8_STAGE(PG8_SB(0, 0), b2, voffB); PG8_STAGE(PG8_SB(0, 1), b2 + hstepB, voffB); PG8_STAGE(PG8_SA(0, 0), a2, voffA);
.LBB0_1776:
	ds_read_b128 v[152:155], v149
	ds_read_b128 v[156:159], v149 offset:1024
	ds_read_b128 v[160:163], v149 offset:2048
	ds_read_b128 v[164:167], v149 offset:3072
	ds_read_b128 v[168:171], v150
	ds_read_b128 v[172:175], v150 offset:1024
	ds_read_b128 v[176:179], v150 offset:2048
	ds_read_b128 v[184:187], v150 offset:3072
	s_add_u32 s54, s52, 0xfff80080
	s_addc_u32 s55, s53, -1
	s_cmp_eq_u32 s72, 28
	s_cselect_b32 s57, s35, s55
	s_cselect_b32 s56, s42, s54
	s_cselect_b32 s55, s25, s71
	s_cselect_b32 s54, s43, s70
	v_lshl_add_u64 v[144:145], s[52:53], 0, v[136:137]
	s_add_i32 m0, s19, 0xc000
	ds_read_b128 v[188:191], v151
	ds_read_b128 v[192:195], v151 offset:1024
	ds_read_b128 v[196:199], v151 offset:2048
	ds_read_b128 v[200:203], v151 offset:3072
	ds_read_b128 v[204:207], v151 offset:4096
	ds_read_b128 v[208:211], v151 offset:5120
	ds_read_b128 v[212:215], v151 offset:6144
	ds_read_b128 v[216:219], v151 offset:7168
	global_load_lds_dwordx4 v[144:145], off
	v_lshl_add_u64 v[144:145], s[52:53], 0, v[138:139]
	s_add_i32 m0, s19, 0xe000
	s_nop 0
	global_load_lds_dwordx4 v[144:145], off
	s_waitcnt vmcnt(8)
	s_waitcnt lgkmcnt(0)
	s_barrier
	s_waitcnt lgkmcnt(0)
	v_mfma_f32_16x16x32_bf16 v[124:127], v[152:155], v[188:191], v[124:127]
	v_mfma_f32_16x16x32_bf16 v[120:123], v[160:163], v[188:191], v[120:123]
	v_mfma_f32_16x16x32_bf16 v[116:119], v[152:155], v[196:199], v[116:119]
	v_mfma_f32_16x16x32_bf16 v[108:111], v[160:163], v[196:199], v[108:111]
	v_mfma_f32_16x16x32_bf16 v[100:103], v[152:155], v[204:207], v[100:103]
	v_mfma_f32_16x16x32_bf16 v[92:95], v[160:163], v[204:207], v[92:95]
	v_mfma_f32_16x16x32_bf16 v[84:87], v[152:155], v[212:215], v[84:87]
	v_mfma_f32_16x16x32_bf16 v[76:79], v[160:163], v[212:215], v[76:79]
	v_mfma_f32_16x16x32_bf16 v[124:127], v[156:159], v[192:195], v[124:127]
	v_mfma_f32_16x16x32_bf16 v[120:123], v[164:167], v[192:195], v[120:123]
	v_mfma_f32_16x16x32_bf16 v[116:119], v[156:159], v[200:203], v[116:119]
	v_mfma_f32_16x16x32_bf16 v[108:111], v[164:167], v[200:203], v[108:111]
	v_mfma_f32_16x16x32_bf16 v[100:103], v[156:159], v[208:211], v[100:103]
	v_mfma_f32_16x16x32_bf16 v[92:95], v[164:167], v[208:211], v[92:95]
	v_mfma_f32_16x16x32_bf16 v[84:87], v[156:159], v[216:219], v[84:87]
	v_mfma_f32_16x16x32_bf16 v[76:79], v[164:167], v[216:219], v[76:79]
	v_mfma_f32_16x16x32_bf16 v[112:115], v[168:171], v[188:191], v[112:115]
	v_mfma_f32_16x16x32_bf16 v[104:107], v[176:179], v[188:191], v[104:107]
	v_mfma_f32_16x16x32_bf16 v[96:99], v[168:171], v[196:199], v[96:99]
	v_mfma_f32_16x16x32_bf16 v[88:91], v[176:179], v[196:199], v[88:91]
	v_mfma_f32_16x16x32_bf16 v[80:83], v[168:171], v[204:207], v[80:83]
	v_mfma_f32_16x16x32_bf16 v[72:75], v[176:179], v[204:207], v[72:75]
	v_mfma_f32_16x16x32_bf16 v[68:71], v[168:171], v[212:215], v[68:71]
	v_mfma_f32_16x16x32_bf16 v[64:67], v[176:179], v[212:215], v[64:67]
	v_mfma_f32_16x16x32_bf16 v[112:115], v[172:175], v[192:195], v[112:115]
	v_mfma_f32_16x16x32_bf16 v[104:107], v[184:187], v[192:195], v[104:107]
	v_mfma_f32_16x16x32_bf16 v[96:99], v[172:175], v[200:203], v[96:99]
	v_mfma_f32_16x16x32_bf16 v[88:91], v[184:187], v[200:203], v[88:91]
	v_mfma_f32_16x16x32_bf16 v[80:83], v[172:175], v[208:211], v[80:83]
	v_mfma_f32_16x16x32_bf16 v[72:75], v[184:187], v[208:211], v[72:75]
	v_mfma_f32_16x16x32_bf16 v[68:71], v[172:175], v[216:219], v[68:71]
	v_mfma_f32_16x16x32_bf16 v[64:67], v[184:187], v[216:219], v[64:67]
	s_barrier
	s_add_i32 s73, s63, s18
	v_lshl_add_u64 v[144:145], s[54:55], 0, v[130:131]
	s_mov_b32 m0, s73
	ds_read_b128 v[188:191], v151 offset:16384
	ds_read_b128 v[192:195], v151 offset:17408
	ds_read_b128 v[196:199], v151 offset:18432
	ds_read_b128 v[200:203], v151 offset:19456
	ds_read_b128 v[204:207], v151 offset:20480
	ds_read_b128 v[208:211], v151 offset:21504
	ds_read_b128 v[212:215], v151 offset:22528
	ds_read_b128 v[216:219], v151 offset:23552
	global_load_lds_dwordx4 v[144:145], off
	s_add_i32 m0, s73, 0x2000
	s_add_u32 s74, s54, 0x80000
	v_lshl_add_u64 v[220:221], s[54:55], 0, v[134:135]
	s_addc_u32 s75, s55, 0
	s_add_i32 s73, s64, s18
	global_load_lds_dwordx4 v[220:221], off
	v_lshl_add_u64 v[222:223], s[74:75], 0, v[130:131]
	s_mov_b32 m0, s73
	v_lshl_add_u64 v[224:225], s[56:57], 0, v[132:133]
	global_load_lds_dwordx4 v[222:223], off
	v_lshl_add_u64 v[222:223], s[74:75], 0, v[134:135]
	s_add_i32 m0, s73, 0x2000
	s_nop 0
	global_load_lds_dwordx4 v[222:223], off
	v_lshl_add_u64 v[222:223], s[56:57], 0, v[128:129]
	s_mov_b32 m0, s19
	s_nop 0
	global_load_lds_dwordx4 v[222:223], off
	s_mov_b32 m0, s27
	s_nop 0
	global_load_lds_dwordx4 v[224:225], off
	s_waitcnt vmcnt(8)
	s_waitcnt lgkmcnt(0)
	s_barrier
; #define PG8_STAGE(bufoff, gbase, voff) do { _Pragma("unroll") for (int _i = 0; _i < 2; ++_i) \
;         __builtin_amdgcn_global_load_lds((const unsigned*)((const char*)(gbase) + (voff)[_i]), (LAS unsigned*)(lds + (bufoff) + ldsw + _i * 8192), 16, 0, 0); } while (0)
; #define PG8_LDA(dst, b, h) do { _Pragma("unroll") for (int m = 0; m < 4; ++m) _Pragma("unroll") for (int k = 0; k < 2; ++k) dst[m][k] = *(const LAS bf16x8*)(lds + PG8_SA(b, h) + aoff + m * 2048 + k * 1024); } while (0)
; #define PG8_LDB(dst, b, h) do { _Pragma("unroll") for (int n = 0; n < 2; ++n) _Pragma("unroll") for (int k = 0; k < 2; ++k) dst[n][k] = *(const LAS bf16x8*)(lds + PG8_SB(b, h) + boff + n * 2048 + k * 1024); } while (0)
; #define PG8_MMA(ai, bj, At, Bt) do { __builtin_amdgcn_s_setprio(1); _Pragma("unroll") for (int m = 0; m < 4; ++m) _Pragma("unroll") for (int n = 0; n < 2; ++n) _Pragma("unroll") for (int k = 0; k < 2; ++k) \
;         acc[ai][bj][m][n] = __builtin_amdgcn_mfma_f32_16x16x32_bf16(Bt[n][k], At[m][k], acc[ai][bj][m][n], 0, 0, 0); __builtin_amdgcn_s_setprio(0); } while (0)
; #define PG8_WAIT_V(n) asm volatile("s_waitcnt vmcnt(" #n ")" ::: "memory")
; #define PG8_WAIT_L(n) asm volatile("s_waitcnt lgkmcnt(" #n ")" ::: "memory")
; #define PG8_BAR __builtin_amdgcn_s_barrier()
; #define PG8_SCHED __builtin_amdgcn_sched_barrier(0)
; template <bool LT, class Epi>
; __device__ __forceinline__ void gemm_phase(LAS unsigned char* lds, const Gemm g, const StaticOrder& S, const Epi& E) {
;     ...
;             PG8_WAIT_V(8); PG8_WAIT_L(0); PG8_BAR; PG8_MMA(1, 0, At, B0); PG8_MMA(1, 1, At, B1); PG8_BAR; PG8_SCHED;
;             PG8_LDB(B0, 1, 0); PG8_LDB(B1, 1, 1); PG8_SCHED; PG8_LDA(At, 1, 0); PG8_STAGE(PG8_SA(0, 1), a2 + hstepA, voffA);
;             PG8_WAIT_V(8); PG8_WAIT_L(0); PG8_BAR; PG8_MMA(0, 0, At, B0); PG8_MMA(0, 1, At, B1); PG8_BAR; PG8_SCHED;
	s_waitcnt lgkmcnt(0)
	v_mfma_f32_16x16x32_bf16 v[60:63], v[152:155], v[188:191], v[60:63]
	v_mfma_f32_16x16x32_bf16 v[56:59], v[160:163], v[188:191], v[56:59]
	v_mfma_f32_16x16x32_bf16 v[52:55], v[152:155], v[196:199], v[52:55]
	v_mfma_f32_16x16x32_bf16 v[44:47], v[160:163], v[196:199], v[44:47]
	v_mfma_f32_16x16x32_bf16 v[36:39], v[152:155], v[204:207], v[36:39]
	v_mfma_f32_16x16x32_bf16 v[28:31], v[160:163], v[204:207], v[28:31]
	v_mfma_f32_16x16x32_bf16 v[20:23], v[152:155], v[212:215], v[20:23]
	v_mfma_f32_16x16x32_bf16 v[12:15], v[160:163], v[212:215], v[12:15]
	v_mfma_f32_16x16x32_bf16 v[60:63], v[156:159], v[192:195], v[60:63]
	v_mfma_f32_16x16x32_bf16 v[56:59], v[164:167], v[192:195], v[56:59]
	v_mfma_f32_16x16x32_bf16 v[52:55], v[156:159], v[200:203], v[52:55]
	v_mfma_f32_16x16x32_bf16 v[44:47], v[164:167], v[200:203], v[44:47]
	v_mfma_f32_16x16x32_bf16 v[36:39], v[156:159], v[208:211], v[36:39]
	v_mfma_f32_16x16x32_bf16 v[28:31], v[164:167], v[208:211], v[28:31]
	v_mfma_f32_16x16x32_bf16 v[20:23], v[156:159], v[216:219], v[20:23]
	v_mfma_f32_16x16x32_bf16 v[12:15], v[164:167], v[216:219], v[12:15]
	v_mfma_f32_16x16x32_bf16 v[48:51], v[168:171], v[188:191], v[48:51]
	v_mfma_f32_16x16x32_bf16 v[40:43], v[176:179], v[188:191], v[40:43]
	v_mfma_f32_16x16x32_bf16 v[32:35], v[168:171], v[196:199], v[32:35]
	v_mfma_f32_16x16x32_bf16 v[24:27], v[176:179], v[196:199], v[24:27]
	v_mfma_f32_16x16x32_bf16 v[16:19], v[168:171], v[204:207], v[16:19]
	v_mfma_f32_16x16x32_bf16 v[8:11], v[176:179], v[204:207], v[8:11]
	v_mfma_f32_16x16x32_bf16 v[4:7], v[168:171], v[212:215], v[4:7]
	v_mfma_f32_16x16x32_bf16 v[0:3], v[176:179], v[212:215], v[0:3]
	v_mfma_f32_16x16x32_bf16 v[48:51], v[172:175], v[192:195], v[48:51]
	v_mfma_f32_16x16x32_bf16 v[40:43], v[184:187], v[192:195], v[40:43]
	v_mfma_f32_16x16x32_bf16 v[32:35], v[172:175], v[200:203], v[32:35]
	v_mfma_f32_16x16x32_bf16 v[24:27], v[184:187], v[200:203], v[24:27]
	v_mfma_f32_16x16x32_bf16 v[16:19], v[172:175], v[208:211], v[16:19]
	v_mfma_f32_16x16x32_bf16 v[8:11], v[184:187], v[208:211], v[8:11]
	v_mfma_f32_16x16x32_bf16 v[4:7], v[172:175], v[216:219], v[4:7]
	v_mfma_f32_16x16x32_bf16 v[0:3], v[184:187], v[216:219], v[0:3]
	s_barrier
	s_add_i32 s73, 0, 0x18000
	s_add_i32 s74, 0, 0x1c000
	v_add_u32_e32 v164, s73, v147
	v_add_u32_e32 v183, s74, v147
	ds_read_b128 v[152:155], v164
	ds_read_b128 v[156:159], v164 offset:1024
	ds_read_b128 v[160:163], v164 offset:2048
	ds_read_b128 v[164:167], v164 offset:3072
	ds_read_b128 v[168:171], v183
	ds_read_b128 v[172:175], v183 offset:1024
	ds_read_b128 v[176:179], v183 offset:2048
	ds_read_b128 v[184:187], v183 offset:3072
	s_add_u32 s56, s56, 0x80000
	s_addc_u32 s57, s57, 0
	s_mov_b32 m0, s33
	v_lshl_add_u64 v[226:227], s[56:57], 0, v[128:129]
	ds_read_b128 v[188:191], v151 offset:32768
	ds_read_b128 v[192:195], v151 offset:33792
	ds_read_b128 v[196:199], v151 offset:34816
	ds_read_b128 v[200:203], v151 offset:35840
	ds_read_b128 v[204:207], v151 offset:36864
	ds_read_b128 v[208:211], v151 offset:37888
	ds_read_b128 v[212:215], v151 offset:38912
	ds_read_b128 v[216:219], v151 offset:39936
	global_load_lds_dwordx4 v[226:227], off
	v_lshl_add_u64 v[226:227], s[56:57], 0, v[132:133]
	s_mov_b32 m0, s51
	s_nop 0
	global_load_lds_dwordx4 v[226:227], off
	s_waitcnt vmcnt(8)
	s_waitcnt lgkmcnt(0)
	s_barrier
	s_waitcnt lgkmcnt(0)
	v_mfma_f32_16x16x32_bf16 v[124:127], v[152:155], v[188:191], v[124:127]
	v_mfma_f32_16x16x32_bf16 v[120:123], v[160:163], v[188:191], v[120:123]
	v_mfma_f32_16x16x32_bf16 v[116:119], v[152:155], v[196:199], v[116:119]
	v_mfma_f32_16x16x32_bf16 v[108:111], v[160:163], v[196:199], v[108:111]
	v_mfma_f32_16x16x32_bf16 v[100:103], v[152:155], v[204:207], v[100:103]
	v_mfma_f32_16x16x32_bf16 v[92:95], v[160:163], v[204:207], v[92:95]
	v_mfma_f32_16x16x32_bf16 v[84:87], v[152:155], v[212:215], v[84:87]
	v_mfma_f32_16x16x32_bf16 v[76:79], v[160:163], v[212:215], v[76:79]
	v_mfma_f32_16x16x32_bf16 v[124:127], v[156:159], v[192:195], v[124:127]
	v_mfma_f32_16x16x32_bf16 v[120:123], v[164:167], v[192:195], v[120:123]
	v_mfma_f32_16x16x32_bf16 v[116:119], v[156:159], v[200:203], v[116:119]
	v_mfma_f32_16x16x32_bf16 v[108:111], v[164:167], v[200:203], v[108:111]
	v_mfma_f32_16x16x32_bf16 v[100:103], v[156:159], v[208:211], v[100:103]
	v_mfma_f32_16x16x32_bf16 v[92:95], v[164:167], v[208:211], v[92:95]
	v_mfma_f32_16x16x32_bf16 v[84:87], v[156:159], v[216:219], v[84:87]
	v_mfma_f32_16x16x32_bf16 v[76:79], v[164:167], v[216:219], v[76:79]
	v_mfma_f32_16x16x32_bf16 v[112:115], v[168:171], v[188:191], v[112:115]
	v_mfma_f32_16x16x32_bf16 v[104:107], v[176:179], v[188:191], v[104:107]
	v_mfma_f32_16x16x32_bf16 v[96:99], v[168:171], v[196:199], v[96:99]
	v_mfma_f32_16x16x32_bf16 v[88:91], v[176:179], v[196:199], v[88:91]
	v_mfma_f32_16x16x32_bf16 v[80:83], v[168:171], v[204:207], v[80:83]
	v_mfma_f32_16x16x32_bf16 v[72:75], v[176:179], v[204:207], v[72:75]
	v_mfma_f32_16x16x32_bf16 v[68:71], v[168:171], v[212:215], v[68:71]
	v_mfma_f32_16x16x32_bf16 v[64:67], v[176:179], v[212:215], v[64:67]
	v_mfma_f32_16x16x32_bf16 v[112:115], v[172:175], v[192:195], v[112:115]
	v_mfma_f32_16x16x32_bf16 v[104:107], v[184:187], v[192:195], v[104:107]
	v_mfma_f32_16x16x32_bf16 v[96:99], v[172:175], v[200:203], v[96:99]
	v_mfma_f32_16x16x32_bf16 v[88:91], v[184:187], v[200:203], v[88:91]
	v_mfma_f32_16x16x32_bf16 v[80:83], v[172:175], v[208:211], v[80:83]
	v_mfma_f32_16x16x32_bf16 v[72:75], v[184:187], v[208:211], v[72:75]
	v_mfma_f32_16x16x32_bf16 v[68:71], v[172:175], v[216:219], v[68:71]
	v_mfma_f32_16x16x32_bf16 v[64:67], v[184:187], v[216:219], v[64:67]
	s_barrier
; #define PG8_STAGE(bufoff, gbase, voff) do { _Pragma("unroll") for (int _i = 0; _i < 2; ++_i) \
;         __builtin_amdgcn_global_load_lds((const unsigned*)((const char*)(gbase) + (voff)[_i]), (LAS unsigned*)(lds + (bufoff) + ldsw + _i * 8192), 16, 0, 0); } while (0)
; #define PG8_LDA(dst, b, h) do { _Pragma("unroll") for (int m = 0; m < 4; ++m) _Pragma("unroll") for (int k = 0; k < 2; ++k) dst[m][k] = *(const LAS bf16x8*)(lds + PG8_SA(b, h) + aoff + m * 2048 + k * 1024); } while (0)
; #define PG8_MMA(ai, bj, At, Bt) do { __builtin_amdgcn_s_setprio(1); _Pragma("unroll") for (int m = 0; m < 4; ++m) _Pragma("unroll") for (int n = 0; n < 2; ++n) _Pragma("unroll") for (int k = 0; k < 2; ++k) \
;         acc[ai][bj][m][n] = __builtin_amdgcn_mfma_f32_16x16x32_bf16(Bt[n][k], At[m][k], acc[ai][bj][m][n], 0, 0, 0); __builtin_amdgcn_s_setprio(0); } while (0)
; #define PG8_WAIT_V(n) asm volatile("s_waitcnt vmcnt(" #n ")" ::: "memory")
; #define PG8_WAIT_L(n) asm volatile("s_waitcnt lgkmcnt(" #n ")" ::: "memory")
; #define PG8_BAR __builtin_amdgcn_s_barrier()
; #define PG8_SCHED __builtin_amdgcn_sched_barrier(0)
; template <bool LT, class Epi>
; __device__ __forceinline__ void gemm_phase(LAS unsigned char* lds, const Gemm g, const StaticOrder& S, const Epi& E) {
;     ...
;         for (int t = 0; t < nt; t += 2) {
;     ...
;             PG8_LDA(At, 1, 1); PG8_STAGE(PG8_SB(1, 0), b3, voffB); PG8_STAGE(PG8_SB(1, 1), b3 + hstepB, voffB); PG8_STAGE(PG8_SA(1, 0), a3, voffA);
;             PG8_WAIT_V(8); PG8_WAIT_L(0); PG8_BAR; PG8_MMA(1, 0, At, B0); PG8_MMA(1, 1, At, B1); PG8_BAR; PG8_SCHED;
	s_add_i32 s56, s73, s18
	v_lshl_add_u64 v[144:145], v[144:145], 0, s[8:9]
	s_mov_b32 m0, s56
	ds_read_b128 v[188:191], v151 offset:49152
	ds_read_b128 v[192:195], v151 offset:50176
	ds_read_b128 v[196:199], v151 offset:51200
	ds_read_b128 v[200:203], v151 offset:52224
	ds_read_b128 v[204:207], v151 offset:53248
	ds_read_b128 v[208:211], v151 offset:54272
	ds_read_b128 v[212:215], v151 offset:55296
	ds_read_b128 v[216:219], v151 offset:56320
	global_load_lds_dwordx4 v[144:145], off
	s_add_i32 m0, s56, 0x2000
	s_add_u32 s54, s54, 0x80080
	v_lshl_add_u64 v[144:145], v[220:221], 0, s[8:9]
	s_addc_u32 s55, s55, 0
	s_add_i32 s56, s74, s18
	global_load_lds_dwordx4 v[144:145], off
	v_lshl_add_u64 v[144:145], s[54:55], 0, v[130:131]
	s_mov_b32 m0, s56
	s_nop 0
	global_load_lds_dwordx4 v[144:145], off
	v_lshl_add_u64 v[144:145], s[54:55], 0, v[134:135]
	s_add_i32 m0, s56, 0x2000
	s_nop 0
	global_load_lds_dwordx4 v[144:145], off
	v_lshl_add_u64 v[144:145], v[222:223], 0, s[8:9]
	s_mov_b32 m0, s59
	s_nop 0
	global_load_lds_dwordx4 v[144:145], off
	v_lshl_add_u64 v[144:145], v[224:225], 0, s[8:9]
	s_mov_b32 m0, s60
	s_nop 0
	global_load_lds_dwordx4 v[144:145], off
	s_waitcnt vmcnt(8)
	s_waitcnt lgkmcnt(0)
	s_barrier
	s_waitcnt lgkmcnt(0)
	v_mfma_f32_16x16x32_bf16 v[60:63], v[152:155], v[188:191], v[60:63]
	v_mfma_f32_16x16x32_bf16 v[56:59], v[160:163], v[188:191], v[56:59]
	v_mfma_f32_16x16x32_bf16 v[52:55], v[152:155], v[196:199], v[52:55]
	v_mfma_f32_16x16x32_bf16 v[44:47], v[160:163], v[196:199], v[44:47]
	v_mfma_f32_16x16x32_bf16 v[36:39], v[152:155], v[204:207], v[36:39]
	v_mfma_f32_16x16x32_bf16 v[28:31], v[160:163], v[204:207], v[28:31]
	v_mfma_f32_16x16x32_bf16 v[20:23], v[152:155], v[212:215], v[20:23]
	v_mfma_f32_16x16x32_bf16 v[12:15], v[160:163], v[212:215], v[12:15]
	v_mfma_f32_16x16x32_bf16 v[60:63], v[156:159], v[192:195], v[60:63]
	v_mfma_f32_16x16x32_bf16 v[56:59], v[164:167], v[192:195], v[56:59]
	v_mfma_f32_16x16x32_bf16 v[52:55], v[156:159], v[200:203], v[52:55]
	v_mfma_f32_16x16x32_bf16 v[44:47], v[164:167], v[200:203], v[44:47]
	v_mfma_f32_16x16x32_bf16 v[36:39], v[156:159], v[208:211], v[36:39]
	v_mfma_f32_16x16x32_bf16 v[28:31], v[164:167], v[208:211], v[28:31]
	v_mfma_f32_16x16x32_bf16 v[20:23], v[156:159], v[216:219], v[20:23]
	v_mfma_f32_16x16x32_bf16 v[12:15], v[164:167], v[216:219], v[12:15]
	v_mfma_f32_16x16x32_bf16 v[48:51], v[168:171], v[188:191], v[48:51]
	v_mfma_f32_16x16x32_bf16 v[40:43], v[176:179], v[188:191], v[40:43]
	v_mfma_f32_16x16x32_bf16 v[32:35], v[168:171], v[196:199], v[32:35]
	v_mfma_f32_16x16x32_bf16 v[24:27], v[176:179], v[196:199], v[24:27]
	v_mfma_f32_16x16x32_bf16 v[16:19], v[168:171], v[204:207], v[16:19]
	v_mfma_f32_16x16x32_bf16 v[8:11], v[176:179], v[204:207], v[8:11]
	v_mfma_f32_16x16x32_bf16 v[4:7], v[168:171], v[212:215], v[4:7]
	v_mfma_f32_16x16x32_bf16 v[0:3], v[176:179], v[212:215], v[0:3]
	v_mfma_f32_16x16x32_bf16 v[48:51], v[172:175], v[192:195], v[48:51]
	v_mfma_f32_16x16x32_bf16 v[40:43], v[184:187], v[192:195], v[40:43]
	v_mfma_f32_16x16x32_bf16 v[32:35], v[172:175], v[200:203], v[32:35]
	v_mfma_f32_16x16x32_bf16 v[24:27], v[184:187], v[200:203], v[24:27]
	v_mfma_f32_16x16x32_bf16 v[16:19], v[172:175], v[208:211], v[16:19]
	v_mfma_f32_16x16x32_bf16 v[8:11], v[184:187], v[208:211], v[8:11]
	v_mfma_f32_16x16x32_bf16 v[4:7], v[172:175], v[216:219], v[4:7]
	v_mfma_f32_16x16x32_bf16 v[0:3], v[184:187], v[216:219], v[0:3]
	s_barrier
	s_add_i32 s72, s72, 2
	s_add_u32 s52, s52, 0x100
	s_addc_u32 s53, s53, 0
	s_add_u32 s70, s70, 0x100
	s_addc_u32 s71, s71, 0
	s_cmp_gt_u32 s72, 29
	s_cbranch_scc0 .LBB0_1776
	s_and_b64 vcc, exec, s[10:11]
	s_cbranch_vccz .LBB0_1779
	s_barrier

; #define PG8_STAGE(bufoff, gbase, voff) do { _Pragma("unroll") for (int _i = 0; _i < 2; ++_i) \
;         __builtin_amdgcn_global_load_lds((const unsigned*)((const char*)(gbase) + (voff)[_i]), (LAS unsigned*)(lds + (bufoff) + ldsw + _i * 8192), 16, 0, 0); } while (0)
; #define PG8_LDA(dst, b, h) do { _Pragma("unroll") for (int m = 0; m < 4; ++m) _Pragma("unroll") for (int k = 0; k < 2; ++k) dst[m][k] = *(const LAS bf16x8*)(lds + PG8_SA(b, h) + aoff + m * 2048 + k * 1024); } while (0)
; #define PG8_LDB(dst, b, h) do { _Pragma("unroll") for (int n = 0; n < 2; ++n) _Pragma("unroll") for (int k = 0; k < 2; ++k) dst[n][k] = *(const LAS bf16x8*)(lds + PG8_SB(b, h) + boff + n * 2048 + k * 1024); } while (0)
; #define PG8_MMA(ai, bj, At, Bt) do { __builtin_amdgcn_s_setprio(1); _Pragma("unroll") for (int m = 0; m < 4; ++m) _Pragma("unroll") for (int n = 0; n < 2; ++n) _Pragma("unroll") for (int k = 0; k < 2; ++k) \
;         acc[ai][bj][m][n] = __builtin_amdgcn_mfma_f32_16x16x32_bf16(Bt[n][k], At[m][k], acc[ai][bj][m][n], 0, 0, 0); __builtin_amdgcn_s_setprio(0); } while (0)
; #define PG8_WAIT_V(n) asm volatile("s_waitcnt vmcnt(" #n ")" ::: "memory")
; #define PG8_WAIT_L(n) asm volatile("s_waitcnt lgkmcnt(" #n ")" ::: "memory")
; #define PG8_BAR __builtin_amdgcn_s_barrier()
; #define PG8_SCHED __builtin_amdgcn_sched_barrier(0)
; template <bool LT, class Epi>
; __device__ __forceinline__ void gemm_phase(LAS unsigned char* lds, const Gemm g, const StaticOrder& S, const Epi& E) {
;     ...
;             const bool last = (t == nt - 2);
;             const char* a1 = cA + (size_t)(t + 1) * kstep;
;             const char* a2 = last ? nA : cA + (size_t)(t + 2) * kstep; const char* b2 = last ? nB : cB + (size_t)(t + 2) * kstep;
;             const char* a3 = a2 + kstep; const char* b3 = b2 + kstep;
;             PG8_LDB(B0, 0, 0); PG8_LDB(B1, 0, 1); PG8_SCHED; PG8_LDA(At, 0, 0); PG8_STAGE(PG8_SA(1, 1), a1 + hstepA, voffA);
;             PG8_WAIT_V(8); PG8_WAIT_L(0); PG8_BAR; PG8_MMA(0, 0, At, B0); PG8_MMA(0, 1, At, B1); PG8_BAR; PG8_SCHED;
;             PG8_LDA(At, 0, 1); PG8_STAGE(PG8_SB(0, 0), b2, voffB); PG8_STAGE(PG8_SB(0, 1), b2 + hstepB, voffB); PG8_STAGE(PG8_SA(0, 0), a2, voffA);
.LBB0_1899:
	ds_read_b128 v[152:155], v149
	ds_read_b128 v[156:159], v149 offset:1024
	ds_read_b128 v[160:163], v149 offset:2048
	ds_read_b128 v[164:167], v149 offset:3072
	ds_read_b128 v[168:171], v150
	ds_read_b128 v[172:175], v150 offset:1024
	ds_read_b128 v[176:179], v150 offset:2048
	ds_read_b128 v[184:187], v150 offset:3072
	s_add_u32 s38, s34, 0xfff80080
	s_addc_u32 s39, s35, -1
	s_cmp_eq_u32 s58, 28
	s_cselect_b32 s41, s13, s39
	s_cselect_b32 s40, s54, s38
	s_cselect_b32 s39, s11, s57
	s_cselect_b32 s38, s55, s56
	v_lshl_add_u64 v[144:145], s[34:35], 0, v[136:137]
	s_add_i32 m0, s25, 0xc000
	ds_read_b128 v[188:191], v151
	ds_read_b128 v[192:195], v151 offset:1024
	ds_read_b128 v[196:199], v151 offset:2048
	ds_read_b128 v[200:203], v151 offset:3072
	ds_read_b128 v[204:207], v151 offset:4096
	ds_read_b128 v[208:211], v151 offset:5120
	ds_read_b128 v[212:215], v151 offset:6144
	ds_read_b128 v[216:219], v151 offset:7168
	global_load_lds_dwordx4 v[144:145], off
	v_lshl_add_u64 v[144:145], s[34:35], 0, v[138:139]
	s_add_i32 m0, s25, 0xe000
	s_nop 0
	global_load_lds_dwordx4 v[144:145], off
	s_waitcnt vmcnt(8)
	s_waitcnt lgkmcnt(0)
	s_barrier
	s_waitcnt lgkmcnt(0)
	v_mfma_f32_16x16x32_bf16 v[124:127], v[152:155], v[188:191], v[124:127]
	v_mfma_f32_16x16x32_bf16 v[120:123], v[160:163], v[188:191], v[120:123]
	v_mfma_f32_16x16x32_bf16 v[108:111], v[152:155], v[196:199], v[108:111]
	v_mfma_f32_16x16x32_bf16 v[104:107], v[160:163], v[196:199], v[104:107]
	v_mfma_f32_16x16x32_bf16 v[92:95], v[152:155], v[204:207], v[92:95]
	v_mfma_f32_16x16x32_bf16 v[88:91], v[160:163], v[204:207], v[88:91]
	v_mfma_f32_16x16x32_bf16 v[76:79], v[152:155], v[212:215], v[76:79]
	v_mfma_f32_16x16x32_bf16 v[72:75], v[160:163], v[212:215], v[72:75]
	v_mfma_f32_16x16x32_bf16 v[124:127], v[156:159], v[192:195], v[124:127]
	v_mfma_f32_16x16x32_bf16 v[120:123], v[164:167], v[192:195], v[120:123]
	v_mfma_f32_16x16x32_bf16 v[108:111], v[156:159], v[200:203], v[108:111]
	v_mfma_f32_16x16x32_bf16 v[104:107], v[164:167], v[200:203], v[104:107]
	v_mfma_f32_16x16x32_bf16 v[92:95], v[156:159], v[208:211], v[92:95]
	v_mfma_f32_16x16x32_bf16 v[88:91], v[164:167], v[208:211], v[88:91]
	v_mfma_f32_16x16x32_bf16 v[76:79], v[156:159], v[216:219], v[76:79]
	v_mfma_f32_16x16x32_bf16 v[72:75], v[164:167], v[216:219], v[72:75]
	v_mfma_f32_16x16x32_bf16 v[116:119], v[168:171], v[188:191], v[116:119]
	v_mfma_f32_16x16x32_bf16 v[112:115], v[176:179], v[188:191], v[112:115]
	v_mfma_f32_16x16x32_bf16 v[100:103], v[168:171], v[196:199], v[100:103]
	v_mfma_f32_16x16x32_bf16 v[96:99], v[176:179], v[196:199], v[96:99]
	v_mfma_f32_16x16x32_bf16 v[84:87], v[168:171], v[204:207], v[84:87]
	v_mfma_f32_16x16x32_bf16 v[80:83], v[176:179], v[204:207], v[80:83]
	v_mfma_f32_16x16x32_bf16 v[68:71], v[168:171], v[212:215], v[68:71]
	v_mfma_f32_16x16x32_bf16 v[64:67], v[176:179], v[212:215], v[64:67]
	v_mfma_f32_16x16x32_bf16 v[116:119], v[172:175], v[192:195], v[116:119]
	v_mfma_f32_16x16x32_bf16 v[112:115], v[184:187], v[192:195], v[112:115]
	v_mfma_f32_16x16x32_bf16 v[100:103], v[172:175], v[200:203], v[100:103]
	v_mfma_f32_16x16x32_bf16 v[96:99], v[184:187], v[200:203], v[96:99]
	v_mfma_f32_16x16x32_bf16 v[84:87], v[172:175], v[208:211], v[84:87]
	v_mfma_f32_16x16x32_bf16 v[80:83], v[184:187], v[208:211], v[80:83]
	v_mfma_f32_16x16x32_bf16 v[68:71], v[172:175], v[216:219], v[68:71]
	v_mfma_f32_16x16x32_bf16 v[64:67], v[184:187], v[216:219], v[64:67]
	s_barrier
	s_add_i32 s59, s50, s3
	v_lshl_add_u64 v[144:145], s[38:39], 0, v[132:133]
	s_mov_b32 m0, s59
	ds_read_b128 v[188:191], v151 offset:16384
	ds_read_b128 v[192:195], v151 offset:17408
	ds_read_b128 v[196:199], v151 offset:18432
	ds_read_b128 v[200:203], v151 offset:19456
	ds_read_b128 v[204:207], v151 offset:20480
	ds_read_b128 v[208:211], v151 offset:21504
	ds_read_b128 v[212:215], v151 offset:22528
	ds_read_b128 v[216:219], v151 offset:23552
	global_load_lds_dwordx4 v[144:145], off
	s_add_i32 m0, s59, 0x2000
	s_add_u32 s60, s38, 0x80000
	v_lshl_add_u64 v[220:221], s[38:39], 0, v[128:129]
	s_addc_u32 s61, s39, 0
	s_add_i32 s59, s51, s3
	global_load_lds_dwordx4 v[220:221], off
	v_lshl_add_u64 v[222:223], s[60:61], 0, v[132:133]
	s_mov_b32 m0, s59
	v_lshl_add_u64 v[224:225], s[40:41], 0, v[130:131]
	global_load_lds_dwordx4 v[222:223], off
	v_lshl_add_u64 v[222:223], s[60:61], 0, v[128:129]
	s_add_i32 m0, s59, 0x2000
	s_nop 0
	global_load_lds_dwordx4 v[222:223], off
	v_lshl_add_u64 v[222:223], s[40:41], 0, v[134:135]
	s_mov_b32 m0, s25
	s_nop 0
	global_load_lds_dwordx4 v[222:223], off
	s_mov_b32 m0, s27
	s_nop 0
	global_load_lds_dwordx4 v[224:225], off
	s_waitcnt vmcnt(8)
	s_waitcnt lgkmcnt(0)
	s_barrier
; #define PG8_STAGE(bufoff, gbase, voff) do { _Pragma("unroll") for (int _i = 0; _i < 2; ++_i) \
;         __builtin_amdgcn_global_load_lds((const unsigned*)((const char*)(gbase) + (voff)[_i]), (LAS unsigned*)(lds + (bufoff) + ldsw + _i * 8192), 16, 0, 0); } while (0)
; #define PG8_LDA(dst, b, h) do { _Pragma("unroll") for (int m = 0; m < 4; ++m) _Pragma("unroll") for (int k = 0; k < 2; ++k) dst[m][k] = *(const LAS bf16x8*)(lds + PG8_SA(b, h) + aoff + m * 2048 + k * 1024); } while (0)
; #define PG8_LDB(dst, b, h) do { _Pragma("unroll") for (int n = 0; n < 2; ++n) _Pragma("unroll") for (int k = 0; k < 2; ++k) dst[n][k] = *(const LAS bf16x8*)(lds + PG8_SB(b, h) + boff + n * 2048 + k * 1024); } while (0)
; #define PG8_MMA(ai, bj, At, Bt) do { __builtin_amdgcn_s_setprio(1); _Pragma("unroll") for (int m = 0; m < 4; ++m) _Pragma("unroll") for (int n = 0; n < 2; ++n) _Pragma("unroll") for (int k = 0; k < 2; ++k) \
;         acc[ai][bj][m][n] = __builtin_amdgcn_mfma_f32_16x16x32_bf16(Bt[n][k], At[m][k], acc[ai][bj][m][n], 0, 0, 0); __builtin_amdgcn_s_setprio(0); } while (0)
; #define PG8_WAIT_V(n) asm volatile("s_waitcnt vmcnt(" #n ")" ::: "memory")
; #define PG8_WAIT_L(n) asm volatile("s_waitcnt lgkmcnt(" #n ")" ::: "memory")
; #define PG8_BAR __builtin_amdgcn_s_barrier()
; #define PG8_SCHED __builtin_amdgcn_sched_barrier(0)
; template <bool LT, class Epi>
; __device__ __forceinline__ void gemm_phase(LAS unsigned char* lds, const Gemm g, const StaticOrder& S, const Epi& E) {
;     ...
;             PG8_WAIT_V(8); PG8_WAIT_L(0); PG8_BAR; PG8_MMA(1, 0, At, B0); PG8_MMA(1, 1, At, B1); PG8_BAR; PG8_SCHED;
;             PG8_LDB(B0, 1, 0); PG8_LDB(B1, 1, 1); PG8_SCHED; PG8_LDA(At, 1, 0); PG8_STAGE(PG8_SA(0, 1), a2 + hstepA, voffA);
;             PG8_WAIT_V(8); PG8_WAIT_L(0); PG8_BAR; PG8_MMA(0, 0, At, B0); PG8_MMA(0, 1, At, B1); PG8_BAR; PG8_SCHED;
	s_waitcnt lgkmcnt(0)
	v_mfma_f32_16x16x32_bf16 v[60:63], v[152:155], v[188:191], v[60:63]
	v_mfma_f32_16x16x32_bf16 v[56:59], v[160:163], v[188:191], v[56:59]
	v_mfma_f32_16x16x32_bf16 v[44:47], v[152:155], v[196:199], v[44:47]
	v_mfma_f32_16x16x32_bf16 v[40:43], v[160:163], v[196:199], v[40:43]
	v_mfma_f32_16x16x32_bf16 v[28:31], v[152:155], v[204:207], v[28:31]
	v_mfma_f32_16x16x32_bf16 v[24:27], v[160:163], v[204:207], v[24:27]
	v_mfma_f32_16x16x32_bf16 v[12:15], v[152:155], v[212:215], v[12:15]
	v_mfma_f32_16x16x32_bf16 v[8:11], v[160:163], v[212:215], v[8:11]
	v_mfma_f32_16x16x32_bf16 v[60:63], v[156:159], v[192:195], v[60:63]
	v_mfma_f32_16x16x32_bf16 v[56:59], v[164:167], v[192:195], v[56:59]
	v_mfma_f32_16x16x32_bf16 v[44:47], v[156:159], v[200:203], v[44:47]
	v_mfma_f32_16x16x32_bf16 v[40:43], v[164:167], v[200:203], v[40:43]
	v_mfma_f32_16x16x32_bf16 v[28:31], v[156:159], v[208:211], v[28:31]
	v_mfma_f32_16x16x32_bf16 v[24:27], v[164:167], v[208:211], v[24:27]
	v_mfma_f32_16x16x32_bf16 v[12:15], v[156:159], v[216:219], v[12:15]
	v_mfma_f32_16x16x32_bf16 v[8:11], v[164:167], v[216:219], v[8:11]
	v_mfma_f32_16x16x32_bf16 v[52:55], v[168:171], v[188:191], v[52:55]
	v_mfma_f32_16x16x32_bf16 v[48:51], v[176:179], v[188:191], v[48:51]
	v_mfma_f32_16x16x32_bf16 v[36:39], v[168:171], v[196:199], v[36:39]
	v_mfma_f32_16x16x32_bf16 v[32:35], v[176:179], v[196:199], v[32:35]
	v_mfma_f32_16x16x32_bf16 v[20:23], v[168:171], v[204:207], v[20:23]
	v_mfma_f32_16x16x32_bf16 v[16:19], v[176:179], v[204:207], v[16:19]
	v_mfma_f32_16x16x32_bf16 v[4:7], v[168:171], v[212:215], v[4:7]
	v_mfma_f32_16x16x32_bf16 v[0:3], v[176:179], v[212:215], v[0:3]
	v_mfma_f32_16x16x32_bf16 v[52:55], v[172:175], v[192:195], v[52:55]
	v_mfma_f32_16x16x32_bf16 v[48:51], v[184:187], v[192:195], v[48:51]
	v_mfma_f32_16x16x32_bf16 v[36:39], v[172:175], v[200:203], v[36:39]
	v_mfma_f32_16x16x32_bf16 v[32:35], v[184:187], v[200:203], v[32:35]
	v_mfma_f32_16x16x32_bf16 v[20:23], v[172:175], v[208:211], v[20:23]
	v_mfma_f32_16x16x32_bf16 v[16:19], v[184:187], v[208:211], v[16:19]
	v_mfma_f32_16x16x32_bf16 v[4:7], v[172:175], v[216:219], v[4:7]
	v_mfma_f32_16x16x32_bf16 v[0:3], v[184:187], v[216:219], v[0:3]
	s_barrier
	s_add_i32 s59, 0, 0x18000
	s_add_i32 s60, 0, 0x1c000
	v_add_u32_e32 v164, s59, v147
	v_add_u32_e32 v183, s60, v147
	ds_read_b128 v[152:155], v164
	ds_read_b128 v[156:159], v164 offset:1024
	ds_read_b128 v[160:163], v164 offset:2048
	ds_read_b128 v[164:167], v164 offset:3072
	ds_read_b128 v[168:171], v183
	ds_read_b128 v[172:175], v183 offset:1024
	ds_read_b128 v[176:179], v183 offset:2048
	ds_read_b128 v[184:187], v183 offset:3072
	s_add_u32 s40, s40, 0x80000
	s_addc_u32 s41, s41, 0
	s_mov_b32 m0, s33
	v_lshl_add_u64 v[226:227], s[40:41], 0, v[134:135]
	ds_read_b128 v[188:191], v151 offset:32768
	ds_read_b128 v[192:195], v151 offset:33792
	ds_read_b128 v[196:199], v151 offset:34816
	ds_read_b128 v[200:203], v151 offset:35840
	ds_read_b128 v[204:207], v151 offset:36864
	ds_read_b128 v[208:211], v151 offset:37888
	ds_read_b128 v[212:215], v151 offset:38912
	ds_read_b128 v[216:219], v151 offset:39936
	global_load_lds_dwordx4 v[226:227], off
	v_lshl_add_u64 v[226:227], s[40:41], 0, v[130:131]
	s_mov_b32 m0, s42
	s_nop 0
	global_load_lds_dwordx4 v[226:227], off
	s_waitcnt vmcnt(8)
	s_waitcnt lgkmcnt(0)
	s_barrier
	s_waitcnt lgkmcnt(0)
	v_mfma_f32_16x16x32_bf16 v[124:127], v[152:155], v[188:191], v[124:127]
	v_mfma_f32_16x16x32_bf16 v[120:123], v[160:163], v[188:191], v[120:123]
	v_mfma_f32_16x16x32_bf16 v[108:111], v[152:155], v[196:199], v[108:111]
	v_mfma_f32_16x16x32_bf16 v[104:107], v[160:163], v[196:199], v[104:107]
	v_mfma_f32_16x16x32_bf16 v[92:95], v[152:155], v[204:207], v[92:95]
	v_mfma_f32_16x16x32_bf16 v[88:91], v[160:163], v[204:207], v[88:91]
	v_mfma_f32_16x16x32_bf16 v[76:79], v[152:155], v[212:215], v[76:79]
	v_mfma_f32_16x16x32_bf16 v[72:75], v[160:163], v[212:215], v[72:75]
	v_mfma_f32_16x16x32_bf16 v[124:127], v[156:159], v[192:195], v[124:127]
	v_mfma_f32_16x16x32_bf16 v[120:123], v[164:167], v[192:195], v[120:123]
	v_mfma_f32_16x16x32_bf16 v[108:111], v[156:159], v[200:203], v[108:111]
	v_mfma_f32_16x16x32_bf16 v[104:107], v[164:167], v[200:203], v[104:107]
	v_mfma_f32_16x16x32_bf16 v[92:95], v[156:159], v[208:211], v[92:95]
	v_mfma_f32_16x16x32_bf16 v[88:91], v[164:167], v[208:211], v[88:91]
	v_mfma_f32_16x16x32_bf16 v[76:79], v[156:159], v[216:219], v[76:79]
	v_mfma_f32_16x16x32_bf16 v[72:75], v[164:167], v[216:219], v[72:75]
	v_mfma_f32_16x16x32_bf16 v[116:119], v[168:171], v[188:191], v[116:119]
	v_mfma_f32_16x16x32_bf16 v[112:115], v[176:179], v[188:191], v[112:115]
	v_mfma_f32_16x16x32_bf16 v[100:103], v[168:171], v[196:199], v[100:103]
	v_mfma_f32_16x16x32_bf16 v[96:99], v[176:179], v[196:199], v[96:99]
	v_mfma_f32_16x16x32_bf16 v[84:87], v[168:171], v[204:207], v[84:87]
	v_mfma_f32_16x16x32_bf16 v[80:83], v[176:179], v[204:207], v[80:83]
	v_mfma_f32_16x16x32_bf16 v[68:71], v[168:171], v[212:215], v[68:71]
	v_mfma_f32_16x16x32_bf16 v[64:67], v[176:179], v[212:215], v[64:67]
	v_mfma_f32_16x16x32_bf16 v[116:119], v[172:175], v[192:195], v[116:119]
	v_mfma_f32_16x16x32_bf16 v[112:115], v[184:187], v[192:195], v[112:115]
	v_mfma_f32_16x16x32_bf16 v[100:103], v[172:175], v[200:203], v[100:103]
	v_mfma_f32_16x16x32_bf16 v[96:99], v[184:187], v[200:203], v[96:99]
	v_mfma_f32_16x16x32_bf16 v[84:87], v[172:175], v[208:211], v[84:87]
	v_mfma_f32_16x16x32_bf16 v[80:83], v[184:187], v[208:211], v[80:83]
	v_mfma_f32_16x16x32_bf16 v[68:71], v[172:175], v[216:219], v[68:71]
	v_mfma_f32_16x16x32_bf16 v[64:67], v[184:187], v[216:219], v[64:67]
	s_barrier
; #define PG8_STAGE(bufoff, gbase, voff) do { _Pragma("unroll") for (int _i = 0; _i < 2; ++_i) \
;         __builtin_amdgcn_global_load_lds((const unsigned*)((const char*)(gbase) + (voff)[_i]), (LAS unsigned*)(lds + (bufoff) + ldsw + _i * 8192), 16, 0, 0); } while (0)
; #define PG8_LDA(dst, b, h) do { _Pragma("unroll") for (int m = 0; m < 4; ++m) _Pragma("unroll") for (int k = 0; k < 2; ++k) dst[m][k] = *(const LAS bf16x8*)(lds + PG8_SA(b, h) + aoff + m * 2048 + k * 1024); } while (0)
; #define PG8_MMA(ai, bj, At, Bt) do { __builtin_amdgcn_s_setprio(1); _Pragma("unroll") for (int m = 0; m < 4; ++m) _Pragma("unroll") for (int n = 0; n < 2; ++n) _Pragma("unroll") for (int k = 0; k < 2; ++k) \
;         acc[ai][bj][m][n] = __builtin_amdgcn_mfma_f32_16x16x32_bf16(Bt[n][k], At[m][k], acc[ai][bj][m][n], 0, 0, 0); __builtin_amdgcn_s_setprio(0); } while (0)
; #define PG8_WAIT_V(n) asm volatile("s_waitcnt vmcnt(" #n ")" ::: "memory")
; #define PG8_WAIT_L(n) asm volatile("s_waitcnt lgkmcnt(" #n ")" ::: "memory")
; #define PG8_BAR __builtin_amdgcn_s_barrier()
; #define PG8_SCHED __builtin_amdgcn_sched_barrier(0)
; template <bool LT, class Epi>
; __device__ __forceinline__ void gemm_phase(LAS unsigned char* lds, const Gemm g, const StaticOrder& S, const Epi& E) {
;     ...
;         for (int t = 0; t < nt; t += 2) {
;     ...
;             PG8_LDA(At, 1, 1); PG8_STAGE(PG8_SB(1, 0), b3, voffB); PG8_STAGE(PG8_SB(1, 1), b3 + hstepB, voffB); PG8_STAGE(PG8_SA(1, 0), a3, voffA);
;             PG8_WAIT_V(8); PG8_WAIT_L(0); PG8_BAR; PG8_MMA(1, 0, At, B0); PG8_MMA(1, 1, At, B1); PG8_BAR; PG8_SCHED;
	s_add_i32 s40, s59, s3
	v_lshl_add_u64 v[144:145], v[144:145], 0, s[6:7]
	s_mov_b32 m0, s40
	ds_read_b128 v[188:191], v151 offset:49152
	ds_read_b128 v[192:195], v151 offset:50176
	ds_read_b128 v[196:199], v151 offset:51200
	ds_read_b128 v[200:203], v151 offset:52224
	ds_read_b128 v[204:207], v151 offset:53248
	ds_read_b128 v[208:211], v151 offset:54272
	ds_read_b128 v[212:215], v151 offset:55296
	ds_read_b128 v[216:219], v151 offset:56320
	global_load_lds_dwordx4 v[144:145], off
	s_add_i32 m0, s40, 0x2000
	s_add_u32 s38, s38, 0x80080
	v_lshl_add_u64 v[144:145], v[220:221], 0, s[6:7]
	s_addc_u32 s39, s39, 0
	s_add_i32 s40, s60, s3
	global_load_lds_dwordx4 v[144:145], off
	v_lshl_add_u64 v[144:145], s[38:39], 0, v[132:133]
	s_mov_b32 m0, s40
	s_nop 0
	global_load_lds_dwordx4 v[144:145], off
	v_lshl_add_u64 v[144:145], s[38:39], 0, v[128:129]
	s_add_i32 m0, s40, 0x2000
	s_nop 0
	global_load_lds_dwordx4 v[144:145], off
	v_lshl_add_u64 v[144:145], v[222:223], 0, s[6:7]
	s_mov_b32 m0, s44
	s_nop 0
	global_load_lds_dwordx4 v[144:145], off
	v_lshl_add_u64 v[144:145], v[224:225], 0, s[6:7]
	s_mov_b32 m0, s45
	s_nop 0
	global_load_lds_dwordx4 v[144:145], off
	s_waitcnt vmcnt(8)
	s_waitcnt lgkmcnt(0)
	s_barrier
	s_waitcnt lgkmcnt(0)
	v_mfma_f32_16x16x32_bf16 v[60:63], v[152:155], v[188:191], v[60:63]
	v_mfma_f32_16x16x32_bf16 v[56:59], v[160:163], v[188:191], v[56:59]
	v_mfma_f32_16x16x32_bf16 v[44:47], v[152:155], v[196:199], v[44:47]
	v_mfma_f32_16x16x32_bf16 v[40:43], v[160:163], v[196:199], v[40:43]
	v_mfma_f32_16x16x32_bf16 v[28:31], v[152:155], v[204:207], v[28:31]
	v_mfma_f32_16x16x32_bf16 v[24:27], v[160:163], v[204:207], v[24:27]
	v_mfma_f32_16x16x32_bf16 v[12:15], v[152:155], v[212:215], v[12:15]
	v_mfma_f32_16x16x32_bf16 v[8:11], v[160:163], v[212:215], v[8:11]
	v_mfma_f32_16x16x32_bf16 v[60:63], v[156:159], v[192:195], v[60:63]
	v_mfma_f32_16x16x32_bf16 v[56:59], v[164:167], v[192:195], v[56:59]
	v_mfma_f32_16x16x32_bf16 v[44:47], v[156:159], v[200:203], v[44:47]
	v_mfma_f32_16x16x32_bf16 v[40:43], v[164:167], v[200:203], v[40:43]
	v_mfma_f32_16x16x32_bf16 v[28:31], v[156:159], v[208:211], v[28:31]
	v_mfma_f32_16x16x32_bf16 v[24:27], v[164:167], v[208:211], v[24:27]
	v_mfma_f32_16x16x32_bf16 v[12:15], v[156:159], v[216:219], v[12:15]
	v_mfma_f32_16x16x32_bf16 v[8:11], v[164:167], v[216:219], v[8:11]
	v_mfma_f32_16x16x32_bf16 v[52:55], v[168:171], v[188:191], v[52:55]
	v_mfma_f32_16x16x32_bf16 v[48:51], v[176:179], v[188:191], v[48:51]
	v_mfma_f32_16x16x32_bf16 v[36:39], v[168:171], v[196:199], v[36:39]
	v_mfma_f32_16x16x32_bf16 v[32:35], v[176:179], v[196:199], v[32:35]
	v_mfma_f32_16x16x32_bf16 v[20:23], v[168:171], v[204:207], v[20:23]
	v_mfma_f32_16x16x32_bf16 v[16:19], v[176:179], v[204:207], v[16:19]
	v_mfma_f32_16x16x32_bf16 v[4:7], v[168:171], v[212:215], v[4:7]
	v_mfma_f32_16x16x32_bf16 v[0:3], v[176:179], v[212:215], v[0:3]
	v_mfma_f32_16x16x32_bf16 v[52:55], v[172:175], v[192:195], v[52:55]
	v_mfma_f32_16x16x32_bf16 v[48:51], v[184:187], v[192:195], v[48:51]
	v_mfma_f32_16x16x32_bf16 v[36:39], v[172:175], v[200:203], v[36:39]
	v_mfma_f32_16x16x32_bf16 v[32:35], v[184:187], v[200:203], v[32:35]
	v_mfma_f32_16x16x32_bf16 v[20:23], v[172:175], v[208:211], v[20:23]
	v_mfma_f32_16x16x32_bf16 v[16:19], v[184:187], v[208:211], v[16:19]
	v_mfma_f32_16x16x32_bf16 v[4:7], v[172:175], v[216:219], v[4:7]
	v_mfma_f32_16x16x32_bf16 v[0:3], v[184:187], v[216:219], v[0:3]
	s_barrier
	s_add_i32 s58, s58, 2
	s_add_u32 s34, s34, 0x100
	s_addc_u32 s35, s35, 0
	s_add_u32 s56, s56, 0x100
	s_addc_u32 s57, s57, 0
	s_cmp_gt_u32 s58, 29
	s_cbranch_scc0 .LBB0_1899
	s_and_b64 vcc, exec, s[8:9]
	s_cbranch_vccz .LBB0_1902
	s_barrier

; #define PG8_STAGE(bufoff, gbase, voff) do { _Pragma("unroll") for (int _i = 0; _i < 2; ++_i) \
;         __builtin_amdgcn_global_load_lds((const unsigned*)((const char*)(gbase) + (voff)[_i]), (LAS unsigned*)(lds + (bufoff) + ldsw + _i * 8192), 16, 0, 0); } while (0)
; #define PG8_LDA(dst, b, h) do { _Pragma("unroll") for (int m = 0; m < 4; ++m) _Pragma("unroll") for (int k = 0; k < 2; ++k) dst[m][k] = *(const LAS bf16x8*)(lds + PG8_SA(b, h) + aoff + m * 2048 + k * 1024); } while (0)
; #define PG8_LDB(dst, b, h) do { _Pragma("unroll") for (int n = 0; n < 2; ++n) _Pragma("unroll") for (int k = 0; k < 2; ++k) dst[n][k] = *(const LAS bf16x8*)(lds + PG8_SB(b, h) + boff + n * 2048 + k * 1024); } while (0)
; #define PG8_MMA(ai, bj, At, Bt) do { __builtin_amdgcn_s_setprio(1); _Pragma("unroll") for (int m = 0; m < 4; ++m) _Pragma("unroll") for (int n = 0; n < 2; ++n) _Pragma("unroll") for (int k = 0; k < 2; ++k) \
;         acc[ai][bj][m][n] = __builtin_amdgcn_mfma_f32_16x16x32_bf16(Bt[n][k], At[m][k], acc[ai][bj][m][n], 0, 0, 0); __builtin_amdgcn_s_setprio(0); } while (0)
; #define PG8_WAIT_V(n) asm volatile("s_waitcnt vmcnt(" #n ")" ::: "memory")
; #define PG8_WAIT_L(n) asm volatile("s_waitcnt lgkmcnt(" #n ")" ::: "memory")
; #define PG8_BAR __builtin_amdgcn_s_barrier()
; #define PG8_SCHED __builtin_amdgcn_sched_barrier(0)
; template <bool LT, class Epi>
; __device__ __forceinline__ void gemm_phase(LAS unsigned char* lds, const Gemm g, const StaticOrder& S, const Epi& E) {
;     ...
;             const bool last = (t == nt - 2);
;             const char* a1 = cA + (size_t)(t + 1) * kstep;
;             const char* a2 = last ? nA : cA + (size_t)(t + 2) * kstep; const char* b2 = last ? nB : cB + (size_t)(t + 2) * kstep;
;             const char* a3 = a2 + kstep; const char* b3 = b2 + kstep;
;             PG8_LDB(B0, 0, 0); PG8_LDB(B1, 0, 1); PG8_SCHED; PG8_LDA(At, 0, 0); PG8_STAGE(PG8_SA(1, 1), a1 + hstepA, voffA);
;             PG8_WAIT_V(8); PG8_WAIT_L(0); PG8_BAR; PG8_MMA(0, 0, At, B0); PG8_MMA(0, 1, At, B1); PG8_BAR; PG8_SCHED;
;             PG8_LDA(At, 0, 1); PG8_STAGE(PG8_SB(0, 0), b2, voffB); PG8_STAGE(PG8_SB(0, 1), b2 + hstepB, voffB); PG8_STAGE(PG8_SA(0, 0), a2, voffA);
.LBB0_1979:
	ds_read_b128 v[152:155], v149
	ds_read_b128 v[156:159], v149 offset:1024
	ds_read_b128 v[160:163], v149 offset:2048
	ds_read_b128 v[164:167], v149 offset:3072
	ds_read_b128 v[168:171], v150
	ds_read_b128 v[172:175], v150 offset:1024
	ds_read_b128 v[176:179], v150 offset:2048
	ds_read_b128 v[184:187], v150 offset:3072
	s_add_u32 s34, s24, 0x100
	s_addc_u32 s35, s25, 0
	s_cmpk_eq_i32 s64, 0x54
	s_cselect_b32 s41, s5, s35
	s_cselect_b32 s40, s4, s34
	s_cselect_b32 s39, s23, s63
	s_cselect_b32 s38, s22, s62
	v_lshl_add_u64 v[144:145], s[24:25], 0, v[136:137]
	s_add_i32 m0, s33, 0xc000
	ds_read_b128 v[188:191], v151
	ds_read_b128 v[192:195], v151 offset:1024
	ds_read_b128 v[196:199], v151 offset:2048
	ds_read_b128 v[200:203], v151 offset:3072
	ds_read_b128 v[204:207], v151 offset:4096
	ds_read_b128 v[208:211], v151 offset:5120
	ds_read_b128 v[212:215], v151 offset:6144
	ds_read_b128 v[216:219], v151 offset:7168
	global_load_lds_dwordx4 v[144:145], off
	v_lshl_add_u64 v[144:145], s[24:25], 0, v[138:139]
	s_add_i32 m0, s33, 0xe000
	s_nop 0
	global_load_lds_dwordx4 v[144:145], off
	s_waitcnt vmcnt(8)
	s_waitcnt lgkmcnt(0)
	s_barrier
	s_waitcnt lgkmcnt(0)
	v_mfma_f32_16x16x32_bf16 v[124:127], v[152:155], v[188:191], v[124:127]
	v_mfma_f32_16x16x32_bf16 v[120:123], v[160:163], v[188:191], v[120:123]
	v_mfma_f32_16x16x32_bf16 v[116:119], v[152:155], v[196:199], v[116:119]
	v_mfma_f32_16x16x32_bf16 v[108:111], v[160:163], v[196:199], v[108:111]
	v_mfma_f32_16x16x32_bf16 v[100:103], v[152:155], v[204:207], v[100:103]
	v_mfma_f32_16x16x32_bf16 v[92:95], v[160:163], v[204:207], v[92:95]
	v_mfma_f32_16x16x32_bf16 v[84:87], v[152:155], v[212:215], v[84:87]
	v_mfma_f32_16x16x32_bf16 v[76:79], v[160:163], v[212:215], v[76:79]
	v_mfma_f32_16x16x32_bf16 v[124:127], v[156:159], v[192:195], v[124:127]
	v_mfma_f32_16x16x32_bf16 v[120:123], v[164:167], v[192:195], v[120:123]
	v_mfma_f32_16x16x32_bf16 v[116:119], v[156:159], v[200:203], v[116:119]
	v_mfma_f32_16x16x32_bf16 v[108:111], v[164:167], v[200:203], v[108:111]
	v_mfma_f32_16x16x32_bf16 v[100:103], v[156:159], v[208:211], v[100:103]
	v_mfma_f32_16x16x32_bf16 v[92:95], v[164:167], v[208:211], v[92:95]
	v_mfma_f32_16x16x32_bf16 v[84:87], v[156:159], v[216:219], v[84:87]
	v_mfma_f32_16x16x32_bf16 v[76:79], v[164:167], v[216:219], v[76:79]
	v_mfma_f32_16x16x32_bf16 v[112:115], v[168:171], v[188:191], v[112:115]
	v_mfma_f32_16x16x32_bf16 v[104:107], v[176:179], v[188:191], v[104:107]
	v_mfma_f32_16x16x32_bf16 v[96:99], v[168:171], v[196:199], v[96:99]
	v_mfma_f32_16x16x32_bf16 v[88:91], v[176:179], v[196:199], v[88:91]
	v_mfma_f32_16x16x32_bf16 v[80:83], v[168:171], v[204:207], v[80:83]
	v_mfma_f32_16x16x32_bf16 v[72:75], v[176:179], v[204:207], v[72:75]
	v_mfma_f32_16x16x32_bf16 v[68:71], v[168:171], v[212:215], v[68:71]
	v_mfma_f32_16x16x32_bf16 v[64:67], v[176:179], v[212:215], v[64:67]
	v_mfma_f32_16x16x32_bf16 v[112:115], v[172:175], v[192:195], v[112:115]
	v_mfma_f32_16x16x32_bf16 v[104:107], v[184:187], v[192:195], v[104:107]
	v_mfma_f32_16x16x32_bf16 v[96:99], v[172:175], v[200:203], v[96:99]
	v_mfma_f32_16x16x32_bf16 v[88:91], v[184:187], v[200:203], v[88:91]
	v_mfma_f32_16x16x32_bf16 v[80:83], v[172:175], v[208:211], v[80:83]
	v_mfma_f32_16x16x32_bf16 v[72:75], v[184:187], v[208:211], v[72:75]
	v_mfma_f32_16x16x32_bf16 v[68:71], v[172:175], v[216:219], v[68:71]
	v_mfma_f32_16x16x32_bf16 v[64:67], v[184:187], v[216:219], v[64:67]
	s_barrier
	s_add_i32 s24, s52, s27
	v_lshl_add_u64 v[144:145], s[38:39], 0, v[130:131]
	s_mov_b32 m0, s24
	ds_read_b128 v[188:191], v151 offset:16384
	ds_read_b128 v[192:195], v151 offset:17408
	ds_read_b128 v[196:199], v151 offset:18432
	ds_read_b128 v[200:203], v151 offset:19456
	ds_read_b128 v[204:207], v151 offset:20480
	ds_read_b128 v[208:211], v151 offset:21504
	ds_read_b128 v[212:215], v151 offset:22528
	ds_read_b128 v[216:219], v151 offset:23552
	global_load_lds_dwordx4 v[144:145], off
	s_add_i32 m0, s24, 0x2000
	s_add_u32 s24, s38, 0x160000
	v_lshl_add_u64 v[220:221], s[38:39], 0, v[134:135]
	s_addc_u32 s25, s39, 0
	s_add_i32 s65, s53, s27
	global_load_lds_dwordx4 v[220:221], off
	v_lshl_add_u64 v[222:223], s[24:25], 0, v[130:131]
	s_mov_b32 m0, s65
	v_lshl_add_u64 v[224:225], s[40:41], 0, v[132:133]
	global_load_lds_dwordx4 v[222:223], off
	v_lshl_add_u64 v[222:223], s[24:25], 0, v[134:135]
	s_add_i32 m0, s65, 0x2000
	s_nop 0
	global_load_lds_dwordx4 v[222:223], off
	v_lshl_add_u64 v[222:223], s[40:41], 0, v[128:129]
	s_mov_b32 m0, s33
	s_nop 0
	global_load_lds_dwordx4 v[222:223], off
	s_mov_b32 m0, s42
	s_nop 0
	global_load_lds_dwordx4 v[224:225], off
	s_waitcnt vmcnt(8)
	s_waitcnt lgkmcnt(0)
	s_barrier
; #define PG8_STAGE(bufoff, gbase, voff) do { _Pragma("unroll") for (int _i = 0; _i < 2; ++_i) \
;         __builtin_amdgcn_global_load_lds((const unsigned*)((const char*)(gbase) + (voff)[_i]), (LAS unsigned*)(lds + (bufoff) + ldsw + _i * 8192), 16, 0, 0); } while (0)
; #define PG8_LDA(dst, b, h) do { _Pragma("unroll") for (int m = 0; m < 4; ++m) _Pragma("unroll") for (int k = 0; k < 2; ++k) dst[m][k] = *(const LAS bf16x8*)(lds + PG8_SA(b, h) + aoff + m * 2048 + k * 1024); } while (0)
; #define PG8_LDB(dst, b, h) do { _Pragma("unroll") for (int n = 0; n < 2; ++n) _Pragma("unroll") for (int k = 0; k < 2; ++k) dst[n][k] = *(const LAS bf16x8*)(lds + PG8_SB(b, h) + boff + n * 2048 + k * 1024); } while (0)
; #define PG8_MMA(ai, bj, At, Bt) do { __builtin_amdgcn_s_setprio(1); _Pragma("unroll") for (int m = 0; m < 4; ++m) _Pragma("unroll") for (int n = 0; n < 2; ++n) _Pragma("unroll") for (int k = 0; k < 2; ++k) \
;         acc[ai][bj][m][n] = __builtin_amdgcn_mfma_f32_16x16x32_bf16(Bt[n][k], At[m][k], acc[ai][bj][m][n], 0, 0, 0); __builtin_amdgcn_s_setprio(0); } while (0)
; #define PG8_WAIT_V(n) asm volatile("s_waitcnt vmcnt(" #n ")" ::: "memory")
; #define PG8_WAIT_L(n) asm volatile("s_waitcnt lgkmcnt(" #n ")" ::: "memory")
; #define PG8_BAR __builtin_amdgcn_s_barrier()
; #define PG8_SCHED __builtin_amdgcn_sched_barrier(0)
; template <bool LT, class Epi>
; __device__ __forceinline__ void gemm_phase(LAS unsigned char* lds, const Gemm g, const StaticOrder& S, const Epi& E) {
;     ...
;             PG8_WAIT_V(8); PG8_WAIT_L(0); PG8_BAR; PG8_MMA(1, 0, At, B0); PG8_MMA(1, 1, At, B1); PG8_BAR; PG8_SCHED;
;             PG8_LDB(B0, 1, 0); PG8_LDB(B1, 1, 1); PG8_SCHED; PG8_LDA(At, 1, 0); PG8_STAGE(PG8_SA(0, 1), a2 + hstepA, voffA);
;             PG8_WAIT_V(8); PG8_WAIT_L(0); PG8_BAR; PG8_MMA(0, 0, At, B0); PG8_MMA(0, 1, At, B1); PG8_BAR; PG8_SCHED;
	s_waitcnt lgkmcnt(0)
	v_mfma_f32_16x16x32_bf16 v[60:63], v[152:155], v[188:191], v[60:63]
	v_mfma_f32_16x16x32_bf16 v[56:59], v[160:163], v[188:191], v[56:59]
	v_mfma_f32_16x16x32_bf16 v[52:55], v[152:155], v[196:199], v[52:55]
	v_mfma_f32_16x16x32_bf16 v[44:47], v[160:163], v[196:199], v[44:47]
	v_mfma_f32_16x16x32_bf16 v[36:39], v[152:155], v[204:207], v[36:39]
	v_mfma_f32_16x16x32_bf16 v[28:31], v[160:163], v[204:207], v[28:31]
	v_mfma_f32_16x16x32_bf16 v[20:23], v[152:155], v[212:215], v[20:23]
	v_mfma_f32_16x16x32_bf16 v[12:15], v[160:163], v[212:215], v[12:15]
	v_mfma_f32_16x16x32_bf16 v[60:63], v[156:159], v[192:195], v[60:63]
	v_mfma_f32_16x16x32_bf16 v[56:59], v[164:167], v[192:195], v[56:59]
	v_mfma_f32_16x16x32_bf16 v[52:55], v[156:159], v[200:203], v[52:55]
	v_mfma_f32_16x16x32_bf16 v[44:47], v[164:167], v[200:203], v[44:47]
	v_mfma_f32_16x16x32_bf16 v[36:39], v[156:159], v[208:211], v[36:39]
	v_mfma_f32_16x16x32_bf16 v[28:31], v[164:167], v[208:211], v[28:31]
	v_mfma_f32_16x16x32_bf16 v[20:23], v[156:159], v[216:219], v[20:23]
	v_mfma_f32_16x16x32_bf16 v[12:15], v[164:167], v[216:219], v[12:15]
	v_mfma_f32_16x16x32_bf16 v[48:51], v[168:171], v[188:191], v[48:51]
	v_mfma_f32_16x16x32_bf16 v[40:43], v[176:179], v[188:191], v[40:43]
	v_mfma_f32_16x16x32_bf16 v[32:35], v[168:171], v[196:199], v[32:35]
	v_mfma_f32_16x16x32_bf16 v[24:27], v[176:179], v[196:199], v[24:27]
	v_mfma_f32_16x16x32_bf16 v[16:19], v[168:171], v[204:207], v[16:19]
	v_mfma_f32_16x16x32_bf16 v[8:11], v[176:179], v[204:207], v[8:11]
	v_mfma_f32_16x16x32_bf16 v[4:7], v[168:171], v[212:215], v[4:7]
	v_mfma_f32_16x16x32_bf16 v[0:3], v[176:179], v[212:215], v[0:3]
	v_mfma_f32_16x16x32_bf16 v[48:51], v[172:175], v[192:195], v[48:51]
	v_mfma_f32_16x16x32_bf16 v[40:43], v[184:187], v[192:195], v[40:43]
	v_mfma_f32_16x16x32_bf16 v[32:35], v[172:175], v[200:203], v[32:35]
	v_mfma_f32_16x16x32_bf16 v[24:27], v[184:187], v[200:203], v[24:27]
	v_mfma_f32_16x16x32_bf16 v[16:19], v[172:175], v[208:211], v[16:19]
	v_mfma_f32_16x16x32_bf16 v[8:11], v[184:187], v[208:211], v[8:11]
	v_mfma_f32_16x16x32_bf16 v[4:7], v[172:175], v[216:219], v[4:7]
	v_mfma_f32_16x16x32_bf16 v[0:3], v[184:187], v[216:219], v[0:3]
	s_barrier
	s_add_i32 s65, 0, 0x18000
	s_add_i32 s66, 0, 0x1c000
	v_add_u32_e32 v164, s65, v147
	v_add_u32_e32 v181, s66, v147
	ds_read_b128 v[152:155], v164
	ds_read_b128 v[156:159], v164 offset:1024
	ds_read_b128 v[160:163], v164 offset:2048
	ds_read_b128 v[164:167], v164 offset:3072
	ds_read_b128 v[168:171], v181
	ds_read_b128 v[172:175], v181 offset:1024
	ds_read_b128 v[176:179], v181 offset:2048
	ds_read_b128 v[184:187], v181 offset:3072
	s_add_u32 s24, s40, 0x160000
	s_addc_u32 s25, s41, 0
	s_mov_b32 m0, s43
	v_lshl_add_u64 v[226:227], s[24:25], 0, v[128:129]
	ds_read_b128 v[188:191], v151 offset:32768
	ds_read_b128 v[192:195], v151 offset:33792
	ds_read_b128 v[196:199], v151 offset:34816
	ds_read_b128 v[200:203], v151 offset:35840
	ds_read_b128 v[204:207], v151 offset:36864
	ds_read_b128 v[208:211], v151 offset:37888
	ds_read_b128 v[212:215], v151 offset:38912
	ds_read_b128 v[216:219], v151 offset:39936
	global_load_lds_dwordx4 v[226:227], off
	v_lshl_add_u64 v[226:227], s[24:25], 0, v[132:133]
	s_mov_b32 m0, s44
	s_nop 0
	global_load_lds_dwordx4 v[226:227], off
	s_waitcnt vmcnt(8)
	s_waitcnt lgkmcnt(0)
	s_barrier
	s_waitcnt lgkmcnt(0)
	v_mfma_f32_16x16x32_bf16 v[124:127], v[152:155], v[188:191], v[124:127]
	v_mfma_f32_16x16x32_bf16 v[120:123], v[160:163], v[188:191], v[120:123]
	v_mfma_f32_16x16x32_bf16 v[116:119], v[152:155], v[196:199], v[116:119]
	v_mfma_f32_16x16x32_bf16 v[108:111], v[160:163], v[196:199], v[108:111]
	v_mfma_f32_16x16x32_bf16 v[100:103], v[152:155], v[204:207], v[100:103]
	v_mfma_f32_16x16x32_bf16 v[92:95], v[160:163], v[204:207], v[92:95]
	v_mfma_f32_16x16x32_bf16 v[84:87], v[152:155], v[212:215], v[84:87]
	v_mfma_f32_16x16x32_bf16 v[76:79], v[160:163], v[212:215], v[76:79]
	v_mfma_f32_16x16x32_bf16 v[124:127], v[156:159], v[192:195], v[124:127]
	v_mfma_f32_16x16x32_bf16 v[120:123], v[164:167], v[192:195], v[120:123]
	v_mfma_f32_16x16x32_bf16 v[116:119], v[156:159], v[200:203], v[116:119]
	v_mfma_f32_16x16x32_bf16 v[108:111], v[164:167], v[200:203], v[108:111]
	v_mfma_f32_16x16x32_bf16 v[100:103], v[156:159], v[208:211], v[100:103]
	v_mfma_f32_16x16x32_bf16 v[92:95], v[164:167], v[208:211], v[92:95]
	v_mfma_f32_16x16x32_bf16 v[84:87], v[156:159], v[216:219], v[84:87]
	v_mfma_f32_16x16x32_bf16 v[76:79], v[164:167], v[216:219], v[76:79]
	v_mfma_f32_16x16x32_bf16 v[112:115], v[168:171], v[188:191], v[112:115]
	v_mfma_f32_16x16x32_bf16 v[104:107], v[176:179], v[188:191], v[104:107]
	v_mfma_f32_16x16x32_bf16 v[96:99], v[168:171], v[196:199], v[96:99]
	v_mfma_f32_16x16x32_bf16 v[88:91], v[176:179], v[196:199], v[88:91]
	v_mfma_f32_16x16x32_bf16 v[80:83], v[168:171], v[204:207], v[80:83]
	v_mfma_f32_16x16x32_bf16 v[72:75], v[176:179], v[204:207], v[72:75]
	v_mfma_f32_16x16x32_bf16 v[68:71], v[168:171], v[212:215], v[68:71]
	v_mfma_f32_16x16x32_bf16 v[64:67], v[176:179], v[212:215], v[64:67]
	v_mfma_f32_16x16x32_bf16 v[112:115], v[172:175], v[192:195], v[112:115]
	v_mfma_f32_16x16x32_bf16 v[104:107], v[184:187], v[192:195], v[104:107]
	v_mfma_f32_16x16x32_bf16 v[96:99], v[172:175], v[200:203], v[96:99]
	v_mfma_f32_16x16x32_bf16 v[88:91], v[184:187], v[200:203], v[88:91]
	v_mfma_f32_16x16x32_bf16 v[80:83], v[172:175], v[208:211], v[80:83]
	v_mfma_f32_16x16x32_bf16 v[72:75], v[184:187], v[208:211], v[72:75]
	v_mfma_f32_16x16x32_bf16 v[68:71], v[172:175], v[216:219], v[68:71]
	v_mfma_f32_16x16x32_bf16 v[64:67], v[184:187], v[216:219], v[64:67]
	s_barrier
; #define PG8_STAGE(bufoff, gbase, voff) do { _Pragma("unroll") for (int _i = 0; _i < 2; ++_i) \
;         __builtin_amdgcn_global_load_lds((const unsigned*)((const char*)(gbase) + (voff)[_i]), (LAS unsigned*)(lds + (bufoff) + ldsw + _i * 8192), 16, 0, 0); } while (0)
; #define PG8_LDA(dst, b, h) do { _Pragma("unroll") for (int m = 0; m < 4; ++m) _Pragma("unroll") for (int k = 0; k < 2; ++k) dst[m][k] = *(const LAS bf16x8*)(lds + PG8_SA(b, h) + aoff + m * 2048 + k * 1024); } while (0)
; #define PG8_MMA(ai, bj, At, Bt) do { __builtin_amdgcn_s_setprio(1); _Pragma("unroll") for (int m = 0; m < 4; ++m) _Pragma("unroll") for (int n = 0; n < 2; ++n) _Pragma("unroll") for (int k = 0; k < 2; ++k) \
;         acc[ai][bj][m][n] = __builtin_amdgcn_mfma_f32_16x16x32_bf16(Bt[n][k], At[m][k], acc[ai][bj][m][n], 0, 0, 0); __builtin_amdgcn_s_setprio(0); } while (0)
; #define PG8_WAIT_V(n) asm volatile("s_waitcnt vmcnt(" #n ")" ::: "memory")
; #define PG8_WAIT_L(n) asm volatile("s_waitcnt lgkmcnt(" #n ")" ::: "memory")
; #define PG8_BAR __builtin_amdgcn_s_barrier()
; #define PG8_SCHED __builtin_amdgcn_sched_barrier(0)
; template <bool LT, class Epi>
; __device__ __forceinline__ void gemm_phase(LAS unsigned char* lds, const Gemm g, const StaticOrder& S, const Epi& E) {
;     ...
;         for (int t = 0; t < nt; t += 2) {
;     ...
;             PG8_LDA(At, 1, 1); PG8_STAGE(PG8_SB(1, 0), b3, voffB); PG8_STAGE(PG8_SB(1, 1), b3 + hstepB, voffB); PG8_STAGE(PG8_SA(1, 0), a3, voffA);
;             PG8_WAIT_V(8); PG8_WAIT_L(0); PG8_BAR; PG8_MMA(1, 0, At, B0); PG8_MMA(1, 1, At, B1); PG8_BAR; PG8_SCHED;
	s_add_i32 s24, s65, s27
	v_lshl_add_u64 v[144:145], v[144:145], 0, s[8:9]
	s_mov_b32 m0, s24
	ds_read_b128 v[188:191], v151 offset:49152
	ds_read_b128 v[192:195], v151 offset:50176
	ds_read_b128 v[196:199], v151 offset:51200
	ds_read_b128 v[200:203], v151 offset:52224
	ds_read_b128 v[204:207], v151 offset:53248
	ds_read_b128 v[208:211], v151 offset:54272
	ds_read_b128 v[212:215], v151 offset:55296
	ds_read_b128 v[216:219], v151 offset:56320
	global_load_lds_dwordx4 v[144:145], off
	s_add_i32 m0, s24, 0x2000
	s_add_u32 s24, s38, 0x160080
	v_lshl_add_u64 v[144:145], v[220:221], 0, s[8:9]
	s_addc_u32 s25, s39, 0
	s_add_i32 s38, s66, s27
	global_load_lds_dwordx4 v[144:145], off
	v_lshl_add_u64 v[144:145], s[24:25], 0, v[130:131]
	s_mov_b32 m0, s38
	s_nop 0
	global_load_lds_dwordx4 v[144:145], off
	v_lshl_add_u64 v[144:145], s[24:25], 0, v[134:135]
	s_add_i32 m0, s38, 0x2000
	s_nop 0
	global_load_lds_dwordx4 v[144:145], off
	v_lshl_add_u64 v[144:145], v[222:223], 0, s[8:9]
	s_mov_b32 m0, s46
	s_nop 0
	global_load_lds_dwordx4 v[144:145], off
	v_lshl_add_u64 v[144:145], v[224:225], 0, s[8:9]
	s_mov_b32 m0, s47
	s_nop 0
	global_load_lds_dwordx4 v[144:145], off
	s_waitcnt vmcnt(8)
	s_waitcnt lgkmcnt(0)
	s_barrier
	s_waitcnt lgkmcnt(0)
	v_mfma_f32_16x16x32_bf16 v[60:63], v[152:155], v[188:191], v[60:63]
	v_mfma_f32_16x16x32_bf16 v[56:59], v[160:163], v[188:191], v[56:59]
	v_mfma_f32_16x16x32_bf16 v[52:55], v[152:155], v[196:199], v[52:55]
	v_mfma_f32_16x16x32_bf16 v[44:47], v[160:163], v[196:199], v[44:47]
	v_mfma_f32_16x16x32_bf16 v[36:39], v[152:155], v[204:207], v[36:39]
	v_mfma_f32_16x16x32_bf16 v[28:31], v[160:163], v[204:207], v[28:31]
	v_mfma_f32_16x16x32_bf16 v[20:23], v[152:155], v[212:215], v[20:23]
	v_mfma_f32_16x16x32_bf16 v[12:15], v[160:163], v[212:215], v[12:15]
	v_mfma_f32_16x16x32_bf16 v[60:63], v[156:159], v[192:195], v[60:63]
	v_mfma_f32_16x16x32_bf16 v[56:59], v[164:167], v[192:195], v[56:59]
	v_mfma_f32_16x16x32_bf16 v[52:55], v[156:159], v[200:203], v[52:55]
	v_mfma_f32_16x16x32_bf16 v[44:47], v[164:167], v[200:203], v[44:47]
	v_mfma_f32_16x16x32_bf16 v[36:39], v[156:159], v[208:211], v[36:39]
	v_mfma_f32_16x16x32_bf16 v[28:31], v[164:167], v[208:211], v[28:31]
	v_mfma_f32_16x16x32_bf16 v[20:23], v[156:159], v[216:219], v[20:23]
	v_mfma_f32_16x16x32_bf16 v[12:15], v[164:167], v[216:219], v[12:15]
	v_mfma_f32_16x16x32_bf16 v[48:51], v[168:171], v[188:191], v[48:51]
	v_mfma_f32_16x16x32_bf16 v[40:43], v[176:179], v[188:191], v[40:43]
	v_mfma_f32_16x16x32_bf16 v[32:35], v[168:171], v[196:199], v[32:35]
	v_mfma_f32_16x16x32_bf16 v[24:27], v[176:179], v[196:199], v[24:27]
	v_mfma_f32_16x16x32_bf16 v[16:19], v[168:171], v[204:207], v[16:19]
	v_mfma_f32_16x16x32_bf16 v[8:11], v[176:179], v[204:207], v[8:11]
	v_mfma_f32_16x16x32_bf16 v[4:7], v[168:171], v[212:215], v[4:7]
	v_mfma_f32_16x16x32_bf16 v[0:3], v[176:179], v[212:215], v[0:3]
	v_mfma_f32_16x16x32_bf16 v[48:51], v[172:175], v[192:195], v[48:51]
	v_mfma_f32_16x16x32_bf16 v[40:43], v[184:187], v[192:195], v[40:43]
	v_mfma_f32_16x16x32_bf16 v[32:35], v[172:175], v[200:203], v[32:35]
	v_mfma_f32_16x16x32_bf16 v[24:27], v[184:187], v[200:203], v[24:27]
	v_mfma_f32_16x16x32_bf16 v[16:19], v[172:175], v[208:211], v[16:19]
	v_mfma_f32_16x16x32_bf16 v[8:11], v[184:187], v[208:211], v[8:11]
	v_mfma_f32_16x16x32_bf16 v[4:7], v[172:175], v[216:219], v[4:7]
	v_mfma_f32_16x16x32_bf16 v[0:3], v[184:187], v[216:219], v[0:3]
	s_barrier
	s_add_i32 s64, s64, 2
	s_add_u32 s62, s62, 0x100
	s_addc_u32 s63, s63, 0
	s_cmpk_gt_u32 s64, 0x55
	s_mov_b64 s[24:25], s[34:35]
	s_cbranch_scc0 .LBB0_1979
	s_and_b64 vcc, exec, s[10:11]
	s_cbranch_vccz .LBB0_1982
	s_barrier
